# GEMM loops: LDS-DMA loads use scalar-base addressing (vOFF + s[base]), 16 v_lshl_add_u64 per iteration removed in all six loop copies
# speedup vs baseline: 1.0226x; 1.0033x over previous
.LBB0_58:
	s_add_u32 s44, s42, 0x100
	s_addc_u32 s45, s43, 0
	s_add_i32 s23, 0, 0x10000
	v_add_u32_e32 v145, s23, v143
	ds_read_b128 v[146:149], v145
	ds_read_b128 v[150:153], v145 offset:1024
	ds_read_b128 v[154:157], v145 offset:2048
	ds_read_b128 v[158:161], v145 offset:3072
	s_cmp_eq_u32 s22, 40
	s_cselect_b32 s49, s1, s45
	s_cselect_b32 s48, s0, s44
	s_cselect_b32 s47, s41, s21
	s_cselect_b32 s46, s40, s20
	s_add_i32 m0, s52, 0xc000
	ds_read_b128 v[162:165], v144
	ds_read_b128 v[166:169], v144 offset:1024
	ds_read_b128 v[170:173], v144 offset:2048
	ds_read_b128 v[174:177], v144 offset:3072
	ds_read_b128 v[178:181], v144 offset:4096
	ds_read_b128 v[182:185], v144 offset:5120
	ds_read_b128 v[186:189], v144 offset:6144
	ds_read_b128 v[190:193], v144 offset:7168
	global_load_lds_dwordx4 v138, s[42:43]
	s_add_i32 m0, s52, 0xe000
	s_nop 0
	global_load_lds_dwordx4 v140, s[42:43]
	s_waitcnt lgkmcnt(8)
	s_barrier
	s_waitcnt lgkmcnt(0)
	v_mfma_f32_16x16x32_bf16 v[128:131], v[146:149], v[162:165], v[128:131]
	v_mfma_f32_16x16x32_bf16 v[124:127], v[154:157], v[162:165], v[124:127]
	v_mfma_f32_16x16x32_bf16 v[120:123], v[146:149], v[170:173], v[120:123]
	v_mfma_f32_16x16x32_bf16 v[116:119], v[154:157], v[170:173], v[116:119]
	v_mfma_f32_16x16x32_bf16 v[104:107], v[146:149], v[178:181], v[104:107]
	v_mfma_f32_16x16x32_bf16 v[100:103], v[154:157], v[178:181], v[100:103]
	v_mfma_f32_16x16x32_bf16 v[88:91], v[146:149], v[186:189], v[88:91]
	v_mfma_f32_16x16x32_bf16 v[84:87], v[154:157], v[186:189], v[84:87]
	v_mfma_f32_16x16x32_bf16 v[128:131], v[150:153], v[166:169], v[128:131]
	v_mfma_f32_16x16x32_bf16 v[124:127], v[158:161], v[166:169], v[124:127]
	v_mfma_f32_16x16x32_bf16 v[120:123], v[150:153], v[174:177], v[120:123]
	v_mfma_f32_16x16x32_bf16 v[116:119], v[158:161], v[174:177], v[116:119]
	v_mfma_f32_16x16x32_bf16 v[104:107], v[150:153], v[182:185], v[104:107]
	v_mfma_f32_16x16x32_bf16 v[100:103], v[158:161], v[182:185], v[100:103]
	v_mfma_f32_16x16x32_bf16 v[88:91], v[150:153], v[190:193], v[88:91]
	v_mfma_f32_16x16x32_bf16 v[84:87], v[158:161], v[190:193], v[84:87]
	s_barrier
	s_add_i32 s26, 0, 0x14000
	s_add_i32 s23, s23, s37
	v_add_u32_e32 v145, s26, v143
	s_mov_b32 m0, s23
	ds_read_b128 v[202:205], v145
	ds_read_b128 v[206:209], v145 offset:1024
	ds_read_b128 v[210:213], v145 offset:2048
	ds_read_b128 v[214:217], v145 offset:3072
	global_load_lds_dwordx4 v132, s[46:47]
	s_add_i32 m0, s23, 0x2000
	s_nop 0
	global_load_lds_dwordx4 v136, s[46:47]
	s_barrier
	s_waitcnt lgkmcnt(0)
	v_mfma_f32_16x16x32_bf16 v[112:115], v[202:205], v[162:165], v[112:115]
	v_mfma_f32_16x16x32_bf16 v[108:111], v[210:213], v[162:165], v[108:111]
	v_mfma_f32_16x16x32_bf16 v[96:99], v[202:205], v[170:173], v[96:99]
	v_mfma_f32_16x16x32_bf16 v[92:95], v[210:213], v[170:173], v[92:95]
	v_mfma_f32_16x16x32_bf16 v[80:83], v[202:205], v[178:181], v[80:83]
	v_mfma_f32_16x16x32_bf16 v[76:79], v[210:213], v[178:181], v[76:79]
	v_mfma_f32_16x16x32_bf16 v[72:75], v[202:205], v[186:189], v[72:75]
	v_mfma_f32_16x16x32_bf16 v[68:71], v[210:213], v[186:189], v[68:71]
	v_mfma_f32_16x16x32_bf16 v[112:115], v[206:209], v[166:169], v[112:115]
	v_mfma_f32_16x16x32_bf16 v[108:111], v[214:217], v[166:169], v[108:111]
	v_mfma_f32_16x16x32_bf16 v[96:99], v[206:209], v[174:177], v[96:99]
	v_mfma_f32_16x16x32_bf16 v[92:95], v[214:217], v[174:177], v[92:95]
	v_mfma_f32_16x16x32_bf16 v[80:83], v[206:209], v[182:185], v[80:83]
	v_mfma_f32_16x16x32_bf16 v[76:79], v[214:217], v[182:185], v[76:79]
	v_mfma_f32_16x16x32_bf16 v[72:75], v[206:209], v[190:193], v[72:75]
	v_mfma_f32_16x16x32_bf16 v[68:71], v[214:217], v[190:193], v[68:71]
	s_mov_b32 m0, s52
	s_barrier
	ds_read_b128 v[162:165], v144 offset:16384
	ds_read_b128 v[166:169], v144 offset:17408
	ds_read_b128 v[170:173], v144 offset:18432
	ds_read_b128 v[174:177], v144 offset:19456
	ds_read_b128 v[178:181], v144 offset:20480
	ds_read_b128 v[182:185], v144 offset:21504
	ds_read_b128 v[186:189], v144 offset:22528
	ds_read_b128 v[190:193], v144 offset:23552
	global_load_lds_dwordx4 v0, s[48:49]
	s_mov_b32 m0, s53
	s_nop 0
	global_load_lds_dwordx4 v134, s[48:49]
	s_barrier
	s_waitcnt lgkmcnt(0)
	v_mfma_f32_16x16x32_bf16 v[64:67], v[146:149], v[162:165], v[64:67]
	v_mfma_f32_16x16x32_bf16 v[60:63], v[154:157], v[162:165], v[60:63]
	v_mfma_f32_16x16x32_bf16 v[56:59], v[146:149], v[170:173], v[56:59]
	v_mfma_f32_16x16x32_bf16 v[52:55], v[154:157], v[170:173], v[52:55]
	v_mfma_f32_16x16x32_bf16 v[40:43], v[146:149], v[178:181], v[40:43]
	v_mfma_f32_16x16x32_bf16 v[36:39], v[154:157], v[178:181], v[36:39]
	v_mfma_f32_16x16x32_bf16 v[24:27], v[146:149], v[186:189], v[24:27]
	v_mfma_f32_16x16x32_bf16 v[16:19], v[154:157], v[186:189], v[16:19]
	v_mfma_f32_16x16x32_bf16 v[64:67], v[150:153], v[166:169], v[64:67]
	v_mfma_f32_16x16x32_bf16 v[60:63], v[158:161], v[166:169], v[60:63]
	v_mfma_f32_16x16x32_bf16 v[56:59], v[150:153], v[174:177], v[56:59]
	v_mfma_f32_16x16x32_bf16 v[52:55], v[158:161], v[174:177], v[52:55]
	v_mfma_f32_16x16x32_bf16 v[40:43], v[150:153], v[182:185], v[40:43]
	v_mfma_f32_16x16x32_bf16 v[36:39], v[158:161], v[182:185], v[36:39]
	v_mfma_f32_16x16x32_bf16 v[24:27], v[150:153], v[190:193], v[24:27]
	v_mfma_f32_16x16x32_bf16 v[16:19], v[158:161], v[190:193], v[16:19]
	s_barrier
	s_add_u32 s24, s46, 0xb0000
	s_addc_u32 s25, s47, 0
	s_add_i32 s23, s26, s37
	s_mov_b32 m0, s23
	s_nop 0
	global_load_lds_dwordx4 v132, s[24:25]
	s_add_i32 m0, s23, 0x2000
	s_nop 0
	global_load_lds_dwordx4 v136, s[24:25]
	s_waitcnt vmcnt(6)
	s_barrier
	v_mfma_f32_16x16x32_bf16 v[48:51], v[202:205], v[162:165], v[48:51]
	v_mfma_f32_16x16x32_bf16 v[44:47], v[210:213], v[162:165], v[44:47]
	v_mfma_f32_16x16x32_bf16 v[32:35], v[202:205], v[170:173], v[32:35]
	v_mfma_f32_16x16x32_bf16 v[28:31], v[210:213], v[170:173], v[28:31]
	v_mfma_f32_16x16x32_bf16 v[20:23], v[202:205], v[178:181], v[20:23]
	v_mfma_f32_16x16x32_bf16 v[12:15], v[210:213], v[178:181], v[12:15]
	v_mfma_f32_16x16x32_bf16 v[8:11], v[202:205], v[186:189], v[8:11]
	v_mfma_f32_16x16x32_bf16 v[4:7], v[210:213], v[186:189], v[4:7]
	v_mfma_f32_16x16x32_bf16 v[48:51], v[206:209], v[166:169], v[48:51]
	v_mfma_f32_16x16x32_bf16 v[44:47], v[214:217], v[166:169], v[44:47]
	v_mfma_f32_16x16x32_bf16 v[32:35], v[206:209], v[174:177], v[32:35]
	v_mfma_f32_16x16x32_bf16 v[28:31], v[214:217], v[174:177], v[28:31]
	v_mfma_f32_16x16x32_bf16 v[20:23], v[206:209], v[182:185], v[20:23]
	v_mfma_f32_16x16x32_bf16 v[12:15], v[214:217], v[182:185], v[12:15]
	v_mfma_f32_16x16x32_bf16 v[8:11], v[206:209], v[190:193], v[8:11]
	v_mfma_f32_16x16x32_bf16 v[4:7], v[214:217], v[190:193], v[4:7]
	s_add_i32 s23, 0, 0x18000
	v_add_u32_e32 v145, s23, v143
	s_barrier
	ds_read_b128 v[146:149], v145
	ds_read_b128 v[150:153], v145 offset:1024
	ds_read_b128 v[154:157], v145 offset:2048
	ds_read_b128 v[158:161], v145 offset:3072
	s_add_u32 s24, s48, 0xb0000
	s_addc_u32 s25, s49, 0
	s_mov_b32 m0, s54
	ds_read_b128 v[162:165], v144 offset:32768
	ds_read_b128 v[166:169], v144 offset:33792
	ds_read_b128 v[170:173], v144 offset:34816
	ds_read_b128 v[174:177], v144 offset:35840
	ds_read_b128 v[178:181], v144 offset:36864
	ds_read_b128 v[182:185], v144 offset:37888
	ds_read_b128 v[186:189], v144 offset:38912
	ds_read_b128 v[190:193], v144 offset:39936
	global_load_lds_dwordx4 v0, s[24:25]
	s_mov_b32 m0, s55
	s_nop 0
	global_load_lds_dwordx4 v134, s[24:25]
	s_waitcnt lgkmcnt(8)
	s_barrier
	s_waitcnt lgkmcnt(0)
	v_mfma_f32_16x16x32_bf16 v[128:131], v[146:149], v[162:165], v[128:131]
	v_mfma_f32_16x16x32_bf16 v[124:127], v[154:157], v[162:165], v[124:127]
	v_mfma_f32_16x16x32_bf16 v[120:123], v[146:149], v[170:173], v[120:123]
	v_mfma_f32_16x16x32_bf16 v[116:119], v[154:157], v[170:173], v[116:119]
	v_mfma_f32_16x16x32_bf16 v[104:107], v[146:149], v[178:181], v[104:107]
	v_mfma_f32_16x16x32_bf16 v[100:103], v[154:157], v[178:181], v[100:103]
	v_mfma_f32_16x16x32_bf16 v[88:91], v[146:149], v[186:189], v[88:91]
	v_mfma_f32_16x16x32_bf16 v[84:87], v[154:157], v[186:189], v[84:87]
	v_mfma_f32_16x16x32_bf16 v[128:131], v[150:153], v[166:169], v[128:131]
	v_mfma_f32_16x16x32_bf16 v[124:127], v[158:161], v[166:169], v[124:127]
	v_mfma_f32_16x16x32_bf16 v[120:123], v[150:153], v[174:177], v[120:123]
	v_mfma_f32_16x16x32_bf16 v[116:119], v[158:161], v[174:177], v[116:119]
	v_mfma_f32_16x16x32_bf16 v[104:107], v[150:153], v[182:185], v[104:107]
	v_mfma_f32_16x16x32_bf16 v[100:103], v[158:161], v[182:185], v[100:103]
	v_mfma_f32_16x16x32_bf16 v[88:91], v[150:153], v[190:193], v[88:91]
	v_mfma_f32_16x16x32_bf16 v[84:87], v[158:161], v[190:193], v[84:87]
	s_barrier
	s_add_i32 s26, 0, 0x1c000
	s_add_i32 s23, s23, s37
	v_add_u32_e32 v145, s26, v143
	s_mov_b32 m0, s23
	ds_read_b128 v[202:205], v145
	ds_read_b128 v[206:209], v145 offset:1024
	ds_read_b128 v[210:213], v145 offset:2048
	ds_read_b128 v[214:217], v145 offset:3072
	s_add_u32 s98, s46, 0x80
	s_addc_u32 s99, s47, 0
	global_load_lds_dwordx4 v132, s[98:99]
	s_add_i32 m0, s23, 0x2000
	s_nop 0
	global_load_lds_dwordx4 v136, s[98:99]
	s_barrier
	s_waitcnt lgkmcnt(0)
	v_mfma_f32_16x16x32_bf16 v[112:115], v[202:205], v[162:165], v[112:115]
	v_mfma_f32_16x16x32_bf16 v[108:111], v[210:213], v[162:165], v[108:111]
	v_mfma_f32_16x16x32_bf16 v[96:99], v[202:205], v[170:173], v[96:99]
	v_mfma_f32_16x16x32_bf16 v[92:95], v[210:213], v[170:173], v[92:95]
	v_mfma_f32_16x16x32_bf16 v[80:83], v[202:205], v[178:181], v[80:83]
	v_mfma_f32_16x16x32_bf16 v[76:79], v[210:213], v[178:181], v[76:79]
	v_mfma_f32_16x16x32_bf16 v[72:75], v[202:205], v[186:189], v[72:75]
	v_mfma_f32_16x16x32_bf16 v[68:71], v[210:213], v[186:189], v[68:71]
	v_mfma_f32_16x16x32_bf16 v[112:115], v[206:209], v[166:169], v[112:115]
	v_mfma_f32_16x16x32_bf16 v[108:111], v[214:217], v[166:169], v[108:111]
	v_mfma_f32_16x16x32_bf16 v[96:99], v[206:209], v[174:177], v[96:99]
	v_mfma_f32_16x16x32_bf16 v[92:95], v[214:217], v[174:177], v[92:95]
	v_mfma_f32_16x16x32_bf16 v[80:83], v[206:209], v[182:185], v[80:83]
	v_mfma_f32_16x16x32_bf16 v[76:79], v[214:217], v[182:185], v[76:79]
	v_mfma_f32_16x16x32_bf16 v[72:75], v[206:209], v[190:193], v[72:75]
	v_mfma_f32_16x16x32_bf16 v[68:71], v[214:217], v[190:193], v[68:71]
	s_mov_b32 m0, s56
	s_barrier
	ds_read_b128 v[162:165], v144 offset:49152
	ds_read_b128 v[166:169], v144 offset:50176
	ds_read_b128 v[170:173], v144 offset:51200
	ds_read_b128 v[174:177], v144 offset:52224
	ds_read_b128 v[178:181], v144 offset:53248
	ds_read_b128 v[182:185], v144 offset:54272
	ds_read_b128 v[186:189], v144 offset:55296
	ds_read_b128 v[190:193], v144 offset:56320
	s_add_u32 s98, s48, 0x80
	s_addc_u32 s99, s49, 0
	global_load_lds_dwordx4 v0, s[98:99]
	s_mov_b32 m0, s57
	s_nop 0
	global_load_lds_dwordx4 v134, s[98:99]
	s_barrier
	s_waitcnt lgkmcnt(0)
	v_mfma_f32_16x16x32_bf16 v[64:67], v[146:149], v[162:165], v[64:67]
	v_mfma_f32_16x16x32_bf16 v[60:63], v[154:157], v[162:165], v[60:63]
	v_mfma_f32_16x16x32_bf16 v[56:59], v[146:149], v[170:173], v[56:59]
	v_mfma_f32_16x16x32_bf16 v[52:55], v[154:157], v[170:173], v[52:55]
	v_mfma_f32_16x16x32_bf16 v[40:43], v[146:149], v[178:181], v[40:43]
	v_mfma_f32_16x16x32_bf16 v[36:39], v[154:157], v[178:181], v[36:39]
	v_mfma_f32_16x16x32_bf16 v[24:27], v[146:149], v[186:189], v[24:27]
	v_mfma_f32_16x16x32_bf16 v[16:19], v[154:157], v[186:189], v[16:19]
	v_mfma_f32_16x16x32_bf16 v[64:67], v[150:153], v[166:169], v[64:67]
	v_mfma_f32_16x16x32_bf16 v[60:63], v[158:161], v[166:169], v[60:63]
	v_mfma_f32_16x16x32_bf16 v[56:59], v[150:153], v[174:177], v[56:59]
	v_mfma_f32_16x16x32_bf16 v[52:55], v[158:161], v[174:177], v[52:55]
	v_mfma_f32_16x16x32_bf16 v[40:43], v[150:153], v[182:185], v[40:43]
	v_mfma_f32_16x16x32_bf16 v[36:39], v[158:161], v[182:185], v[36:39]
	v_mfma_f32_16x16x32_bf16 v[24:27], v[150:153], v[190:193], v[24:27]
	v_mfma_f32_16x16x32_bf16 v[16:19], v[158:161], v[190:193], v[16:19]
	s_barrier
	s_add_u32 s24, s46, 0xb0080
	s_addc_u32 s25, s47, 0
	s_add_i32 s23, s26, s37
	s_mov_b32 m0, s23
	s_nop 0
	global_load_lds_dwordx4 v132, s[24:25]
	s_add_i32 m0, s23, 0x2000
	s_nop 0
	global_load_lds_dwordx4 v136, s[24:25]
	s_waitcnt vmcnt(6)
	s_barrier
	v_mfma_f32_16x16x32_bf16 v[48:51], v[202:205], v[162:165], v[48:51]
	v_mfma_f32_16x16x32_bf16 v[44:47], v[210:213], v[162:165], v[44:47]
	v_mfma_f32_16x16x32_bf16 v[32:35], v[202:205], v[170:173], v[32:35]
	v_mfma_f32_16x16x32_bf16 v[28:31], v[210:213], v[170:173], v[28:31]
	v_mfma_f32_16x16x32_bf16 v[20:23], v[202:205], v[178:181], v[20:23]
	v_mfma_f32_16x16x32_bf16 v[12:15], v[210:213], v[178:181], v[12:15]
	v_mfma_f32_16x16x32_bf16 v[8:11], v[202:205], v[186:189], v[8:11]
	v_mfma_f32_16x16x32_bf16 v[4:7], v[210:213], v[186:189], v[4:7]
	v_mfma_f32_16x16x32_bf16 v[48:51], v[206:209], v[166:169], v[48:51]
	v_mfma_f32_16x16x32_bf16 v[44:47], v[214:217], v[166:169], v[44:47]
	v_mfma_f32_16x16x32_bf16 v[32:35], v[206:209], v[174:177], v[32:35]
	v_mfma_f32_16x16x32_bf16 v[28:31], v[214:217], v[174:177], v[28:31]
	v_mfma_f32_16x16x32_bf16 v[20:23], v[206:209], v[182:185], v[20:23]
	v_mfma_f32_16x16x32_bf16 v[12:15], v[214:217], v[182:185], v[12:15]
	v_mfma_f32_16x16x32_bf16 v[8:11], v[206:209], v[190:193], v[8:11]
	v_mfma_f32_16x16x32_bf16 v[4:7], v[214:217], v[190:193], v[4:7]
	s_add_i32 s22, s22, 2
	s_add_u32 s20, s20, 0x100
	s_addc_u32 s21, s21, 0
	s_cmp_gt_u32 s22, 41
	s_mov_b64 s[42:43], s[44:45]
	s_barrier
	s_cbranch_scc0 .LBB0_58
	v_lshl_add_u32 v146, s61, 8, v142
	v_cvt_pk_bf16_f32 v72, v72, v73
	v_cvt_pk_bf16_f32 v73, v74, v75
	v_cvt_pk_bf16_f32 v74, v68, v69
	v_add_u32_e32 v68, 0x80, v146
	s_lshl_b32 s20, s62, 8
	v_ashrrev_i32_e32 v147, 31, v146
	v_readlane_b32 s22, v252, 10
	v_cvt_pk_bf16_f32 v112, v112, v113
	v_cvt_pk_bf16_f32 v113, v114, v115
	v_cvt_pk_bf16_f32 v114, v108, v109
	v_or_b32_e32 v108, 16, v146
	v_ashrrev_i32_e32 v69, 31, v68
	v_cvt_pk_bf16_f32 v48, v48, v49
	v_cvt_pk_bf16_f32 v49, v50, v51
	v_cvt_pk_bf16_f32 v50, v44, v45
	v_add_u32_e32 v44, 0x90, v146
	s_ashr_i32 s21, s20, 31
	v_lshlrev_b64 v[148:149], 11, v[146:147]
	v_readlane_b32 s23, v252, 11
	v_ashrrev_i32_e32 v109, 31, v108
	v_cvt_pk_bf16_f32 v96, v96, v97
	v_cvt_pk_bf16_f32 v97, v98, v99
	v_cvt_pk_bf16_f32 v98, v92, v93
	v_or_b32_e32 v92, 32, v146
	v_lshlrev_b64 v[68:69], 11, v[68:69]
	v_ashrrev_i32_e32 v45, 31, v44
	v_cvt_pk_bf16_f32 v32, v32, v33
	v_cvt_pk_bf16_f32 v33, v34, v35
	v_cvt_pk_bf16_f32 v34, v28, v29
	v_add_u32_e32 v28, 0xa0, v146
	v_lshl_add_u64 v[148:149], s[22:23], 0, v[148:149]
	s_lshl_b64 s[42:43], s[20:21], 1
	v_lshlrev_b64 v[108:109], 11, v[108:109]
	v_ashrrev_i32_e32 v93, 31, v92
	v_cvt_pk_bf16_f32 v80, v80, v81
	v_cvt_pk_bf16_f32 v81, v82, v83
	v_cvt_pk_bf16_f32 v82, v76, v77
	v_or_b32_e32 v76, 48, v146
	v_lshl_add_u64 v[68:69], s[22:23], 0, v[68:69]
	v_lshlrev_b64 v[44:45], 11, v[44:45]
	v_ashrrev_i32_e32 v29, 31, v28
	v_cvt_pk_bf16_f32 v20, v20, v21
	v_cvt_pk_bf16_f32 v21, v22, v23
	v_cvt_pk_bf16_f32 v22, v12, v13
	v_add_u32_e32 v12, 0xb0, v146
	v_lshl_add_u64 v[148:149], v[148:149], 0, s[42:43]
	v_lshl_add_u64 v[108:109], s[22:23], 0, v[108:109]
	v_lshlrev_b64 v[92:93], 11, v[92:93]
	v_ashrrev_i32_e32 v77, 31, v76
	v_lshl_add_u64 v[68:69], v[68:69], 0, s[42:43]
	v_lshl_add_u64 v[44:45], s[22:23], 0, v[44:45]
	v_lshlrev_b64 v[28:29], 11, v[28:29]
	v_ashrrev_i32_e32 v13, 31, v12
	v_lshl_add_u64 v[148:149], v[148:149], 0, s[72:73]
	v_lshl_add_u64 v[108:109], v[108:109], 0, s[42:43]
	v_lshl_add_u64 v[92:93], s[22:23], 0, v[92:93]
	v_lshlrev_b64 v[76:77], 11, v[76:77]
	v_lshl_add_u64 v[68:69], v[68:69], 0, s[72:73]
	v_lshl_add_u64 v[44:45], v[44:45], 0, s[42:43]
	v_lshl_add_u64 v[28:29], s[22:23], 0, v[28:29]
	v_lshlrev_b64 v[12:13], 11, v[12:13]
	v_lshl_add_u64 v[148:149], v[148:149], 0, v[2:3]
	v_cvt_pk_bf16_f32 v115, v110, v111
	v_lshl_add_u64 v[108:109], v[108:109], 0, s[72:73]
	v_lshl_add_u64 v[92:93], v[92:93], 0, s[42:43]
	v_lshl_add_u64 v[76:77], s[22:23], 0, v[76:77]
	v_lshl_add_u64 v[68:69], v[68:69], 0, v[2:3]
	v_cvt_pk_bf16_f32 v51, v46, v47
	v_lshl_add_u64 v[44:45], v[44:45], 0, s[72:73]
	v_lshl_add_u64 v[28:29], v[28:29], 0, s[42:43]
	v_lshl_add_u64 v[12:13], s[22:23], 0, v[12:13]
	global_store_dwordx4 v[148:149], v[112:115], off offset:256
	v_cvt_pk_bf16_f32 v99, v94, v95
	v_lshl_add_u64 v[92:93], v[92:93], 0, s[72:73]
	v_lshl_add_u64 v[112:113], v[108:109], 0, v[2:3]
	v_lshl_add_u64 v[76:77], v[76:77], 0, s[42:43]
	global_store_dwordx4 v[68:69], v[48:51], off offset:256
	v_cvt_pk_bf16_f32 v35, v30, v31
	v_lshl_add_u64 v[28:29], v[28:29], 0, s[72:73]
	v_lshl_add_u64 v[48:49], v[44:45], 0, v[2:3]
	v_lshl_add_u64 v[12:13], v[12:13], 0, s[42:43]
	global_store_dwordx4 v[112:113], v[96:99], off offset:256
	v_cvt_pk_bf16_f32 v83, v78, v79
	v_lshl_add_u64 v[76:77], v[76:77], 0, s[72:73]
	v_lshl_add_u64 v[96:97], v[92:93], 0, v[2:3]
	global_store_dwordx4 v[48:49], v[32:35], off offset:256
	v_cvt_pk_bf16_f32 v23, v14, v15
	v_lshl_add_u64 v[12:13], v[12:13], 0, s[72:73]
	v_lshl_add_u64 v[32:33], v[28:29], 0, v[2:3]
	v_cvt_pk_bf16_f32 v128, v128, v129
	v_cvt_pk_bf16_f32 v129, v130, v131
	v_cvt_pk_bf16_f32 v130, v124, v125
	v_cvt_pk_bf16_f32 v131, v126, v127
	v_cvt_pk_bf16_f32 v108, v120, v121
	v_cvt_pk_bf16_f32 v109, v122, v123
	v_cvt_pk_bf16_f32 v110, v116, v117
	v_cvt_pk_bf16_f32 v111, v118, v119
	v_cvt_pk_bf16_f32 v92, v104, v105
	v_cvt_pk_bf16_f32 v93, v106, v107
	v_cvt_pk_bf16_f32 v94, v100, v101
	v_cvt_pk_bf16_f32 v95, v102, v103
	global_store_dwordx4 v[96:97], v[80:83], off offset:256
	v_cvt_pk_bf16_f32 v78, v84, v85
	v_cvt_pk_bf16_f32 v79, v86, v87
	v_lshl_add_u64 v[80:81], v[76:77], 0, v[2:3]
	v_cvt_pk_bf16_f32 v76, v88, v89
	v_cvt_pk_bf16_f32 v77, v90, v91
	v_cvt_pk_bf16_f32 v75, v70, v71
	v_cvt_pk_bf16_f32 v64, v64, v65
	v_cvt_pk_bf16_f32 v65, v66, v67
	v_cvt_pk_bf16_f32 v66, v60, v61
	v_cvt_pk_bf16_f32 v67, v62, v63
	v_cvt_pk_bf16_f32 v44, v56, v57
	v_cvt_pk_bf16_f32 v45, v58, v59
	v_cvt_pk_bf16_f32 v46, v52, v53
	v_cvt_pk_bf16_f32 v47, v54, v55
	v_cvt_pk_bf16_f32 v28, v40, v41
	v_cvt_pk_bf16_f32 v29, v42, v43
	v_cvt_pk_bf16_f32 v30, v36, v37
	v_cvt_pk_bf16_f32 v31, v38, v39
	global_store_dwordx4 v[32:33], v[20:23], off offset:256
	v_cvt_pk_bf16_f32 v14, v16, v17
	v_cvt_pk_bf16_f32 v15, v18, v19
	v_lshl_add_u64 v[20:21], v[12:13], 0, v[2:3]
	v_cvt_pk_bf16_f32 v12, v24, v25
	v_cvt_pk_bf16_f32 v13, v26, v27
	v_cvt_pk_bf16_f32 v8, v8, v9
	v_cvt_pk_bf16_f32 v9, v10, v11
	v_cvt_pk_bf16_f32 v10, v4, v5
	v_cvt_pk_bf16_f32 v11, v6, v7
	s_and_b64 vcc, exec, s[38:39]
	s_mov_b32 s62, s59
	s_mov_b32 s61, s60
	s_mov_b64 s[44:45], s[40:41]
	s_mov_b64 s[42:43], s[0:1]
	global_store_dwordx4 v[148:149], v[128:131], off
	global_store_dwordx4 v[112:113], v[108:111], off
	global_store_dwordx4 v[96:97], v[92:95], off
	global_store_dwordx4 v[80:81], v[76:79], off
	global_store_dwordx4 v[80:81], v[72:75], off offset:256
	global_store_dwordx4 v[68:69], v[64:67], off
	global_store_dwordx4 v[48:49], v[44:47], off
	global_store_dwordx4 v[32:33], v[28:31], off
	global_store_dwordx4 v[20:21], v[12:15], off
	global_store_dwordx4 v[20:21], v[8:11], off offset:256
	s_cbranch_vccz .LBB0_51
	s_waitcnt vmcnt(0)
	s_cmpk_gt_u32 s36, 0xff
	s_cbranch_scc1 .LBB0_62
	s_barrier

.LBB0_80:
	s_add_u32 s22, s52, 0xfffc0080
	s_addc_u32 s23, s53, -1
	s_add_i32 s24, 0, 0x10000
	v_add_u32_e32 v64, s24, v235
	ds_read_b128 v[52:55], v64
	ds_read_b128 v[56:59], v64 offset:1024
	ds_read_b128 v[60:63], v64 offset:2048
	ds_read_b128 v[64:67], v64 offset:3072
	s_cmp_eq_u32 s21, 12
	s_cselect_b32 s57, s47, s23
	s_cselect_b32 s56, s46, s22
	s_cselect_b32 s55, s49, s20
	s_cselect_b32 s54, s48, s1
	s_add_i32 m0, s62, 0xc000
	ds_read_b128 v[76:79], v239
	ds_read_b128 v[80:83], v239 offset:1024
	ds_read_b128 v[84:87], v239 offset:2048
	ds_read_b128 v[88:91], v239 offset:3072
	ds_read_b128 v[92:95], v239 offset:4096
	ds_read_b128 v[96:99], v239 offset:5120
	ds_read_b128 v[100:103], v239 offset:6144
	ds_read_b128 v[104:107], v239 offset:7168
	global_load_lds_dwordx4 v206, s[52:53]
	s_add_i32 m0, s62, 0xe000
	s_nop 0
	global_load_lds_dwordx4 v208, s[52:53]
	s_waitcnt lgkmcnt(8)
	s_barrier
	s_waitcnt lgkmcnt(0)
	v_mfma_f32_16x16x32_bf16 v[160:163], v[52:55], v[92:95], v[160:163]
	v_mfma_f32_16x16x32_bf16 v[152:155], v[60:63], v[92:95], v[152:155]
	v_mfma_f32_16x16x32_bf16 v[144:147], v[52:55], v[100:103], v[144:147]
	v_mfma_f32_16x16x32_bf16 v[140:143], v[60:63], v[100:103], v[140:143]
	v_mfma_f32_16x16x32_bf16 v[116:119], v[52:55], v[76:79], v[192:195]
	v_mfma_f32_16x16x32_bf16 v[120:123], v[60:63], v[76:79], v[184:187]
	v_mfma_f32_16x16x32_bf16 v[124:127], v[52:55], v[84:87], v[176:179]
	v_mfma_f32_16x16x32_bf16 v[128:131], v[60:63], v[84:87], v[168:171]
	v_mfma_f32_16x16x32_bf16 v[160:163], v[56:59], v[96:99], v[160:163]
	v_mfma_f32_16x16x32_bf16 v[152:155], v[64:67], v[96:99], v[152:155]
	v_mfma_f32_16x16x32_bf16 v[144:147], v[56:59], v[104:107], v[144:147]
	v_mfma_f32_16x16x32_bf16 v[140:143], v[64:67], v[104:107], v[140:143]
	v_mfma_f32_16x16x32_bf16 v[116:119], v[56:59], v[80:83], v[116:119]
	v_mfma_f32_16x16x32_bf16 v[120:123], v[64:67], v[80:83], v[120:123]
	v_mfma_f32_16x16x32_bf16 v[124:127], v[56:59], v[88:91], v[124:127]
	v_mfma_f32_16x16x32_bf16 v[128:131], v[64:67], v[88:91], v[128:131]
	s_barrier
	s_add_i32 s25, 0, 0x14000
	s_add_i32 s22, s24, s60
	v_add_u32_e32 v192, s25, v235
	s_mov_b32 m0, s22
	ds_read_b128 v[168:171], v192
	ds_read_b128 v[176:179], v192 offset:1024
	ds_read_b128 v[184:187], v192 offset:2048
	ds_read_b128 v[192:195], v192 offset:3072
	global_load_lds_dwordx4 v2, s[54:55]
	s_add_i32 m0, s22, 0x2000
	s_nop 0
	global_load_lds_dwordx4 v0, s[54:55]
	s_barrier
	s_waitcnt lgkmcnt(0)
	v_mfma_f32_16x16x32_bf16 v[188:191], v[168:171], v[76:79], v[188:191]
	v_mfma_f32_16x16x32_bf16 v[76:79], v[184:187], v[76:79], v[180:183]
	v_mfma_f32_16x16x32_bf16 v[188:191], v[176:179], v[80:83], v[188:191]
	v_mfma_f32_16x16x32_bf16 v[76:79], v[192:195], v[80:83], v[76:79]
	v_mfma_f32_16x16x32_bf16 v[80:83], v[168:171], v[84:87], v[172:175]
	v_mfma_f32_16x16x32_bf16 v[84:87], v[184:187], v[84:87], v[164:167]
	v_mfma_f32_16x16x32_bf16 v[80:83], v[176:179], v[88:91], v[80:83]
	v_mfma_f32_16x16x32_bf16 v[84:87], v[192:195], v[88:91], v[84:87]
	v_mfma_f32_16x16x32_bf16 v[88:91], v[168:171], v[92:95], v[156:159]
	v_mfma_f32_16x16x32_bf16 v[92:95], v[184:187], v[92:95], v[148:151]
	v_mfma_f32_16x16x32_bf16 v[88:91], v[176:179], v[96:99], v[88:91]
	v_mfma_f32_16x16x32_bf16 v[92:95], v[192:195], v[96:99], v[92:95]
	v_mfma_f32_16x16x32_bf16 v[96:99], v[168:171], v[100:103], v[136:139]
	v_mfma_f32_16x16x32_bf16 v[100:103], v[184:187], v[100:103], v[132:135]
	v_mfma_f32_16x16x32_bf16 v[96:99], v[176:179], v[104:107], v[96:99]
	v_mfma_f32_16x16x32_bf16 v[100:103], v[192:195], v[104:107], v[100:103]
	s_mov_b32 m0, s62
	s_barrier
	ds_read_b128 v[104:107], v239 offset:16384
	ds_read_b128 v[132:135], v239 offset:17408
	ds_read_b128 v[136:139], v239 offset:18432
	ds_read_b128 v[148:151], v239 offset:19456
	ds_read_b128 v[156:159], v239 offset:20480
	ds_read_b128 v[164:167], v239 offset:21504
	ds_read_b128 v[172:175], v239 offset:22528
	ds_read_b128 v[180:183], v239 offset:23552
	global_load_lds_dwordx4 v204, s[56:57]
	s_mov_b32 m0, s63
	s_nop 0
	global_load_lds_dwordx4 v202, s[56:57]
	s_barrier
	s_waitcnt lgkmcnt(0)
	v_mfma_f32_16x16x32_bf16 v[112:115], v[52:55], v[104:107], v[112:115]
	v_mfma_f32_16x16x32_bf16 v[72:75], v[60:63], v[104:107], v[72:75]
	v_mfma_f32_16x16x32_bf16 v[48:51], v[52:55], v[136:139], v[48:51]
	v_mfma_f32_16x16x32_bf16 v[40:43], v[60:63], v[136:139], v[40:43]
	v_mfma_f32_16x16x32_bf16 v[32:35], v[52:55], v[156:159], v[32:35]
	v_mfma_f32_16x16x32_bf16 v[24:27], v[60:63], v[156:159], v[24:27]
	v_mfma_f32_16x16x32_bf16 v[16:19], v[52:55], v[172:175], v[16:19]
	v_mfma_f32_16x16x32_bf16 v[12:15], v[60:63], v[172:175], v[12:15]
	v_mfma_f32_16x16x32_bf16 v[112:115], v[56:59], v[132:135], v[112:115]
	v_mfma_f32_16x16x32_bf16 v[72:75], v[64:67], v[132:135], v[72:75]
	v_mfma_f32_16x16x32_bf16 v[48:51], v[56:59], v[148:151], v[48:51]
	v_mfma_f32_16x16x32_bf16 v[40:43], v[64:67], v[148:151], v[40:43]
	v_mfma_f32_16x16x32_bf16 v[32:35], v[56:59], v[164:167], v[32:35]
	v_mfma_f32_16x16x32_bf16 v[24:27], v[64:67], v[164:167], v[24:27]
	v_mfma_f32_16x16x32_bf16 v[16:19], v[56:59], v[180:183], v[16:19]
	v_mfma_f32_16x16x32_bf16 v[12:15], v[64:67], v[180:183], v[12:15]
	s_barrier
	s_add_u32 s22, s54, 0x40000
	s_addc_u32 s23, s55, 0
	s_add_i32 s24, s25, s60
	s_mov_b32 m0, s24
	s_nop 0
	global_load_lds_dwordx4 v2, s[22:23]
	s_add_i32 m0, s24, 0x2000
	s_nop 0
	global_load_lds_dwordx4 v0, s[22:23]
	s_waitcnt vmcnt(6)
	s_barrier
	v_mfma_f32_16x16x32_bf16 v[44:47], v[168:171], v[136:139], v[44:47]
	v_mfma_f32_16x16x32_bf16 v[36:39], v[184:187], v[136:139], v[36:39]
	v_mfma_f32_16x16x32_bf16 v[28:31], v[168:171], v[156:159], v[28:31]
	v_mfma_f32_16x16x32_bf16 v[20:23], v[184:187], v[156:159], v[20:23]
	v_mfma_f32_16x16x32_bf16 v[8:11], v[168:171], v[172:175], v[8:11]
	v_mfma_f32_16x16x32_bf16 v[4:7], v[184:187], v[172:175], v[4:7]
	v_mfma_f32_16x16x32_bf16 v[52:55], v[168:171], v[104:107], v[108:111]
	v_mfma_f32_16x16x32_bf16 v[56:59], v[184:187], v[104:107], v[68:71]
	v_mfma_f32_16x16x32_bf16 v[44:47], v[176:179], v[148:151], v[44:47]
	v_mfma_f32_16x16x32_bf16 v[36:39], v[192:195], v[148:151], v[36:39]
	v_mfma_f32_16x16x32_bf16 v[28:31], v[176:179], v[164:167], v[28:31]
	v_mfma_f32_16x16x32_bf16 v[20:23], v[192:195], v[164:167], v[20:23]
	v_mfma_f32_16x16x32_bf16 v[8:11], v[176:179], v[180:183], v[8:11]
	v_mfma_f32_16x16x32_bf16 v[4:7], v[192:195], v[180:183], v[4:7]
	v_mfma_f32_16x16x32_bf16 v[52:55], v[176:179], v[132:135], v[52:55]
	v_mfma_f32_16x16x32_bf16 v[56:59], v[192:195], v[132:135], v[56:59]
	s_add_i32 s24, 0, 0x18000
	v_add_u32_e32 v104, s24, v235
	s_barrier
	ds_read_b128 v[60:63], v104
	ds_read_b128 v[64:67], v104 offset:1024
	ds_read_b128 v[68:71], v104 offset:2048
	ds_read_b128 v[104:107], v104 offset:3072
	s_add_u32 s22, s56, 0x40000
	s_addc_u32 s23, s57, 0
	s_mov_b32 m0, s64
	ds_read_b128 v[108:111], v239 offset:32768
	ds_read_b128 v[132:135], v239 offset:33792
	ds_read_b128 v[136:139], v239 offset:34816
	ds_read_b128 v[148:151], v239 offset:35840
	ds_read_b128 v[210:213], v239 offset:36864
	ds_read_b128 v[214:217], v239 offset:37888
	ds_read_b128 v[240:243], v239 offset:38912
	ds_read_b128 v[244:247], v239 offset:39936
	global_load_lds_dwordx4 v204, s[22:23]
	s_mov_b32 m0, s65
	s_nop 0
	global_load_lds_dwordx4 v202, s[22:23]
	s_waitcnt lgkmcnt(8)
	s_barrier
	s_waitcnt lgkmcnt(0)
	v_mfma_f32_16x16x32_bf16 v[116:119], v[60:63], v[108:111], v[116:119]
	v_mfma_f32_16x16x32_bf16 v[192:195], v[64:67], v[132:135], v[116:119]
	v_mfma_f32_16x16x32_bf16 v[116:119], v[68:71], v[108:111], v[120:123]
	v_mfma_f32_16x16x32_bf16 v[184:187], v[104:107], v[132:135], v[116:119]
	v_mfma_f32_16x16x32_bf16 v[116:119], v[60:63], v[136:139], v[124:127]
	v_mfma_f32_16x16x32_bf16 v[176:179], v[64:67], v[148:151], v[116:119]
	v_mfma_f32_16x16x32_bf16 v[116:119], v[68:71], v[136:139], v[128:131]
	v_mfma_f32_16x16x32_bf16 v[168:171], v[104:107], v[148:151], v[116:119]
	v_mfma_f32_16x16x32_bf16 v[116:119], v[60:63], v[210:213], v[160:163]
	v_mfma_f32_16x16x32_bf16 v[160:163], v[64:67], v[214:217], v[116:119]
	v_mfma_f32_16x16x32_bf16 v[116:119], v[68:71], v[210:213], v[152:155]
	v_mfma_f32_16x16x32_bf16 v[152:155], v[104:107], v[214:217], v[116:119]
	v_mfma_f32_16x16x32_bf16 v[116:119], v[60:63], v[240:243], v[144:147]
	v_mfma_f32_16x16x32_bf16 v[144:147], v[64:67], v[244:247], v[116:119]
	v_mfma_f32_16x16x32_bf16 v[116:119], v[68:71], v[240:243], v[140:143]
	v_mfma_f32_16x16x32_bf16 v[140:143], v[104:107], v[244:247], v[116:119]
	s_barrier
	s_add_i32 s25, 0, 0x1c000
	s_add_i32 s22, s24, s60
	v_add_u32_e32 v128, s25, v235
	s_mov_b32 m0, s22
	ds_read_b128 v[116:119], v128
	ds_read_b128 v[120:123], v128 offset:1024
	ds_read_b128 v[124:127], v128 offset:2048
	ds_read_b128 v[128:131], v128 offset:3072
	s_add_u32 s98, s54, 0x80
	s_addc_u32 s99, s55, 0
	global_load_lds_dwordx4 v2, s[98:99]
	s_add_i32 m0, s22, 0x2000
	s_nop 0
	global_load_lds_dwordx4 v0, s[98:99]
	s_barrier
	s_waitcnt lgkmcnt(0)
	v_mfma_f32_16x16x32_bf16 v[76:79], v[124:127], v[108:111], v[76:79]
	v_mfma_f32_16x16x32_bf16 v[180:183], v[128:131], v[132:135], v[76:79]
	v_mfma_f32_16x16x32_bf16 v[76:79], v[116:119], v[136:139], v[80:83]
	v_mfma_f32_16x16x32_bf16 v[172:175], v[120:123], v[148:151], v[76:79]
	v_mfma_f32_16x16x32_bf16 v[76:79], v[124:127], v[136:139], v[84:87]
	v_mfma_f32_16x16x32_bf16 v[156:159], v[116:119], v[108:111], v[188:191]
	v_mfma_f32_16x16x32_bf16 v[164:167], v[128:131], v[148:151], v[76:79]
	v_mfma_f32_16x16x32_bf16 v[76:79], v[116:119], v[210:213], v[88:91]
	v_mfma_f32_16x16x32_bf16 v[188:191], v[120:123], v[132:135], v[156:159]
	v_mfma_f32_16x16x32_bf16 v[156:159], v[120:123], v[214:217], v[76:79]
	v_mfma_f32_16x16x32_bf16 v[76:79], v[124:127], v[210:213], v[92:95]
	v_mfma_f32_16x16x32_bf16 v[148:151], v[128:131], v[214:217], v[76:79]
	v_mfma_f32_16x16x32_bf16 v[76:79], v[116:119], v[240:243], v[96:99]
	v_mfma_f32_16x16x32_bf16 v[136:139], v[120:123], v[244:247], v[76:79]
	v_mfma_f32_16x16x32_bf16 v[76:79], v[124:127], v[240:243], v[100:103]
	v_mfma_f32_16x16x32_bf16 v[132:135], v[128:131], v[244:247], v[76:79]
	s_mov_b32 m0, s72
	s_barrier
	s_nop 2
	ds_read_b128 v[76:79], v239 offset:49152
	ds_read_b128 v[80:83], v239 offset:50176
	ds_read_b128 v[84:87], v239 offset:51200
	ds_read_b128 v[88:91], v239 offset:52224
	ds_read_b128 v[92:95], v239 offset:53248
	ds_read_b128 v[96:99], v239 offset:54272
	ds_read_b128 v[100:103], v239 offset:55296
	ds_read_b128 v[210:213], v239 offset:56320
	s_add_u32 s98, s56, 0x80
	s_addc_u32 s99, s57, 0
	global_load_lds_dwordx4 v204, s[98:99]
	s_mov_b32 m0, s74
	s_nop 0
	global_load_lds_dwordx4 v202, s[98:99]
	s_barrier
	s_waitcnt lgkmcnt(0)
	v_mfma_f32_16x16x32_bf16 v[108:111], v[60:63], v[76:79], v[112:115]
	v_mfma_f32_16x16x32_bf16 v[72:75], v[68:71], v[76:79], v[72:75]
	v_mfma_f32_16x16x32_bf16 v[48:51], v[60:63], v[84:87], v[48:51]
	v_mfma_f32_16x16x32_bf16 v[40:43], v[68:71], v[84:87], v[40:43]
	v_mfma_f32_16x16x32_bf16 v[32:35], v[60:63], v[92:95], v[32:35]
	v_mfma_f32_16x16x32_bf16 v[24:27], v[68:71], v[92:95], v[24:27]
	v_mfma_f32_16x16x32_bf16 v[16:19], v[60:63], v[100:103], v[16:19]
	v_mfma_f32_16x16x32_bf16 v[12:15], v[68:71], v[100:103], v[12:15]
	v_mfma_f32_16x16x32_bf16 v[112:115], v[64:67], v[80:83], v[108:111]
	v_mfma_f32_16x16x32_bf16 v[72:75], v[104:107], v[80:83], v[72:75]
	v_mfma_f32_16x16x32_bf16 v[48:51], v[64:67], v[88:91], v[48:51]
	v_mfma_f32_16x16x32_bf16 v[40:43], v[104:107], v[88:91], v[40:43]
	v_mfma_f32_16x16x32_bf16 v[32:35], v[64:67], v[96:99], v[32:35]
	v_mfma_f32_16x16x32_bf16 v[24:27], v[104:107], v[96:99], v[24:27]
	v_mfma_f32_16x16x32_bf16 v[16:19], v[64:67], v[210:213], v[16:19]
	v_mfma_f32_16x16x32_bf16 v[12:15], v[104:107], v[210:213], v[12:15]
	s_barrier
	s_add_u32 s22, s54, 0x40080
	s_addc_u32 s23, s55, 0
	s_add_i32 s24, s25, s60
	s_mov_b32 m0, s24
	s_nop 0
	global_load_lds_dwordx4 v2, s[22:23]
	s_add_i32 m0, s24, 0x2000
	s_nop 0
	global_load_lds_dwordx4 v0, s[22:23]
	s_waitcnt vmcnt(6)
	s_barrier
	v_mfma_f32_16x16x32_bf16 v[52:55], v[116:119], v[76:79], v[52:55]
	v_mfma_f32_16x16x32_bf16 v[108:111], v[120:123], v[80:83], v[52:55]
	v_mfma_f32_16x16x32_bf16 v[52:55], v[124:127], v[76:79], v[56:59]
	v_mfma_f32_16x16x32_bf16 v[44:47], v[116:119], v[84:87], v[44:47]
	v_mfma_f32_16x16x32_bf16 v[36:39], v[124:127], v[84:87], v[36:39]
	v_mfma_f32_16x16x32_bf16 v[28:31], v[116:119], v[92:95], v[28:31]
	v_mfma_f32_16x16x32_bf16 v[20:23], v[124:127], v[92:95], v[20:23]
	v_mfma_f32_16x16x32_bf16 v[8:11], v[116:119], v[100:103], v[8:11]
	v_mfma_f32_16x16x32_bf16 v[4:7], v[124:127], v[100:103], v[4:7]
	v_mfma_f32_16x16x32_bf16 v[68:71], v[128:131], v[80:83], v[52:55]
	v_mfma_f32_16x16x32_bf16 v[44:47], v[120:123], v[88:91], v[44:47]
	v_mfma_f32_16x16x32_bf16 v[36:39], v[128:131], v[88:91], v[36:39]
	v_mfma_f32_16x16x32_bf16 v[28:31], v[120:123], v[96:99], v[28:31]
	v_mfma_f32_16x16x32_bf16 v[20:23], v[128:131], v[96:99], v[20:23]
	v_mfma_f32_16x16x32_bf16 v[8:11], v[120:123], v[210:213], v[8:11]
	v_mfma_f32_16x16x32_bf16 v[4:7], v[128:131], v[210:213], v[4:7]
	s_add_i32 s21, s21, 2
	s_add_u32 s52, s52, 0x100
	s_addc_u32 s53, s53, 0
	s_add_u32 s1, s1, 0x100
	s_addc_u32 s20, s20, 0
	s_cmp_gt_u32 s21, 13
	s_barrier
	s_cbranch_scc0 .LBB0_80
	v_lshl_or_b32 v210, s30, 7, v238
	s_lshl_b32 s1, s50, 8
	s_add_i32 s1, s1, s67
	v_lshlrev_b32_e32 v211, 2, v210
	v_lshlrev_b32_e32 v219, 1, v210
	v_readlane_b32 s2, v252, 4
	v_readlane_b32 s3, v252, 5
	v_readlane_b32 s20, v252, 20
	v_readlane_b32 s21, v252, 21
	v_readlane_b32 s22, v252, 2
	v_readlane_b32 s23, v252, 3
	v_readlane_b32 s24, v252, 22
	v_readlane_b32 s25, v252, 23
	v_readlane_b32 s26, v252, 24
	v_readlane_b32 s27, v252, 25
	v_readlane_b32 s50, v252, 26
	v_readlane_b32 s51, v252, 27
	v_readlane_b32 s56, v252, 28
	v_readlane_b32 s57, v252, 29
	v_readlane_b32 s98, v252, 30
	v_readlane_b32 s99, v252, 31
	v_lshl_add_u32 v240, v201, 2, s1
	v_mul_u32_u24_e32 v240, 0x1600, v240
	v_add_u32_e32 v240, v240, v219
	global_load_dwordx4 v[120:123], v211, s[2:3]
	global_load_dwordx4 v[80:83], v211, s[2:3] offset:16
	global_load_dwordx4 v[116:119], v211, s[20:21]
	global_load_dwordx4 v[76:79], v211, s[20:21] offset:16
	global_load_dwordx4 v[96:99], v211, s[22:23]
	global_load_dwordx4 v[56:59], v211, s[22:23] offset:16
	global_load_dwordx4 v[92:95], v211, s[24:25]
	global_load_dwordx4 v[52:55], v211, s[24:25] offset:16
	global_load_dwordx4 v[104:107], v211, s[26:27]
	global_load_dwordx4 v[64:67], v211, s[26:27] offset:16
	global_load_dwordx4 v[100:103], v211, s[50:51]
	global_load_dwordx4 v[60:63], v211, s[50:51] offset:16
	global_load_dwordx4 v[124:127], v211, s[56:57]
	global_load_dwordx4 v[84:87], v211, s[56:57] offset:16
	global_load_dwordx4 v[128:131], v211, s[98:99]
	global_load_dwordx4 v[88:91], v211, s[98:99] offset:16
	v_readlane_b32 s56, v254, 63
	v_readlane_b32 s57, v255, 0
	v_cmp_eq_u32_e64 s[2:3], 0, v201
	v_cmp_eq_u32_e64 s[26:27], 15, v201
	s_lshr_b32 s24, s1, 4
	s_mov_b64 exec, s[2:3]
	v_cvt_pk_bf16_f32 v212, v192, v193
	v_cvt_pk_bf16_f32 v213, v194, v195
	v_cvt_pk_bf16_f32 v214, v184, v185
	v_cvt_pk_bf16_f32 v215, v186, v187
	s_add_i32 s20, s24, 2
	s_mulk_i32 s20, 0x2c00
	s_add_u32 s22, s56, s20
	s_addc_u32 s23, s57, 0
	global_store_dwordx4 v219, v[212:215], s[22:23]
	v_cvt_pk_bf16_f32 v242, v188, v189
	v_cvt_pk_bf16_f32 v243, v190, v191
	v_cvt_pk_bf16_f32 v244, v180, v181
	v_cvt_pk_bf16_f32 v245, v182, v183
	s_add_u32 s22, s22, 0x1600
	s_addc_u32 s23, s23, 0
	global_store_dwordx4 v219, v[242:245], s[22:23]
	v_cvt_pk_bf16_f32 v246, v176, v177
	v_cvt_pk_bf16_f32 v247, v178, v179
	v_cvt_pk_bf16_f32 v248, v168, v169
	v_cvt_pk_bf16_f32 v249, v170, v171
	s_add_i32 s20, s24, 3
	s_mulk_i32 s20, 0x2c00
	s_add_u32 s22, s56, s20
	s_addc_u32 s23, s57, 0
	global_store_dwordx4 v219, v[246:249], s[22:23]
	v_cvt_pk_bf16_f32 v212, v172, v173
	v_cvt_pk_bf16_f32 v213, v174, v175
	v_cvt_pk_bf16_f32 v214, v164, v165
	v_cvt_pk_bf16_f32 v215, v166, v167
	s_add_u32 s22, s22, 0x1600
	s_addc_u32 s23, s23, 0
	global_store_dwordx4 v219, v[212:215], s[22:23]
	s_mov_b64 exec, s[26:27]
	v_cvt_pk_bf16_f32 v242, v160, v161
	v_cvt_pk_bf16_f32 v243, v162, v163
	v_cvt_pk_bf16_f32 v244, v152, v153
	v_cvt_pk_bf16_f32 v245, v154, v155
	s_add_i32 s20, s24, 0
	s_mulk_i32 s20, 0x2c00
	s_add_u32 s22, s56, s20
	s_addc_u32 s23, s57, 0
	global_store_dwordx4 v219, v[242:245], s[22:23]
	v_cvt_pk_bf16_f32 v246, v156, v157
	v_cvt_pk_bf16_f32 v247, v158, v159
	v_cvt_pk_bf16_f32 v248, v148, v149
	v_cvt_pk_bf16_f32 v249, v150, v151
	s_add_u32 s22, s22, 0x1600
	s_addc_u32 s23, s23, 0
	global_store_dwordx4 v219, v[246:249], s[22:23]
	v_cvt_pk_bf16_f32 v212, v144, v145
	v_cvt_pk_bf16_f32 v213, v146, v147
	v_cvt_pk_bf16_f32 v214, v140, v141
	v_cvt_pk_bf16_f32 v215, v142, v143
	s_add_i32 s20, s24, 1
	s_mulk_i32 s20, 0x2c00
	s_add_u32 s22, s56, s20
	s_addc_u32 s23, s57, 0
	global_store_dwordx4 v219, v[212:215], s[22:23]
	v_cvt_pk_bf16_f32 v242, v136, v137
	v_cvt_pk_bf16_f32 v243, v138, v139
	v_cvt_pk_bf16_f32 v244, v132, v133
	v_cvt_pk_bf16_f32 v245, v134, v135
	s_add_u32 s22, s22, 0x1600
	s_addc_u32 s23, s23, 0
	global_store_dwordx4 v219, v[242:245], s[22:23]
	s_mov_b64 exec, s[2:3]
	v_cvt_pk_bf16_f32 v246, v112, v113
	v_cvt_pk_bf16_f32 v247, v114, v115
	v_cvt_pk_bf16_f32 v248, v72, v73
	v_cvt_pk_bf16_f32 v249, v74, v75
	s_add_i32 s20, s24, 10
	s_mulk_i32 s20, 0x2c00
	s_add_u32 s22, s56, s20
	s_addc_u32 s23, s57, 0
	global_store_dwordx4 v219, v[246:249], s[22:23]
	v_cvt_pk_bf16_f32 v212, v108, v109
	v_cvt_pk_bf16_f32 v213, v110, v111
	v_cvt_pk_bf16_f32 v214, v68, v69
	v_cvt_pk_bf16_f32 v215, v70, v71
	s_add_u32 s22, s22, 0x1600
	s_addc_u32 s23, s23, 0
	global_store_dwordx4 v219, v[212:215], s[22:23]
	v_cvt_pk_bf16_f32 v242, v48, v49
	v_cvt_pk_bf16_f32 v243, v50, v51
	v_cvt_pk_bf16_f32 v244, v40, v41
	v_cvt_pk_bf16_f32 v245, v42, v43
	s_add_i32 s20, s24, 11
	s_mulk_i32 s20, 0x2c00
	s_add_u32 s22, s56, s20
	s_addc_u32 s23, s57, 0
	global_store_dwordx4 v219, v[242:245], s[22:23]
	v_cvt_pk_bf16_f32 v246, v44, v45
	v_cvt_pk_bf16_f32 v247, v46, v47
	v_cvt_pk_bf16_f32 v248, v36, v37
	v_cvt_pk_bf16_f32 v249, v38, v39
	s_add_u32 s22, s22, 0x1600
	s_addc_u32 s23, s23, 0
	global_store_dwordx4 v219, v[246:249], s[22:23]
	s_mov_b64 exec, s[26:27]
	v_cvt_pk_bf16_f32 v212, v32, v33
	v_cvt_pk_bf16_f32 v213, v34, v35
	v_cvt_pk_bf16_f32 v214, v24, v25
	v_cvt_pk_bf16_f32 v215, v26, v27
	s_add_i32 s20, s24, 8
	s_mulk_i32 s20, 0x2c00
	s_add_u32 s22, s56, s20
	s_addc_u32 s23, s57, 0
	global_store_dwordx4 v219, v[212:215], s[22:23]
	v_cvt_pk_bf16_f32 v242, v28, v29
	v_cvt_pk_bf16_f32 v243, v30, v31
	v_cvt_pk_bf16_f32 v244, v20, v21
	v_cvt_pk_bf16_f32 v245, v22, v23
	s_add_u32 s22, s22, 0x1600
	s_addc_u32 s23, s23, 0
	global_store_dwordx4 v219, v[242:245], s[22:23]
	v_cvt_pk_bf16_f32 v246, v16, v17
	v_cvt_pk_bf16_f32 v247, v18, v19
	v_cvt_pk_bf16_f32 v248, v12, v13
	v_cvt_pk_bf16_f32 v249, v14, v15
	s_add_i32 s20, s24, 9
	s_mulk_i32 s20, 0x2c00
	s_add_u32 s22, s56, s20
	s_addc_u32 s23, s57, 0
	global_store_dwordx4 v219, v[246:249], s[22:23]
	v_cvt_pk_bf16_f32 v212, v8, v9
	v_cvt_pk_bf16_f32 v213, v10, v11
	v_cvt_pk_bf16_f32 v214, v4, v5
	v_cvt_pk_bf16_f32 v215, v6, v7
	s_add_u32 s22, s22, 0x1600
	s_addc_u32 s23, s23, 0
	global_store_dwordx4 v219, v[212:215], s[22:23]
	s_mov_b64 exec, -1
	s_mov_b32 s50, 0xbfb8aa3b
	s_mov_b32 s51, 0xbfb8aa3b
	s_waitcnt vmcnt(16)
	v_mov_b32_dpp v198, v144 row_shr:1 row_mask:0xf bank_mask:0xf bound_ctrl:1
	v_mov_b32_dpp v199, v145 row_shr:1 row_mask:0xf bank_mask:0xf bound_ctrl:1
	v_mov_b32_dpp v214, v136 row_shr:1 row_mask:0xf bank_mask:0xf bound_ctrl:1
	v_mov_b32_dpp v215, v137 row_shr:1 row_mask:0xf bank_mask:0xf bound_ctrl:1
	v_mov_b32_dpp v212, v160 row_shr:1 row_mask:0xf bank_mask:0xf bound_ctrl:1
	v_mov_b32_dpp v213, v161 row_shr:1 row_mask:0xf bank_mask:0xf bound_ctrl:1
	v_mov_b32_dpp v216, v156 row_shr:1 row_mask:0xf bank_mask:0xf bound_ctrl:1
	v_mov_b32_dpp v217, v157 row_shr:1 row_mask:0xf bank_mask:0xf bound_ctrl:1
	v_pk_fma_f32 v[144:145], v[144:145], v[124:125], v[120:121]
	v_pk_fma_f32 v[136:137], v[136:137], v[128:129], v[116:117]
	v_pk_fma_f32 v[144:145], v[160:161], v[104:105], v[144:145]
	v_pk_fma_f32 v[136:137], v[156:157], v[100:101], v[136:137]
	v_pk_fma_f32 v[144:145], v[176:177], v[96:97], v[144:145]
	v_pk_fma_f32 v[136:137], v[172:173], v[92:93], v[136:137]
	v_pk_fma_f32 v[160:161], v[160:161], v[124:125], v[120:121]
	v_pk_fma_f32 v[156:157], v[156:157], v[128:129], v[116:117]
	v_pk_fma_f32 v[160:161], v[176:177], v[104:105], v[160:161]
	v_pk_fma_f32 v[156:157], v[172:173], v[100:101], v[156:157]
	v_pk_fma_f32 v[160:161], v[192:193], v[96:97], v[160:161]
	v_pk_fma_f32 v[156:157], v[188:189], v[92:93], v[156:157]
	v_pk_fma_f32 v[176:177], v[176:177], v[124:125], v[120:121]
	v_pk_fma_f32 v[172:173], v[172:173], v[128:129], v[116:117]
	v_pk_fma_f32 v[176:177], v[192:193], v[104:105], v[176:177]
	v_pk_fma_f32 v[172:173], v[188:189], v[100:101], v[172:173]
	v_pk_fma_f32 v[176:177], v[198:199], v[96:97], v[176:177]
	v_pk_fma_f32 v[172:173], v[214:215], v[92:93], v[172:173]
	v_pk_fma_f32 v[192:193], v[192:193], v[124:125], v[120:121]
	v_pk_fma_f32 v[188:189], v[188:189], v[128:129], v[116:117]
	v_pk_fma_f32 v[192:193], v[198:199], v[104:105], v[192:193]
	v_pk_fma_f32 v[188:189], v[214:215], v[100:101], v[188:189]
	v_pk_fma_f32 v[192:193], v[212:213], v[96:97], v[192:193]
	v_pk_fma_f32 v[188:189], v[216:217], v[92:93], v[188:189]
	v_pk_mul_f32 v[222:223], v[192:193], s[50:51]
	v_pk_mul_f32 v[242:243], v[176:177], s[50:51]
	v_pk_mul_f32 v[244:245], v[160:161], s[50:51]
	v_pk_mul_f32 v[246:247], v[144:145], s[50:51]
	v_exp_f32_e32 v222, v222
	v_exp_f32_e32 v223, v223
	v_exp_f32_e32 v242, v242
	v_exp_f32_e32 v243, v243
	v_exp_f32_e32 v244, v244
	v_exp_f32_e32 v245, v245
	v_exp_f32_e32 v246, v246
	v_exp_f32_e32 v247, v247
	v_pk_add_f32 v[222:223], v[222:223], 1.0 op_sel_hi:[1,0]
	v_pk_add_f32 v[242:243], v[242:243], 1.0 op_sel_hi:[1,0]
	v_pk_add_f32 v[244:245], v[244:245], 1.0 op_sel_hi:[1,0]
	v_pk_add_f32 v[246:247], v[246:247], 1.0 op_sel_hi:[1,0]
	v_rcp_f32_e32 v222, v222
	v_rcp_f32_e32 v223, v223
	v_rcp_f32_e32 v242, v242
	v_rcp_f32_e32 v243, v243
	v_rcp_f32_e32 v244, v244
	v_rcp_f32_e32 v245, v245
	v_rcp_f32_e32 v246, v246
	v_rcp_f32_e32 v247, v247
	v_pk_mul_f32 v[192:193], v[192:193], v[222:223]
	v_pk_mul_f32 v[176:177], v[176:177], v[242:243]
	v_pk_mul_f32 v[160:161], v[160:161], v[244:245]
	v_pk_mul_f32 v[144:145], v[144:145], v[246:247]
	v_pk_mul_f32 v[192:193], v[192:193], v[188:189]
	v_pk_mul_f32 v[176:177], v[176:177], v[172:173]
	v_pk_mul_f32 v[160:161], v[160:161], v[156:157]
	v_pk_mul_f32 v[144:145], v[144:145], v[136:137]
	v_cvt_pk_bf16_f32 v192, v192, v193
	v_cvt_pk_bf16_f32 v176, v176, v177
	v_cvt_pk_bf16_f32 v160, v160, v161
	v_cvt_pk_bf16_f32 v144, v144, v145
	v_mov_b32_dpp v198, v146 row_shr:1 row_mask:0xf bank_mask:0xf bound_ctrl:1
	v_mov_b32_dpp v199, v147 row_shr:1 row_mask:0xf bank_mask:0xf bound_ctrl:1
	v_mov_b32_dpp v214, v138 row_shr:1 row_mask:0xf bank_mask:0xf bound_ctrl:1
	v_mov_b32_dpp v215, v139 row_shr:1 row_mask:0xf bank_mask:0xf bound_ctrl:1
	v_mov_b32_dpp v212, v162 row_shr:1 row_mask:0xf bank_mask:0xf bound_ctrl:1
	v_mov_b32_dpp v213, v163 row_shr:1 row_mask:0xf bank_mask:0xf bound_ctrl:1
	v_mov_b32_dpp v216, v158 row_shr:1 row_mask:0xf bank_mask:0xf bound_ctrl:1
	v_mov_b32_dpp v217, v159 row_shr:1 row_mask:0xf bank_mask:0xf bound_ctrl:1
	v_pk_fma_f32 v[146:147], v[146:147], v[126:127], v[122:123]
	v_pk_fma_f32 v[138:139], v[138:139], v[130:131], v[118:119]
	v_pk_fma_f32 v[146:147], v[162:163], v[106:107], v[146:147]
	v_pk_fma_f32 v[138:139], v[158:159], v[102:103], v[138:139]
	v_pk_fma_f32 v[146:147], v[178:179], v[98:99], v[146:147]
	v_pk_fma_f32 v[138:139], v[174:175], v[94:95], v[138:139]
	v_pk_fma_f32 v[162:163], v[162:163], v[126:127], v[122:123]
	v_pk_fma_f32 v[158:159], v[158:159], v[130:131], v[118:119]
	v_pk_fma_f32 v[162:163], v[178:179], v[106:107], v[162:163]
	v_pk_fma_f32 v[158:159], v[174:175], v[102:103], v[158:159]
	v_pk_fma_f32 v[162:163], v[194:195], v[98:99], v[162:163]
	v_pk_fma_f32 v[158:159], v[190:191], v[94:95], v[158:159]
	v_pk_fma_f32 v[178:179], v[178:179], v[126:127], v[122:123]
	v_pk_fma_f32 v[174:175], v[174:175], v[130:131], v[118:119]
	v_pk_fma_f32 v[178:179], v[194:195], v[106:107], v[178:179]
	v_pk_fma_f32 v[174:175], v[190:191], v[102:103], v[174:175]
	v_pk_fma_f32 v[178:179], v[198:199], v[98:99], v[178:179]
	v_pk_fma_f32 v[174:175], v[214:215], v[94:95], v[174:175]
	v_pk_fma_f32 v[194:195], v[194:195], v[126:127], v[122:123]
	v_pk_fma_f32 v[190:191], v[190:191], v[130:131], v[118:119]
	v_pk_fma_f32 v[194:195], v[198:199], v[106:107], v[194:195]
	v_pk_fma_f32 v[190:191], v[214:215], v[102:103], v[190:191]
	v_pk_fma_f32 v[194:195], v[212:213], v[98:99], v[194:195]
	v_pk_fma_f32 v[190:191], v[216:217], v[94:95], v[190:191]
	v_pk_mul_f32 v[222:223], v[194:195], s[50:51]
	v_pk_mul_f32 v[242:243], v[178:179], s[50:51]
	v_pk_mul_f32 v[244:245], v[162:163], s[50:51]
	v_pk_mul_f32 v[246:247], v[146:147], s[50:51]
	v_exp_f32_e32 v222, v222
	v_exp_f32_e32 v223, v223
	v_exp_f32_e32 v242, v242
	v_exp_f32_e32 v243, v243
	v_exp_f32_e32 v244, v244
	v_exp_f32_e32 v245, v245
	v_exp_f32_e32 v246, v246
	v_exp_f32_e32 v247, v247
	v_pk_add_f32 v[222:223], v[222:223], 1.0 op_sel_hi:[1,0]
	v_pk_add_f32 v[242:243], v[242:243], 1.0 op_sel_hi:[1,0]
	v_pk_add_f32 v[244:245], v[244:245], 1.0 op_sel_hi:[1,0]
	v_pk_add_f32 v[246:247], v[246:247], 1.0 op_sel_hi:[1,0]
	v_rcp_f32_e32 v222, v222
	v_rcp_f32_e32 v223, v223
	v_rcp_f32_e32 v242, v242
	v_rcp_f32_e32 v243, v243
	v_rcp_f32_e32 v244, v244
	v_rcp_f32_e32 v245, v245
	v_rcp_f32_e32 v246, v246
	v_rcp_f32_e32 v247, v247
	v_pk_mul_f32 v[194:195], v[194:195], v[222:223]
	v_pk_mul_f32 v[178:179], v[178:179], v[242:243]
	v_pk_mul_f32 v[162:163], v[162:163], v[244:245]
	v_pk_mul_f32 v[146:147], v[146:147], v[246:247]
	v_pk_mul_f32 v[194:195], v[194:195], v[190:191]
	v_pk_mul_f32 v[178:179], v[178:179], v[174:175]
	v_pk_mul_f32 v[162:163], v[162:163], v[158:159]
	v_pk_mul_f32 v[146:147], v[146:147], v[138:139]
	v_cvt_pk_bf16_f32 v193, v194, v195
	v_cvt_pk_bf16_f32 v177, v178, v179
	v_cvt_pk_bf16_f32 v161, v162, v163
	v_cvt_pk_bf16_f32 v145, v146, v147
	v_mov_b32_dpp v198, v140 row_shr:1 row_mask:0xf bank_mask:0xf bound_ctrl:1
	v_mov_b32_dpp v199, v141 row_shr:1 row_mask:0xf bank_mask:0xf bound_ctrl:1
	v_mov_b32_dpp v214, v132 row_shr:1 row_mask:0xf bank_mask:0xf bound_ctrl:1
	v_mov_b32_dpp v215, v133 row_shr:1 row_mask:0xf bank_mask:0xf bound_ctrl:1
	v_mov_b32_dpp v212, v152 row_shr:1 row_mask:0xf bank_mask:0xf bound_ctrl:1
	v_mov_b32_dpp v213, v153 row_shr:1 row_mask:0xf bank_mask:0xf bound_ctrl:1
	v_mov_b32_dpp v216, v148 row_shr:1 row_mask:0xf bank_mask:0xf bound_ctrl:1
	v_mov_b32_dpp v217, v149 row_shr:1 row_mask:0xf bank_mask:0xf bound_ctrl:1
	v_pk_fma_f32 v[140:141], v[140:141], v[84:85], v[80:81]
	v_pk_fma_f32 v[132:133], v[132:133], v[88:89], v[76:77]
	v_pk_fma_f32 v[140:141], v[152:153], v[64:65], v[140:141]
	v_pk_fma_f32 v[132:133], v[148:149], v[60:61], v[132:133]
	v_pk_fma_f32 v[140:141], v[168:169], v[56:57], v[140:141]
	v_pk_fma_f32 v[132:133], v[164:165], v[52:53], v[132:133]
	v_pk_fma_f32 v[152:153], v[152:153], v[84:85], v[80:81]
	v_pk_fma_f32 v[148:149], v[148:149], v[88:89], v[76:77]
	v_pk_fma_f32 v[152:153], v[168:169], v[64:65], v[152:153]
	v_pk_fma_f32 v[148:149], v[164:165], v[60:61], v[148:149]
	v_pk_fma_f32 v[152:153], v[184:185], v[56:57], v[152:153]
	v_pk_fma_f32 v[148:149], v[180:181], v[52:53], v[148:149]
	v_pk_fma_f32 v[168:169], v[168:169], v[84:85], v[80:81]
	v_pk_fma_f32 v[164:165], v[164:165], v[88:89], v[76:77]
	v_pk_fma_f32 v[168:169], v[184:185], v[64:65], v[168:169]
	v_pk_fma_f32 v[164:165], v[180:181], v[60:61], v[164:165]
	v_pk_fma_f32 v[168:169], v[198:199], v[56:57], v[168:169]
	v_pk_fma_f32 v[164:165], v[214:215], v[52:53], v[164:165]
	v_pk_fma_f32 v[184:185], v[184:185], v[84:85], v[80:81]
	v_pk_fma_f32 v[180:181], v[180:181], v[88:89], v[76:77]
	v_pk_fma_f32 v[184:185], v[198:199], v[64:65], v[184:185]
	v_pk_fma_f32 v[180:181], v[214:215], v[60:61], v[180:181]
	v_pk_fma_f32 v[184:185], v[212:213], v[56:57], v[184:185]
	v_pk_fma_f32 v[180:181], v[216:217], v[52:53], v[180:181]
	v_pk_mul_f32 v[222:223], v[184:185], s[50:51]
	v_pk_mul_f32 v[242:243], v[168:169], s[50:51]
	v_pk_mul_f32 v[244:245], v[152:153], s[50:51]
	v_pk_mul_f32 v[246:247], v[140:141], s[50:51]
	v_exp_f32_e32 v222, v222
	v_exp_f32_e32 v223, v223
	v_exp_f32_e32 v242, v242
	v_exp_f32_e32 v243, v243
	v_exp_f32_e32 v244, v244
	v_exp_f32_e32 v245, v245
	v_exp_f32_e32 v246, v246
	v_exp_f32_e32 v247, v247
	v_pk_add_f32 v[222:223], v[222:223], 1.0 op_sel_hi:[1,0]
	v_pk_add_f32 v[242:243], v[242:243], 1.0 op_sel_hi:[1,0]
	v_pk_add_f32 v[244:245], v[244:245], 1.0 op_sel_hi:[1,0]
	v_pk_add_f32 v[246:247], v[246:247], 1.0 op_sel_hi:[1,0]
	v_rcp_f32_e32 v222, v222
	v_rcp_f32_e32 v223, v223
	v_rcp_f32_e32 v242, v242
	v_rcp_f32_e32 v243, v243
	v_rcp_f32_e32 v244, v244
	v_rcp_f32_e32 v245, v245
	v_rcp_f32_e32 v246, v246
	v_rcp_f32_e32 v247, v247
	v_pk_mul_f32 v[184:185], v[184:185], v[222:223]
	v_pk_mul_f32 v[168:169], v[168:169], v[242:243]
	v_pk_mul_f32 v[152:153], v[152:153], v[244:245]
	v_pk_mul_f32 v[140:141], v[140:141], v[246:247]
	v_pk_mul_f32 v[184:185], v[184:185], v[180:181]
	v_pk_mul_f32 v[168:169], v[168:169], v[164:165]
	v_pk_mul_f32 v[152:153], v[152:153], v[148:149]
	v_pk_mul_f32 v[140:141], v[140:141], v[132:133]
	v_cvt_pk_bf16_f32 v194, v184, v185
	v_cvt_pk_bf16_f32 v178, v168, v169
	v_cvt_pk_bf16_f32 v162, v152, v153
	v_cvt_pk_bf16_f32 v146, v140, v141
	v_mov_b32_dpp v198, v142 row_shr:1 row_mask:0xf bank_mask:0xf bound_ctrl:1
	v_mov_b32_dpp v199, v143 row_shr:1 row_mask:0xf bank_mask:0xf bound_ctrl:1
	v_mov_b32_dpp v214, v134 row_shr:1 row_mask:0xf bank_mask:0xf bound_ctrl:1
	v_mov_b32_dpp v215, v135 row_shr:1 row_mask:0xf bank_mask:0xf bound_ctrl:1
	v_mov_b32_dpp v212, v154 row_shr:1 row_mask:0xf bank_mask:0xf bound_ctrl:1
	v_mov_b32_dpp v213, v155 row_shr:1 row_mask:0xf bank_mask:0xf bound_ctrl:1
	v_mov_b32_dpp v216, v150 row_shr:1 row_mask:0xf bank_mask:0xf bound_ctrl:1
	v_mov_b32_dpp v217, v151 row_shr:1 row_mask:0xf bank_mask:0xf bound_ctrl:1
	v_pk_fma_f32 v[142:143], v[142:143], v[86:87], v[82:83]
	v_pk_fma_f32 v[134:135], v[134:135], v[90:91], v[78:79]
	v_pk_fma_f32 v[142:143], v[154:155], v[66:67], v[142:143]
	v_pk_fma_f32 v[134:135], v[150:151], v[62:63], v[134:135]
	v_pk_fma_f32 v[142:143], v[170:171], v[58:59], v[142:143]
	v_pk_fma_f32 v[134:135], v[166:167], v[54:55], v[134:135]
	v_pk_fma_f32 v[154:155], v[154:155], v[86:87], v[82:83]
	v_pk_fma_f32 v[150:151], v[150:151], v[90:91], v[78:79]
	v_pk_fma_f32 v[154:155], v[170:171], v[66:67], v[154:155]
	v_pk_fma_f32 v[150:151], v[166:167], v[62:63], v[150:151]
	v_pk_fma_f32 v[154:155], v[186:187], v[58:59], v[154:155]
	v_pk_fma_f32 v[150:151], v[182:183], v[54:55], v[150:151]
	v_pk_fma_f32 v[170:171], v[170:171], v[86:87], v[82:83]
	v_pk_fma_f32 v[166:167], v[166:167], v[90:91], v[78:79]
	v_pk_fma_f32 v[170:171], v[186:187], v[66:67], v[170:171]
	v_pk_fma_f32 v[166:167], v[182:183], v[62:63], v[166:167]
	v_pk_fma_f32 v[170:171], v[198:199], v[58:59], v[170:171]
	v_pk_fma_f32 v[166:167], v[214:215], v[54:55], v[166:167]
	v_pk_fma_f32 v[186:187], v[186:187], v[86:87], v[82:83]
	v_pk_fma_f32 v[182:183], v[182:183], v[90:91], v[78:79]
	v_pk_fma_f32 v[186:187], v[198:199], v[66:67], v[186:187]
	v_pk_fma_f32 v[182:183], v[214:215], v[62:63], v[182:183]
	v_pk_fma_f32 v[186:187], v[212:213], v[58:59], v[186:187]
	v_pk_fma_f32 v[182:183], v[216:217], v[54:55], v[182:183]
	v_pk_mul_f32 v[222:223], v[186:187], s[50:51]
	v_pk_mul_f32 v[242:243], v[170:171], s[50:51]
	v_pk_mul_f32 v[244:245], v[154:155], s[50:51]
	v_pk_mul_f32 v[246:247], v[142:143], s[50:51]
	v_exp_f32_e32 v222, v222
	v_exp_f32_e32 v223, v223
	v_exp_f32_e32 v242, v242
	v_exp_f32_e32 v243, v243
	v_exp_f32_e32 v244, v244
	v_exp_f32_e32 v245, v245
	v_exp_f32_e32 v246, v246
	v_exp_f32_e32 v247, v247
	v_pk_add_f32 v[222:223], v[222:223], 1.0 op_sel_hi:[1,0]
	v_pk_add_f32 v[242:243], v[242:243], 1.0 op_sel_hi:[1,0]
	v_pk_add_f32 v[244:245], v[244:245], 1.0 op_sel_hi:[1,0]
	v_pk_add_f32 v[246:247], v[246:247], 1.0 op_sel_hi:[1,0]
	v_rcp_f32_e32 v222, v222
	v_rcp_f32_e32 v223, v223
	v_rcp_f32_e32 v242, v242
	v_rcp_f32_e32 v243, v243
	v_rcp_f32_e32 v244, v244
	v_rcp_f32_e32 v245, v245
	v_rcp_f32_e32 v246, v246
	v_rcp_f32_e32 v247, v247
	v_pk_mul_f32 v[186:187], v[186:187], v[222:223]
	v_pk_mul_f32 v[170:171], v[170:171], v[242:243]
	v_pk_mul_f32 v[154:155], v[154:155], v[244:245]
	v_pk_mul_f32 v[142:143], v[142:143], v[246:247]
	v_pk_mul_f32 v[186:187], v[186:187], v[182:183]
	v_pk_mul_f32 v[170:171], v[170:171], v[166:167]
	v_pk_mul_f32 v[154:155], v[154:155], v[150:151]
	v_pk_mul_f32 v[142:143], v[142:143], v[134:135]
	v_cvt_pk_bf16_f32 v195, v186, v187
	v_cvt_pk_bf16_f32 v179, v170, v171
	v_cvt_pk_bf16_f32 v163, v154, v155
	v_cvt_pk_bf16_f32 v147, v142, v143
	s_mov_b64 s[20:21], s[82:83]
	global_store_dwordx4 v240, v[192:195], s[20:21]
	s_add_u32 s20, s82, 0x1600
	s_addc_u32 s21, s83, 0
	global_store_dwordx4 v240, v[176:179], s[20:21]
	s_add_u32 s20, s82, 0x2c00
	s_addc_u32 s21, s83, 0
	global_store_dwordx4 v240, v[160:163], s[20:21]
	s_add_u32 s20, s82, 0x4200
	s_addc_u32 s21, s83, 0
	global_store_dwordx4 v240, v[144:147], s[20:21]
	v_mov_b32_dpp v198, v16 row_shr:1 row_mask:0xf bank_mask:0xf bound_ctrl:1
	v_mov_b32_dpp v199, v17 row_shr:1 row_mask:0xf bank_mask:0xf bound_ctrl:1
	v_mov_b32_dpp v214, v8 row_shr:1 row_mask:0xf bank_mask:0xf bound_ctrl:1
	v_mov_b32_dpp v215, v9 row_shr:1 row_mask:0xf bank_mask:0xf bound_ctrl:1
	v_mov_b32_dpp v212, v32 row_shr:1 row_mask:0xf bank_mask:0xf bound_ctrl:1
	v_mov_b32_dpp v213, v33 row_shr:1 row_mask:0xf bank_mask:0xf bound_ctrl:1
	v_mov_b32_dpp v216, v28 row_shr:1 row_mask:0xf bank_mask:0xf bound_ctrl:1
	v_mov_b32_dpp v217, v29 row_shr:1 row_mask:0xf bank_mask:0xf bound_ctrl:1
	v_pk_fma_f32 v[16:17], v[16:17], v[124:125], v[120:121]
	v_pk_fma_f32 v[8:9], v[8:9], v[128:129], v[116:117]
	v_pk_fma_f32 v[16:17], v[32:33], v[104:105], v[16:17]
	v_pk_fma_f32 v[8:9], v[28:29], v[100:101], v[8:9]
	v_pk_fma_f32 v[16:17], v[48:49], v[96:97], v[16:17]
	v_pk_fma_f32 v[8:9], v[44:45], v[92:93], v[8:9]
	v_pk_fma_f32 v[32:33], v[32:33], v[124:125], v[120:121]
	v_pk_fma_f32 v[28:29], v[28:29], v[128:129], v[116:117]
	v_pk_fma_f32 v[32:33], v[48:49], v[104:105], v[32:33]
	v_pk_fma_f32 v[28:29], v[44:45], v[100:101], v[28:29]
	v_pk_fma_f32 v[32:33], v[112:113], v[96:97], v[32:33]
	v_pk_fma_f32 v[28:29], v[108:109], v[92:93], v[28:29]
	v_pk_fma_f32 v[48:49], v[48:49], v[124:125], v[120:121]
	v_pk_fma_f32 v[44:45], v[44:45], v[128:129], v[116:117]
	v_pk_fma_f32 v[48:49], v[112:113], v[104:105], v[48:49]
	v_pk_fma_f32 v[44:45], v[108:109], v[100:101], v[44:45]
	v_pk_fma_f32 v[48:49], v[198:199], v[96:97], v[48:49]
	v_pk_fma_f32 v[44:45], v[214:215], v[92:93], v[44:45]
	v_pk_fma_f32 v[112:113], v[112:113], v[124:125], v[120:121]
	v_pk_fma_f32 v[108:109], v[108:109], v[128:129], v[116:117]
	v_pk_fma_f32 v[112:113], v[198:199], v[104:105], v[112:113]
	v_pk_fma_f32 v[108:109], v[214:215], v[100:101], v[108:109]
	v_pk_fma_f32 v[112:113], v[212:213], v[96:97], v[112:113]
	v_pk_fma_f32 v[108:109], v[216:217], v[92:93], v[108:109]
	v_pk_mul_f32 v[222:223], v[112:113], s[50:51]
	v_pk_mul_f32 v[242:243], v[48:49], s[50:51]
	v_pk_mul_f32 v[244:245], v[32:33], s[50:51]
	v_pk_mul_f32 v[246:247], v[16:17], s[50:51]
	v_exp_f32_e32 v222, v222
	v_exp_f32_e32 v223, v223
	v_exp_f32_e32 v242, v242
	v_exp_f32_e32 v243, v243
	v_exp_f32_e32 v244, v244
	v_exp_f32_e32 v245, v245
	v_exp_f32_e32 v246, v246
	v_exp_f32_e32 v247, v247
	v_pk_add_f32 v[222:223], v[222:223], 1.0 op_sel_hi:[1,0]
	v_pk_add_f32 v[242:243], v[242:243], 1.0 op_sel_hi:[1,0]
	v_pk_add_f32 v[244:245], v[244:245], 1.0 op_sel_hi:[1,0]
	v_pk_add_f32 v[246:247], v[246:247], 1.0 op_sel_hi:[1,0]
	v_rcp_f32_e32 v222, v222
	v_rcp_f32_e32 v223, v223
	v_rcp_f32_e32 v242, v242
	v_rcp_f32_e32 v243, v243
	v_rcp_f32_e32 v244, v244
	v_rcp_f32_e32 v245, v245
	v_rcp_f32_e32 v246, v246
	v_rcp_f32_e32 v247, v247
	v_pk_mul_f32 v[112:113], v[112:113], v[222:223]
	v_pk_mul_f32 v[48:49], v[48:49], v[242:243]
	v_pk_mul_f32 v[32:33], v[32:33], v[244:245]
	v_pk_mul_f32 v[16:17], v[16:17], v[246:247]
	v_pk_mul_f32 v[112:113], v[112:113], v[108:109]
	v_pk_mul_f32 v[48:49], v[48:49], v[44:45]
	v_pk_mul_f32 v[32:33], v[32:33], v[28:29]
	v_pk_mul_f32 v[16:17], v[16:17], v[8:9]
	v_cvt_pk_bf16_f32 v112, v112, v113
	v_cvt_pk_bf16_f32 v48, v48, v49
	v_cvt_pk_bf16_f32 v32, v32, v33
	v_cvt_pk_bf16_f32 v16, v16, v17
	v_mov_b32_dpp v198, v18 row_shr:1 row_mask:0xf bank_mask:0xf bound_ctrl:1
	v_mov_b32_dpp v199, v19 row_shr:1 row_mask:0xf bank_mask:0xf bound_ctrl:1
	v_mov_b32_dpp v214, v10 row_shr:1 row_mask:0xf bank_mask:0xf bound_ctrl:1
	v_mov_b32_dpp v215, v11 row_shr:1 row_mask:0xf bank_mask:0xf bound_ctrl:1
	v_mov_b32_dpp v212, v34 row_shr:1 row_mask:0xf bank_mask:0xf bound_ctrl:1
	v_mov_b32_dpp v213, v35 row_shr:1 row_mask:0xf bank_mask:0xf bound_ctrl:1
	v_mov_b32_dpp v216, v30 row_shr:1 row_mask:0xf bank_mask:0xf bound_ctrl:1
	v_mov_b32_dpp v217, v31 row_shr:1 row_mask:0xf bank_mask:0xf bound_ctrl:1
	v_pk_fma_f32 v[18:19], v[18:19], v[126:127], v[122:123]
	v_pk_fma_f32 v[10:11], v[10:11], v[130:131], v[118:119]
	v_pk_fma_f32 v[18:19], v[34:35], v[106:107], v[18:19]
	v_pk_fma_f32 v[10:11], v[30:31], v[102:103], v[10:11]
	v_pk_fma_f32 v[18:19], v[50:51], v[98:99], v[18:19]
	v_pk_fma_f32 v[10:11], v[46:47], v[94:95], v[10:11]
	v_pk_fma_f32 v[34:35], v[34:35], v[126:127], v[122:123]
	v_pk_fma_f32 v[30:31], v[30:31], v[130:131], v[118:119]
	v_pk_fma_f32 v[34:35], v[50:51], v[106:107], v[34:35]
	v_pk_fma_f32 v[30:31], v[46:47], v[102:103], v[30:31]
	v_pk_fma_f32 v[34:35], v[114:115], v[98:99], v[34:35]
	v_pk_fma_f32 v[30:31], v[110:111], v[94:95], v[30:31]
	v_pk_fma_f32 v[50:51], v[50:51], v[126:127], v[122:123]
	v_pk_fma_f32 v[46:47], v[46:47], v[130:131], v[118:119]
	v_pk_fma_f32 v[50:51], v[114:115], v[106:107], v[50:51]
	v_pk_fma_f32 v[46:47], v[110:111], v[102:103], v[46:47]
	v_pk_fma_f32 v[50:51], v[198:199], v[98:99], v[50:51]
	v_pk_fma_f32 v[46:47], v[214:215], v[94:95], v[46:47]
	v_pk_fma_f32 v[114:115], v[114:115], v[126:127], v[122:123]
	v_pk_fma_f32 v[110:111], v[110:111], v[130:131], v[118:119]
	v_pk_fma_f32 v[114:115], v[198:199], v[106:107], v[114:115]
	v_pk_fma_f32 v[110:111], v[214:215], v[102:103], v[110:111]
	v_pk_fma_f32 v[114:115], v[212:213], v[98:99], v[114:115]
	v_pk_fma_f32 v[110:111], v[216:217], v[94:95], v[110:111]
	v_pk_mul_f32 v[222:223], v[114:115], s[50:51]
	v_pk_mul_f32 v[242:243], v[50:51], s[50:51]
	v_pk_mul_f32 v[244:245], v[34:35], s[50:51]
	v_pk_mul_f32 v[246:247], v[18:19], s[50:51]
	v_exp_f32_e32 v222, v222
	v_exp_f32_e32 v223, v223
	v_exp_f32_e32 v242, v242
	v_exp_f32_e32 v243, v243
	v_exp_f32_e32 v244, v244
	v_exp_f32_e32 v245, v245
	v_exp_f32_e32 v246, v246
	v_exp_f32_e32 v247, v247
	v_pk_add_f32 v[222:223], v[222:223], 1.0 op_sel_hi:[1,0]
	v_pk_add_f32 v[242:243], v[242:243], 1.0 op_sel_hi:[1,0]
	v_pk_add_f32 v[244:245], v[244:245], 1.0 op_sel_hi:[1,0]
	v_pk_add_f32 v[246:247], v[246:247], 1.0 op_sel_hi:[1,0]
	v_rcp_f32_e32 v222, v222
	v_rcp_f32_e32 v223, v223
	v_rcp_f32_e32 v242, v242
	v_rcp_f32_e32 v243, v243
	v_rcp_f32_e32 v244, v244
	v_rcp_f32_e32 v245, v245
	v_rcp_f32_e32 v246, v246
	v_rcp_f32_e32 v247, v247
	v_pk_mul_f32 v[114:115], v[114:115], v[222:223]
	v_pk_mul_f32 v[50:51], v[50:51], v[242:243]
	v_pk_mul_f32 v[34:35], v[34:35], v[244:245]
	v_pk_mul_f32 v[18:19], v[18:19], v[246:247]
	v_pk_mul_f32 v[114:115], v[114:115], v[110:111]
	v_pk_mul_f32 v[50:51], v[50:51], v[46:47]
	v_pk_mul_f32 v[34:35], v[34:35], v[30:31]
	v_pk_mul_f32 v[18:19], v[18:19], v[10:11]
	v_cvt_pk_bf16_f32 v113, v114, v115
	v_cvt_pk_bf16_f32 v49, v50, v51
	v_cvt_pk_bf16_f32 v33, v34, v35
	v_cvt_pk_bf16_f32 v17, v18, v19
	v_mov_b32_dpp v198, v12 row_shr:1 row_mask:0xf bank_mask:0xf bound_ctrl:1
	v_mov_b32_dpp v199, v13 row_shr:1 row_mask:0xf bank_mask:0xf bound_ctrl:1
	v_mov_b32_dpp v214, v4 row_shr:1 row_mask:0xf bank_mask:0xf bound_ctrl:1
	v_mov_b32_dpp v215, v5 row_shr:1 row_mask:0xf bank_mask:0xf bound_ctrl:1
	v_mov_b32_dpp v212, v24 row_shr:1 row_mask:0xf bank_mask:0xf bound_ctrl:1
	v_mov_b32_dpp v213, v25 row_shr:1 row_mask:0xf bank_mask:0xf bound_ctrl:1
	v_mov_b32_dpp v216, v20 row_shr:1 row_mask:0xf bank_mask:0xf bound_ctrl:1
	v_mov_b32_dpp v217, v21 row_shr:1 row_mask:0xf bank_mask:0xf bound_ctrl:1
	v_pk_fma_f32 v[12:13], v[12:13], v[84:85], v[80:81]
	v_pk_fma_f32 v[4:5], v[4:5], v[88:89], v[76:77]
	v_pk_fma_f32 v[12:13], v[24:25], v[64:65], v[12:13]
	v_pk_fma_f32 v[4:5], v[20:21], v[60:61], v[4:5]
	v_pk_fma_f32 v[12:13], v[40:41], v[56:57], v[12:13]
	v_pk_fma_f32 v[4:5], v[36:37], v[52:53], v[4:5]
	v_pk_fma_f32 v[24:25], v[24:25], v[84:85], v[80:81]
	v_pk_fma_f32 v[20:21], v[20:21], v[88:89], v[76:77]
	v_pk_fma_f32 v[24:25], v[40:41], v[64:65], v[24:25]
	v_pk_fma_f32 v[20:21], v[36:37], v[60:61], v[20:21]
	v_pk_fma_f32 v[24:25], v[72:73], v[56:57], v[24:25]
	v_pk_fma_f32 v[20:21], v[68:69], v[52:53], v[20:21]
	v_pk_fma_f32 v[40:41], v[40:41], v[84:85], v[80:81]
	v_pk_fma_f32 v[36:37], v[36:37], v[88:89], v[76:77]
	v_pk_fma_f32 v[40:41], v[72:73], v[64:65], v[40:41]
	v_pk_fma_f32 v[36:37], v[68:69], v[60:61], v[36:37]
	v_pk_fma_f32 v[40:41], v[198:199], v[56:57], v[40:41]
	v_pk_fma_f32 v[36:37], v[214:215], v[52:53], v[36:37]
	v_pk_fma_f32 v[72:73], v[72:73], v[84:85], v[80:81]
	v_pk_fma_f32 v[68:69], v[68:69], v[88:89], v[76:77]
	v_pk_fma_f32 v[72:73], v[198:199], v[64:65], v[72:73]
	v_pk_fma_f32 v[68:69], v[214:215], v[60:61], v[68:69]
	v_pk_fma_f32 v[72:73], v[212:213], v[56:57], v[72:73]
	v_pk_fma_f32 v[68:69], v[216:217], v[52:53], v[68:69]
	v_pk_mul_f32 v[222:223], v[72:73], s[50:51]
	v_pk_mul_f32 v[242:243], v[40:41], s[50:51]
	v_pk_mul_f32 v[244:245], v[24:25], s[50:51]
	v_pk_mul_f32 v[246:247], v[12:13], s[50:51]
	v_exp_f32_e32 v222, v222
	v_exp_f32_e32 v223, v223
	v_exp_f32_e32 v242, v242
	v_exp_f32_e32 v243, v243
	v_exp_f32_e32 v244, v244
	v_exp_f32_e32 v245, v245
	v_exp_f32_e32 v246, v246
	v_exp_f32_e32 v247, v247
	v_pk_add_f32 v[222:223], v[222:223], 1.0 op_sel_hi:[1,0]
	v_pk_add_f32 v[242:243], v[242:243], 1.0 op_sel_hi:[1,0]
	v_pk_add_f32 v[244:245], v[244:245], 1.0 op_sel_hi:[1,0]
	v_pk_add_f32 v[246:247], v[246:247], 1.0 op_sel_hi:[1,0]
	v_rcp_f32_e32 v222, v222
	v_rcp_f32_e32 v223, v223
	v_rcp_f32_e32 v242, v242
	v_rcp_f32_e32 v243, v243
	v_rcp_f32_e32 v244, v244
	v_rcp_f32_e32 v245, v245
	v_rcp_f32_e32 v246, v246
	v_rcp_f32_e32 v247, v247
	v_pk_mul_f32 v[72:73], v[72:73], v[222:223]
	v_pk_mul_f32 v[40:41], v[40:41], v[242:243]
	v_pk_mul_f32 v[24:25], v[24:25], v[244:245]
	v_pk_mul_f32 v[12:13], v[12:13], v[246:247]
	v_pk_mul_f32 v[72:73], v[72:73], v[68:69]
	v_pk_mul_f32 v[40:41], v[40:41], v[36:37]
	v_pk_mul_f32 v[24:25], v[24:25], v[20:21]
	v_pk_mul_f32 v[12:13], v[12:13], v[4:5]
	v_cvt_pk_bf16_f32 v114, v72, v73
	v_cvt_pk_bf16_f32 v50, v40, v41
	v_cvt_pk_bf16_f32 v34, v24, v25
	v_cvt_pk_bf16_f32 v18, v12, v13
	v_mov_b32_dpp v198, v14 row_shr:1 row_mask:0xf bank_mask:0xf bound_ctrl:1
	v_mov_b32_dpp v199, v15 row_shr:1 row_mask:0xf bank_mask:0xf bound_ctrl:1
	v_mov_b32_dpp v214, v6 row_shr:1 row_mask:0xf bank_mask:0xf bound_ctrl:1
	v_mov_b32_dpp v215, v7 row_shr:1 row_mask:0xf bank_mask:0xf bound_ctrl:1
	v_mov_b32_dpp v212, v26 row_shr:1 row_mask:0xf bank_mask:0xf bound_ctrl:1
	v_mov_b32_dpp v213, v27 row_shr:1 row_mask:0xf bank_mask:0xf bound_ctrl:1
	v_mov_b32_dpp v216, v22 row_shr:1 row_mask:0xf bank_mask:0xf bound_ctrl:1
	v_mov_b32_dpp v217, v23 row_shr:1 row_mask:0xf bank_mask:0xf bound_ctrl:1
	v_pk_fma_f32 v[14:15], v[14:15], v[86:87], v[82:83]
	v_pk_fma_f32 v[6:7], v[6:7], v[90:91], v[78:79]
	v_pk_fma_f32 v[14:15], v[26:27], v[66:67], v[14:15]
	v_pk_fma_f32 v[6:7], v[22:23], v[62:63], v[6:7]
	v_pk_fma_f32 v[14:15], v[42:43], v[58:59], v[14:15]
	v_pk_fma_f32 v[6:7], v[38:39], v[54:55], v[6:7]
	v_pk_fma_f32 v[26:27], v[26:27], v[86:87], v[82:83]
	v_pk_fma_f32 v[22:23], v[22:23], v[90:91], v[78:79]
	v_pk_fma_f32 v[26:27], v[42:43], v[66:67], v[26:27]
	v_pk_fma_f32 v[22:23], v[38:39], v[62:63], v[22:23]
	v_pk_fma_f32 v[26:27], v[74:75], v[58:59], v[26:27]
	v_pk_fma_f32 v[22:23], v[70:71], v[54:55], v[22:23]
	v_pk_fma_f32 v[42:43], v[42:43], v[86:87], v[82:83]
	v_pk_fma_f32 v[38:39], v[38:39], v[90:91], v[78:79]
	v_pk_fma_f32 v[42:43], v[74:75], v[66:67], v[42:43]
	v_pk_fma_f32 v[38:39], v[70:71], v[62:63], v[38:39]
	v_pk_fma_f32 v[42:43], v[198:199], v[58:59], v[42:43]
	v_pk_fma_f32 v[38:39], v[214:215], v[54:55], v[38:39]
	v_pk_fma_f32 v[74:75], v[74:75], v[86:87], v[82:83]
	v_pk_fma_f32 v[70:71], v[70:71], v[90:91], v[78:79]
	v_pk_fma_f32 v[74:75], v[198:199], v[66:67], v[74:75]
	v_pk_fma_f32 v[70:71], v[214:215], v[62:63], v[70:71]
	v_pk_fma_f32 v[74:75], v[212:213], v[58:59], v[74:75]
	v_pk_fma_f32 v[70:71], v[216:217], v[54:55], v[70:71]
	v_pk_mul_f32 v[222:223], v[74:75], s[50:51]
	v_pk_mul_f32 v[242:243], v[42:43], s[50:51]
	v_pk_mul_f32 v[244:245], v[26:27], s[50:51]
	v_pk_mul_f32 v[246:247], v[14:15], s[50:51]
	v_exp_f32_e32 v222, v222
	v_exp_f32_e32 v223, v223
	v_exp_f32_e32 v242, v242
	v_exp_f32_e32 v243, v243
	v_exp_f32_e32 v244, v244
	v_exp_f32_e32 v245, v245
	v_exp_f32_e32 v246, v246
	v_exp_f32_e32 v247, v247
	v_pk_add_f32 v[222:223], v[222:223], 1.0 op_sel_hi:[1,0]
	v_pk_add_f32 v[242:243], v[242:243], 1.0 op_sel_hi:[1,0]
	v_pk_add_f32 v[244:245], v[244:245], 1.0 op_sel_hi:[1,0]
	v_pk_add_f32 v[246:247], v[246:247], 1.0 op_sel_hi:[1,0]
	v_rcp_f32_e32 v222, v222
	v_rcp_f32_e32 v223, v223
	v_rcp_f32_e32 v242, v242
	v_rcp_f32_e32 v243, v243
	v_rcp_f32_e32 v244, v244
	v_rcp_f32_e32 v245, v245
	v_rcp_f32_e32 v246, v246
	v_rcp_f32_e32 v247, v247
	v_pk_mul_f32 v[74:75], v[74:75], v[222:223]
	v_pk_mul_f32 v[42:43], v[42:43], v[242:243]
	v_pk_mul_f32 v[26:27], v[26:27], v[244:245]
	v_pk_mul_f32 v[14:15], v[14:15], v[246:247]
	v_pk_mul_f32 v[74:75], v[74:75], v[70:71]
	v_pk_mul_f32 v[42:43], v[42:43], v[38:39]
	v_pk_mul_f32 v[26:27], v[26:27], v[22:23]
	v_pk_mul_f32 v[14:15], v[14:15], v[6:7]
	v_cvt_pk_bf16_f32 v115, v74, v75
	v_cvt_pk_bf16_f32 v51, v42, v43
	v_cvt_pk_bf16_f32 v35, v26, v27
	v_cvt_pk_bf16_f32 v19, v14, v15
	s_add_u32 s20, s82, 0xb0000
	s_addc_u32 s21, s83, 0
	global_store_dwordx4 v240, v[112:115], s[20:21]
	s_add_u32 s20, s82, 0xb1600
	s_addc_u32 s21, s83, 0
	global_store_dwordx4 v240, v[48:51], s[20:21]
	s_add_u32 s20, s82, 0xb2c00
	s_addc_u32 s21, s83, 0
	global_store_dwordx4 v240, v[32:35], s[20:21]
	s_add_u32 s20, s82, 0xb4200
	s_addc_u32 s21, s83, 0
	global_store_dwordx4 v240, v[16:19], s[20:21]
	s_mov_b64 s[50:51], -1
	s_branch .LBB0_76

.LBB0_136:
	s_add_u32 s23, s48, 0xfffc0080
	s_addc_u32 s24, s49, -1
	s_add_i32 s25, 0, 0x10000
	v_add_u32_e32 v145, s25, v143
	ds_read_b128 v[146:149], v145
	ds_read_b128 v[150:153], v145 offset:1024
	ds_read_b128 v[154:157], v145 offset:2048
	ds_read_b128 v[158:161], v145 offset:3072
	s_cmp_eq_u32 s22, 12
	s_cselect_b32 s53, s45, s24
	s_cselect_b32 s52, s44, s23
	s_cselect_b32 s51, s47, s21
	s_cselect_b32 s50, s46, s20
	s_add_i32 m0, s54, 0xc000
	ds_read_b128 v[162:165], v144
	ds_read_b128 v[166:169], v144 offset:1024
	ds_read_b128 v[170:173], v144 offset:2048
	ds_read_b128 v[174:177], v144 offset:3072
	ds_read_b128 v[178:181], v144 offset:4096
	ds_read_b128 v[182:185], v144 offset:5120
	ds_read_b128 v[186:189], v144 offset:6144
	ds_read_b128 v[190:193], v144 offset:7168
	global_load_lds_dwordx4 v138, s[48:49]
	s_add_i32 m0, s54, 0xe000
	s_nop 0
	global_load_lds_dwordx4 v140, s[48:49]
	s_waitcnt lgkmcnt(8)
	s_barrier
	s_waitcnt lgkmcnt(0)
	v_mfma_f32_16x16x32_bf16 v[128:131], v[146:149], v[162:165], v[128:131]
	v_mfma_f32_16x16x32_bf16 v[124:127], v[154:157], v[162:165], v[124:127]
	v_mfma_f32_16x16x32_bf16 v[120:123], v[146:149], v[170:173], v[120:123]
	v_mfma_f32_16x16x32_bf16 v[116:119], v[154:157], v[170:173], v[116:119]
	v_mfma_f32_16x16x32_bf16 v[104:107], v[146:149], v[178:181], v[104:107]
	v_mfma_f32_16x16x32_bf16 v[100:103], v[154:157], v[178:181], v[100:103]
	v_mfma_f32_16x16x32_bf16 v[88:91], v[146:149], v[186:189], v[88:91]
	v_mfma_f32_16x16x32_bf16 v[84:87], v[154:157], v[186:189], v[84:87]
	v_mfma_f32_16x16x32_bf16 v[128:131], v[150:153], v[166:169], v[128:131]
	v_mfma_f32_16x16x32_bf16 v[124:127], v[158:161], v[166:169], v[124:127]
	v_mfma_f32_16x16x32_bf16 v[120:123], v[150:153], v[174:177], v[120:123]
	v_mfma_f32_16x16x32_bf16 v[116:119], v[158:161], v[174:177], v[116:119]
	v_mfma_f32_16x16x32_bf16 v[104:107], v[150:153], v[182:185], v[104:107]
	v_mfma_f32_16x16x32_bf16 v[100:103], v[158:161], v[182:185], v[100:103]
	v_mfma_f32_16x16x32_bf16 v[88:91], v[150:153], v[190:193], v[88:91]
	v_mfma_f32_16x16x32_bf16 v[84:87], v[158:161], v[190:193], v[84:87]
	s_barrier
	s_add_i32 s23, 0, 0x14000
	s_add_i32 s24, s25, s37
	v_add_u32_e32 v145, s23, v143
	s_mov_b32 m0, s24
	ds_read_b128 v[202:205], v145
	ds_read_b128 v[206:209], v145 offset:1024
	ds_read_b128 v[210:213], v145 offset:2048
	ds_read_b128 v[214:217], v145 offset:3072
	global_load_lds_dwordx4 v132, s[50:51]
	s_add_i32 m0, s24, 0x2000
	s_nop 0
	global_load_lds_dwordx4 v136, s[50:51]
	s_barrier
	s_waitcnt lgkmcnt(0)
	v_mfma_f32_16x16x32_bf16 v[112:115], v[202:205], v[162:165], v[112:115]
	v_mfma_f32_16x16x32_bf16 v[108:111], v[210:213], v[162:165], v[108:111]
	v_mfma_f32_16x16x32_bf16 v[96:99], v[202:205], v[170:173], v[96:99]
	v_mfma_f32_16x16x32_bf16 v[92:95], v[210:213], v[170:173], v[92:95]
	v_mfma_f32_16x16x32_bf16 v[80:83], v[202:205], v[178:181], v[80:83]
	v_mfma_f32_16x16x32_bf16 v[76:79], v[210:213], v[178:181], v[76:79]
	v_mfma_f32_16x16x32_bf16 v[72:75], v[202:205], v[186:189], v[72:75]
	v_mfma_f32_16x16x32_bf16 v[68:71], v[210:213], v[186:189], v[68:71]
	v_mfma_f32_16x16x32_bf16 v[112:115], v[206:209], v[166:169], v[112:115]
	v_mfma_f32_16x16x32_bf16 v[108:111], v[214:217], v[166:169], v[108:111]
	v_mfma_f32_16x16x32_bf16 v[96:99], v[206:209], v[174:177], v[96:99]
	v_mfma_f32_16x16x32_bf16 v[92:95], v[214:217], v[174:177], v[92:95]
	v_mfma_f32_16x16x32_bf16 v[80:83], v[206:209], v[182:185], v[80:83]
	v_mfma_f32_16x16x32_bf16 v[76:79], v[214:217], v[182:185], v[76:79]
	v_mfma_f32_16x16x32_bf16 v[72:75], v[206:209], v[190:193], v[72:75]
	v_mfma_f32_16x16x32_bf16 v[68:71], v[214:217], v[190:193], v[68:71]
	s_mov_b32 m0, s54
	s_barrier
	ds_read_b128 v[162:165], v144 offset:16384
	ds_read_b128 v[166:169], v144 offset:17408
	ds_read_b128 v[170:173], v144 offset:18432
	ds_read_b128 v[174:177], v144 offset:19456
	ds_read_b128 v[178:181], v144 offset:20480
	ds_read_b128 v[182:185], v144 offset:21504
	ds_read_b128 v[186:189], v144 offset:22528
	ds_read_b128 v[190:193], v144 offset:23552
	global_load_lds_dwordx4 v0, s[52:53]
	s_mov_b32 m0, s55
	s_nop 0
	global_load_lds_dwordx4 v134, s[52:53]
	s_barrier
	s_waitcnt lgkmcnt(0)
	v_mfma_f32_16x16x32_bf16 v[64:67], v[146:149], v[162:165], v[64:67]
	v_mfma_f32_16x16x32_bf16 v[60:63], v[154:157], v[162:165], v[60:63]
	v_mfma_f32_16x16x32_bf16 v[56:59], v[146:149], v[170:173], v[56:59]
	v_mfma_f32_16x16x32_bf16 v[52:55], v[154:157], v[170:173], v[52:55]
	v_mfma_f32_16x16x32_bf16 v[40:43], v[146:149], v[178:181], v[40:43]
	v_mfma_f32_16x16x32_bf16 v[36:39], v[154:157], v[178:181], v[36:39]
	v_mfma_f32_16x16x32_bf16 v[24:27], v[146:149], v[186:189], v[24:27]
	v_mfma_f32_16x16x32_bf16 v[16:19], v[154:157], v[186:189], v[16:19]
	v_mfma_f32_16x16x32_bf16 v[64:67], v[150:153], v[166:169], v[64:67]
	v_mfma_f32_16x16x32_bf16 v[60:63], v[158:161], v[166:169], v[60:63]
	v_mfma_f32_16x16x32_bf16 v[56:59], v[150:153], v[174:177], v[56:59]
	v_mfma_f32_16x16x32_bf16 v[52:55], v[158:161], v[174:177], v[52:55]
	v_mfma_f32_16x16x32_bf16 v[40:43], v[150:153], v[182:185], v[40:43]
	v_mfma_f32_16x16x32_bf16 v[36:39], v[158:161], v[182:185], v[36:39]
	v_mfma_f32_16x16x32_bf16 v[24:27], v[150:153], v[190:193], v[24:27]
	v_mfma_f32_16x16x32_bf16 v[16:19], v[158:161], v[190:193], v[16:19]
	s_barrier
	s_add_u32 s24, s50, 0x40000
	s_addc_u32 s25, s51, 0
	s_add_i32 s23, s23, s37
	s_mov_b32 m0, s23
	s_nop 0
	global_load_lds_dwordx4 v132, s[24:25]
	s_add_i32 m0, s23, 0x2000
	s_nop 0
	global_load_lds_dwordx4 v136, s[24:25]
	s_waitcnt vmcnt(6)
	s_barrier
	v_mfma_f32_16x16x32_bf16 v[48:51], v[202:205], v[162:165], v[48:51]
	v_mfma_f32_16x16x32_bf16 v[44:47], v[210:213], v[162:165], v[44:47]
	v_mfma_f32_16x16x32_bf16 v[32:35], v[202:205], v[170:173], v[32:35]
	v_mfma_f32_16x16x32_bf16 v[28:31], v[210:213], v[170:173], v[28:31]
	v_mfma_f32_16x16x32_bf16 v[20:23], v[202:205], v[178:181], v[20:23]
	v_mfma_f32_16x16x32_bf16 v[12:15], v[210:213], v[178:181], v[12:15]
	v_mfma_f32_16x16x32_bf16 v[8:11], v[202:205], v[186:189], v[8:11]
	v_mfma_f32_16x16x32_bf16 v[4:7], v[210:213], v[186:189], v[4:7]
	v_mfma_f32_16x16x32_bf16 v[48:51], v[206:209], v[166:169], v[48:51]
	v_mfma_f32_16x16x32_bf16 v[44:47], v[214:217], v[166:169], v[44:47]
	v_mfma_f32_16x16x32_bf16 v[32:35], v[206:209], v[174:177], v[32:35]
	v_mfma_f32_16x16x32_bf16 v[28:31], v[214:217], v[174:177], v[28:31]
	v_mfma_f32_16x16x32_bf16 v[20:23], v[206:209], v[182:185], v[20:23]
	v_mfma_f32_16x16x32_bf16 v[12:15], v[214:217], v[182:185], v[12:15]
	v_mfma_f32_16x16x32_bf16 v[8:11], v[206:209], v[190:193], v[8:11]
	v_mfma_f32_16x16x32_bf16 v[4:7], v[214:217], v[190:193], v[4:7]
	s_add_i32 s23, 0, 0x18000
	v_add_u32_e32 v145, s23, v143
	s_barrier
	ds_read_b128 v[146:149], v145
	ds_read_b128 v[150:153], v145 offset:1024
	ds_read_b128 v[154:157], v145 offset:2048
	ds_read_b128 v[158:161], v145 offset:3072
	s_add_u32 s24, s52, 0x40000
	s_addc_u32 s25, s53, 0
	s_mov_b32 m0, s56
	ds_read_b128 v[162:165], v144 offset:32768
	ds_read_b128 v[166:169], v144 offset:33792
	ds_read_b128 v[170:173], v144 offset:34816
	ds_read_b128 v[174:177], v144 offset:35840
	ds_read_b128 v[178:181], v144 offset:36864
	ds_read_b128 v[182:185], v144 offset:37888
	ds_read_b128 v[186:189], v144 offset:38912
	ds_read_b128 v[190:193], v144 offset:39936
	global_load_lds_dwordx4 v0, s[24:25]
	s_mov_b32 m0, s57
	s_nop 0
	global_load_lds_dwordx4 v134, s[24:25]
	s_waitcnt lgkmcnt(8)
	s_barrier
	s_waitcnt lgkmcnt(0)
	v_mfma_f32_16x16x32_bf16 v[128:131], v[146:149], v[162:165], v[128:131]
	v_mfma_f32_16x16x32_bf16 v[124:127], v[154:157], v[162:165], v[124:127]
	v_mfma_f32_16x16x32_bf16 v[120:123], v[146:149], v[170:173], v[120:123]
	v_mfma_f32_16x16x32_bf16 v[116:119], v[154:157], v[170:173], v[116:119]
	v_mfma_f32_16x16x32_bf16 v[104:107], v[146:149], v[178:181], v[104:107]
	v_mfma_f32_16x16x32_bf16 v[100:103], v[154:157], v[178:181], v[100:103]
	v_mfma_f32_16x16x32_bf16 v[88:91], v[146:149], v[186:189], v[88:91]
	v_mfma_f32_16x16x32_bf16 v[84:87], v[154:157], v[186:189], v[84:87]
	v_mfma_f32_16x16x32_bf16 v[128:131], v[150:153], v[166:169], v[128:131]
	v_mfma_f32_16x16x32_bf16 v[124:127], v[158:161], v[166:169], v[124:127]
	v_mfma_f32_16x16x32_bf16 v[120:123], v[150:153], v[174:177], v[120:123]
	v_mfma_f32_16x16x32_bf16 v[116:119], v[158:161], v[174:177], v[116:119]
	v_mfma_f32_16x16x32_bf16 v[104:107], v[150:153], v[182:185], v[104:107]
	v_mfma_f32_16x16x32_bf16 v[100:103], v[158:161], v[182:185], v[100:103]
	v_mfma_f32_16x16x32_bf16 v[88:91], v[150:153], v[190:193], v[88:91]
	v_mfma_f32_16x16x32_bf16 v[84:87], v[158:161], v[190:193], v[84:87]
	s_barrier
	s_add_i32 s26, 0, 0x1c000
	s_add_i32 s23, s23, s37
	v_add_u32_e32 v145, s26, v143
	s_mov_b32 m0, s23
	ds_read_b128 v[202:205], v145
	ds_read_b128 v[206:209], v145 offset:1024
	ds_read_b128 v[210:213], v145 offset:2048
	ds_read_b128 v[214:217], v145 offset:3072
	s_add_u32 s98, s50, 0x80
	s_addc_u32 s99, s51, 0
	global_load_lds_dwordx4 v132, s[98:99]
	s_add_i32 m0, s23, 0x2000
	s_nop 0
	global_load_lds_dwordx4 v136, s[98:99]
	s_barrier
	s_waitcnt lgkmcnt(0)
	v_mfma_f32_16x16x32_bf16 v[112:115], v[202:205], v[162:165], v[112:115]
	v_mfma_f32_16x16x32_bf16 v[108:111], v[210:213], v[162:165], v[108:111]
	v_mfma_f32_16x16x32_bf16 v[96:99], v[202:205], v[170:173], v[96:99]
	v_mfma_f32_16x16x32_bf16 v[92:95], v[210:213], v[170:173], v[92:95]
	v_mfma_f32_16x16x32_bf16 v[80:83], v[202:205], v[178:181], v[80:83]
	v_mfma_f32_16x16x32_bf16 v[76:79], v[210:213], v[178:181], v[76:79]
	v_mfma_f32_16x16x32_bf16 v[72:75], v[202:205], v[186:189], v[72:75]
	v_mfma_f32_16x16x32_bf16 v[68:71], v[210:213], v[186:189], v[68:71]
	v_mfma_f32_16x16x32_bf16 v[112:115], v[206:209], v[166:169], v[112:115]
	v_mfma_f32_16x16x32_bf16 v[108:111], v[214:217], v[166:169], v[108:111]
	v_mfma_f32_16x16x32_bf16 v[96:99], v[206:209], v[174:177], v[96:99]
	v_mfma_f32_16x16x32_bf16 v[92:95], v[214:217], v[174:177], v[92:95]
	v_mfma_f32_16x16x32_bf16 v[80:83], v[206:209], v[182:185], v[80:83]
	v_mfma_f32_16x16x32_bf16 v[76:79], v[214:217], v[182:185], v[76:79]
	v_mfma_f32_16x16x32_bf16 v[72:75], v[206:209], v[190:193], v[72:75]
	v_mfma_f32_16x16x32_bf16 v[68:71], v[214:217], v[190:193], v[68:71]
	s_mov_b32 m0, s59
	s_barrier
	ds_read_b128 v[162:165], v144 offset:49152
	ds_read_b128 v[166:169], v144 offset:50176
	ds_read_b128 v[170:173], v144 offset:51200
	ds_read_b128 v[174:177], v144 offset:52224
	ds_read_b128 v[178:181], v144 offset:53248
	ds_read_b128 v[182:185], v144 offset:54272
	ds_read_b128 v[186:189], v144 offset:55296
	ds_read_b128 v[190:193], v144 offset:56320
	s_add_u32 s98, s52, 0x80
	s_addc_u32 s99, s53, 0
	global_load_lds_dwordx4 v0, s[98:99]
	s_mov_b32 m0, s60
	s_nop 0
	global_load_lds_dwordx4 v134, s[98:99]
	s_barrier
	s_waitcnt lgkmcnt(0)
	v_mfma_f32_16x16x32_bf16 v[64:67], v[146:149], v[162:165], v[64:67]
	v_mfma_f32_16x16x32_bf16 v[60:63], v[154:157], v[162:165], v[60:63]
	v_mfma_f32_16x16x32_bf16 v[56:59], v[146:149], v[170:173], v[56:59]
	v_mfma_f32_16x16x32_bf16 v[52:55], v[154:157], v[170:173], v[52:55]
	v_mfma_f32_16x16x32_bf16 v[40:43], v[146:149], v[178:181], v[40:43]
	v_mfma_f32_16x16x32_bf16 v[36:39], v[154:157], v[178:181], v[36:39]
	v_mfma_f32_16x16x32_bf16 v[24:27], v[146:149], v[186:189], v[24:27]
	v_mfma_f32_16x16x32_bf16 v[16:19], v[154:157], v[186:189], v[16:19]
	v_mfma_f32_16x16x32_bf16 v[64:67], v[150:153], v[166:169], v[64:67]
	v_mfma_f32_16x16x32_bf16 v[60:63], v[158:161], v[166:169], v[60:63]
	v_mfma_f32_16x16x32_bf16 v[56:59], v[150:153], v[174:177], v[56:59]
	v_mfma_f32_16x16x32_bf16 v[52:55], v[158:161], v[174:177], v[52:55]
	v_mfma_f32_16x16x32_bf16 v[40:43], v[150:153], v[182:185], v[40:43]
	v_mfma_f32_16x16x32_bf16 v[36:39], v[158:161], v[182:185], v[36:39]
	v_mfma_f32_16x16x32_bf16 v[24:27], v[150:153], v[190:193], v[24:27]
	v_mfma_f32_16x16x32_bf16 v[16:19], v[158:161], v[190:193], v[16:19]
	s_barrier
	s_add_u32 s24, s50, 0x40080
	s_addc_u32 s25, s51, 0
	s_add_i32 s23, s26, s37
	s_mov_b32 m0, s23
	s_nop 0
	global_load_lds_dwordx4 v132, s[24:25]
	s_add_i32 m0, s23, 0x2000
	s_nop 0
	global_load_lds_dwordx4 v136, s[24:25]
	s_waitcnt vmcnt(6)
	s_barrier
	v_mfma_f32_16x16x32_bf16 v[48:51], v[202:205], v[162:165], v[48:51]
	v_mfma_f32_16x16x32_bf16 v[44:47], v[210:213], v[162:165], v[44:47]
	v_mfma_f32_16x16x32_bf16 v[32:35], v[202:205], v[170:173], v[32:35]
	v_mfma_f32_16x16x32_bf16 v[28:31], v[210:213], v[170:173], v[28:31]
	v_mfma_f32_16x16x32_bf16 v[20:23], v[202:205], v[178:181], v[20:23]
	v_mfma_f32_16x16x32_bf16 v[12:15], v[210:213], v[178:181], v[12:15]
	v_mfma_f32_16x16x32_bf16 v[8:11], v[202:205], v[186:189], v[8:11]
	v_mfma_f32_16x16x32_bf16 v[4:7], v[210:213], v[186:189], v[4:7]
	v_mfma_f32_16x16x32_bf16 v[48:51], v[206:209], v[166:169], v[48:51]
	v_mfma_f32_16x16x32_bf16 v[44:47], v[214:217], v[166:169], v[44:47]
	v_mfma_f32_16x16x32_bf16 v[32:35], v[206:209], v[174:177], v[32:35]
	v_mfma_f32_16x16x32_bf16 v[28:31], v[214:217], v[174:177], v[28:31]
	v_mfma_f32_16x16x32_bf16 v[20:23], v[206:209], v[182:185], v[20:23]
	v_mfma_f32_16x16x32_bf16 v[12:15], v[214:217], v[182:185], v[12:15]
	v_mfma_f32_16x16x32_bf16 v[8:11], v[206:209], v[190:193], v[8:11]
	v_mfma_f32_16x16x32_bf16 v[4:7], v[214:217], v[190:193], v[4:7]
	s_add_i32 s22, s22, 2
	s_add_u32 s48, s48, 0x100
	s_addc_u32 s49, s49, 0
	s_add_u32 s20, s20, 0x100
	s_addc_u32 s21, s21, 0
	s_cmp_gt_u32 s22, 13
	s_barrier
	s_cbranch_scc0 .LBB0_136
	v_lshl_add_u32 v146, s0, 8, v142
	v_cvt_pk_bf16_f32 v72, v72, v73
	v_cvt_pk_bf16_f32 v73, v74, v75
	v_cvt_pk_bf16_f32 v74, v68, v69
	v_add_u32_e32 v68, 0x80, v146
	s_lshl_b32 s0, s1, 8
	v_ashrrev_i32_e32 v147, 31, v146
	v_readlane_b32 s20, v252, 12
	v_cvt_pk_bf16_f32 v112, v112, v113
	v_cvt_pk_bf16_f32 v113, v114, v115
	v_cvt_pk_bf16_f32 v114, v108, v109
	v_or_b32_e32 v108, 16, v146
	v_ashrrev_i32_e32 v69, 31, v68
	v_cvt_pk_bf16_f32 v48, v48, v49
	v_cvt_pk_bf16_f32 v49, v50, v51
	v_cvt_pk_bf16_f32 v50, v44, v45
	v_add_u32_e32 v44, 0x90, v146
	s_ashr_i32 s1, s0, 31
	v_lshlrev_b64 v[148:149], 11, v[146:147]
	v_readlane_b32 s21, v252, 13
	v_ashrrev_i32_e32 v109, 31, v108
	v_cvt_pk_bf16_f32 v96, v96, v97
	v_cvt_pk_bf16_f32 v97, v98, v99
	v_cvt_pk_bf16_f32 v98, v92, v93
	v_or_b32_e32 v92, 32, v146
	v_lshlrev_b64 v[68:69], 11, v[68:69]
	v_ashrrev_i32_e32 v45, 31, v44
	v_cvt_pk_bf16_f32 v32, v32, v33
	v_cvt_pk_bf16_f32 v33, v34, v35
	v_cvt_pk_bf16_f32 v34, v28, v29
	v_add_u32_e32 v28, 0xa0, v146
	v_lshl_add_u64 v[148:149], s[20:21], 0, v[148:149]
	s_lshl_b64 s[0:1], s[0:1], 1
	v_lshlrev_b64 v[108:109], 11, v[108:109]
	v_ashrrev_i32_e32 v93, 31, v92
	v_cvt_pk_bf16_f32 v80, v80, v81
	v_cvt_pk_bf16_f32 v81, v82, v83
	v_cvt_pk_bf16_f32 v82, v76, v77
	v_or_b32_e32 v76, 48, v146
	v_lshl_add_u64 v[68:69], s[20:21], 0, v[68:69]
	v_lshlrev_b64 v[44:45], 11, v[44:45]
	v_ashrrev_i32_e32 v29, 31, v28
	v_cvt_pk_bf16_f32 v20, v20, v21
	v_cvt_pk_bf16_f32 v21, v22, v23
	v_cvt_pk_bf16_f32 v22, v12, v13
	v_add_u32_e32 v12, 0xb0, v146
	v_lshl_add_u64 v[148:149], v[148:149], 0, s[0:1]
	v_lshl_add_u64 v[108:109], s[20:21], 0, v[108:109]
	v_lshlrev_b64 v[92:93], 11, v[92:93]
	v_ashrrev_i32_e32 v77, 31, v76
	v_lshl_add_u64 v[68:69], v[68:69], 0, s[0:1]
	v_lshl_add_u64 v[44:45], s[20:21], 0, v[44:45]
	v_lshlrev_b64 v[28:29], 11, v[28:29]
	v_ashrrev_i32_e32 v13, 31, v12
	v_lshl_add_u64 v[148:149], v[148:149], 0, s[72:73]
	v_lshl_add_u64 v[108:109], v[108:109], 0, s[0:1]
	v_lshl_add_u64 v[92:93], s[20:21], 0, v[92:93]
	v_lshlrev_b64 v[76:77], 11, v[76:77]
	v_lshl_add_u64 v[68:69], v[68:69], 0, s[72:73]
	v_lshl_add_u64 v[44:45], v[44:45], 0, s[0:1]
	v_lshl_add_u64 v[28:29], s[20:21], 0, v[28:29]
	v_lshlrev_b64 v[12:13], 11, v[12:13]
	v_lshl_add_u64 v[148:149], v[148:149], 0, v[2:3]
	v_cvt_pk_bf16_f32 v115, v110, v111
	v_lshl_add_u64 v[108:109], v[108:109], 0, s[72:73]
	v_lshl_add_u64 v[92:93], v[92:93], 0, s[0:1]
	v_lshl_add_u64 v[76:77], s[20:21], 0, v[76:77]
	v_lshl_add_u64 v[68:69], v[68:69], 0, v[2:3]
	v_cvt_pk_bf16_f32 v51, v46, v47
	v_lshl_add_u64 v[44:45], v[44:45], 0, s[72:73]
	v_lshl_add_u64 v[28:29], v[28:29], 0, s[0:1]
	v_lshl_add_u64 v[12:13], s[20:21], 0, v[12:13]
	global_store_dwordx4 v[148:149], v[112:115], off offset:256
	v_cvt_pk_bf16_f32 v99, v94, v95
	v_lshl_add_u64 v[92:93], v[92:93], 0, s[72:73]
	v_lshl_add_u64 v[112:113], v[108:109], 0, v[2:3]
	v_lshl_add_u64 v[76:77], v[76:77], 0, s[0:1]
	global_store_dwordx4 v[68:69], v[48:51], off offset:256
	v_cvt_pk_bf16_f32 v35, v30, v31
	v_lshl_add_u64 v[28:29], v[28:29], 0, s[72:73]
	v_lshl_add_u64 v[48:49], v[44:45], 0, v[2:3]
	v_lshl_add_u64 v[12:13], v[12:13], 0, s[0:1]
	global_store_dwordx4 v[112:113], v[96:99], off offset:256
	v_cvt_pk_bf16_f32 v83, v78, v79
	v_lshl_add_u64 v[76:77], v[76:77], 0, s[72:73]
	v_lshl_add_u64 v[96:97], v[92:93], 0, v[2:3]
	global_store_dwordx4 v[48:49], v[32:35], off offset:256
	v_cvt_pk_bf16_f32 v23, v14, v15
	v_lshl_add_u64 v[12:13], v[12:13], 0, s[72:73]
	v_lshl_add_u64 v[32:33], v[28:29], 0, v[2:3]
	v_cvt_pk_bf16_f32 v128, v128, v129
	v_cvt_pk_bf16_f32 v129, v130, v131
	v_cvt_pk_bf16_f32 v130, v124, v125
	v_cvt_pk_bf16_f32 v131, v126, v127
	v_cvt_pk_bf16_f32 v108, v120, v121
	v_cvt_pk_bf16_f32 v109, v122, v123
	v_cvt_pk_bf16_f32 v110, v116, v117
	v_cvt_pk_bf16_f32 v111, v118, v119
	v_cvt_pk_bf16_f32 v92, v104, v105
	v_cvt_pk_bf16_f32 v93, v106, v107
	v_cvt_pk_bf16_f32 v94, v100, v101
	v_cvt_pk_bf16_f32 v95, v102, v103
	global_store_dwordx4 v[96:97], v[80:83], off offset:256
	v_cvt_pk_bf16_f32 v78, v84, v85
	v_cvt_pk_bf16_f32 v79, v86, v87
	v_lshl_add_u64 v[80:81], v[76:77], 0, v[2:3]
	v_cvt_pk_bf16_f32 v76, v88, v89
	v_cvt_pk_bf16_f32 v77, v90, v91
	v_cvt_pk_bf16_f32 v75, v70, v71
	v_cvt_pk_bf16_f32 v64, v64, v65
	v_cvt_pk_bf16_f32 v65, v66, v67
	v_cvt_pk_bf16_f32 v66, v60, v61
	v_cvt_pk_bf16_f32 v67, v62, v63
	v_cvt_pk_bf16_f32 v44, v56, v57
	v_cvt_pk_bf16_f32 v45, v58, v59
	v_cvt_pk_bf16_f32 v46, v52, v53
	v_cvt_pk_bf16_f32 v47, v54, v55
	v_cvt_pk_bf16_f32 v28, v40, v41
	v_cvt_pk_bf16_f32 v29, v42, v43
	v_cvt_pk_bf16_f32 v30, v36, v37
	v_cvt_pk_bf16_f32 v31, v38, v39
	global_store_dwordx4 v[32:33], v[20:23], off offset:256
	v_cvt_pk_bf16_f32 v14, v16, v17
	v_cvt_pk_bf16_f32 v15, v18, v19
	v_lshl_add_u64 v[20:21], v[12:13], 0, v[2:3]
	v_cvt_pk_bf16_f32 v12, v24, v25
	v_cvt_pk_bf16_f32 v13, v26, v27
	v_cvt_pk_bf16_f32 v8, v8, v9
	v_cvt_pk_bf16_f32 v9, v10, v11
	v_cvt_pk_bf16_f32 v10, v4, v5
	v_cvt_pk_bf16_f32 v11, v6, v7
	s_and_b64 vcc, exec, s[38:39]
	s_mov_b32 s1, s40
	s_mov_b32 s0, s42
	s_mov_b64 s[50:51], s[46:47]
	s_mov_b64 s[48:49], s[44:45]
	global_store_dwordx4 v[148:149], v[128:131], off
	global_store_dwordx4 v[112:113], v[108:111], off
	global_store_dwordx4 v[96:97], v[92:95], off
	global_store_dwordx4 v[80:81], v[76:79], off
	global_store_dwordx4 v[80:81], v[72:75], off offset:256
	global_store_dwordx4 v[68:69], v[64:67], off
	global_store_dwordx4 v[48:49], v[44:47], off
	global_store_dwordx4 v[32:33], v[28:31], off
	global_store_dwordx4 v[20:21], v[12:15], off
	global_store_dwordx4 v[20:21], v[8:11], off offset:256
	s_cbranch_vccz .LBB0_129
	s_waitcnt vmcnt(0)
	s_cmpk_gt_u32 s31, 0xff
	s_cbranch_scc1 .LBB0_140
	s_barrier

.LBB0_175:
	s_add_i32 s26, s27, 2
	s_add_u32 s44, s40, 0x100
	s_addc_u32 s45, s41, 0
	s_add_i32 s30, 0, 0x10000
	v_add_u32_e32 v0, s30, v157
	ds_read_b128 v[132:135], v0
	ds_read_b128 v[164:167], v0 offset:1024
	ds_read_b128 v[168:171], v0 offset:2048
	ds_read_b128 v[174:177], v0 offset:3072
	s_cmp_eq_u32 s23, s27
	s_cselect_b32 s49, s1, s45
	s_cselect_b32 s48, s0, s44
	s_cselect_b32 s47, s43, s25
	s_cselect_b32 s46, s42, s24
	s_add_i32 m0, s53, 0xc000
	ds_read_b128 v[178:181], v172
	ds_read_b128 v[182:185], v172 offset:1024
	ds_read_b128 v[186:189], v172 offset:2048
	ds_read_b128 v[190:193], v172 offset:3072
	ds_read_b128 v[202:205], v172 offset:4096
	ds_read_b128 v[206:209], v172 offset:5120
	ds_read_b128 v[210:213], v172 offset:6144
	ds_read_b128 v[214:217], v172 offset:7168
	global_load_lds_dwordx4 v160, s[40:41]
	s_add_i32 m0, s53, 0xe000
	s_nop 0
	global_load_lds_dwordx4 v162, s[40:41]
	s_waitcnt lgkmcnt(8)
	s_barrier
	s_waitcnt lgkmcnt(0)
	v_mfma_f32_16x16x32_bf16 v[4:7], v[132:135], v[178:181], v[4:7]
	v_mfma_f32_16x16x32_bf16 v[8:11], v[168:171], v[178:181], v[8:11]
	v_mfma_f32_16x16x32_bf16 v[128:131], v[132:135], v[186:189], v[128:131]
	v_mfma_f32_16x16x32_bf16 v[124:127], v[168:171], v[186:189], v[124:127]
	v_mfma_f32_16x16x32_bf16 v[120:123], v[132:135], v[202:205], v[120:123]
	v_mfma_f32_16x16x32_bf16 v[116:119], v[168:171], v[202:205], v[116:119]
	v_mfma_f32_16x16x32_bf16 v[112:115], v[132:135], v[210:213], v[112:115]
	v_mfma_f32_16x16x32_bf16 v[108:111], v[168:171], v[210:213], v[108:111]
	v_mfma_f32_16x16x32_bf16 v[4:7], v[164:167], v[182:185], v[4:7]
	v_mfma_f32_16x16x32_bf16 v[8:11], v[174:177], v[182:185], v[8:11]
	v_mfma_f32_16x16x32_bf16 v[128:131], v[164:167], v[190:193], v[128:131]
	v_mfma_f32_16x16x32_bf16 v[124:127], v[174:177], v[190:193], v[124:127]
	v_mfma_f32_16x16x32_bf16 v[120:123], v[164:167], v[206:209], v[120:123]
	v_mfma_f32_16x16x32_bf16 v[116:119], v[174:177], v[206:209], v[116:119]
	v_mfma_f32_16x16x32_bf16 v[112:115], v[164:167], v[214:217], v[112:115]
	v_mfma_f32_16x16x32_bf16 v[108:111], v[174:177], v[214:217], v[108:111]
	s_barrier
	s_add_i32 s27, 0, 0x14000
	v_add_u32_e32 v0, s27, v157
	s_add_i32 s30, s30, s52
	ds_read_b128 v[236:239], v0
	ds_read_b128 v[240:243], v0 offset:1024
	ds_read_b128 v[244:247], v0 offset:2048
	ds_read_b128 v[248:251], v0 offset:3072
	s_mov_b32 m0, s30
	s_nop 0
	global_load_lds_dwordx4 v138, s[46:47]
	s_add_i32 m0, s30, 0x2000
	s_nop 0
	global_load_lds_dwordx4 v142, s[46:47]
	s_barrier
	s_waitcnt lgkmcnt(0)
	v_mfma_f32_16x16x32_bf16 v[12:15], v[236:239], v[178:181], v[12:15]
	v_mfma_f32_16x16x32_bf16 v[16:19], v[244:247], v[178:181], v[16:19]
	v_mfma_f32_16x16x32_bf16 v[104:107], v[236:239], v[186:189], v[104:107]
	v_mfma_f32_16x16x32_bf16 v[100:103], v[244:247], v[186:189], v[100:103]
	v_mfma_f32_16x16x32_bf16 v[96:99], v[236:239], v[202:205], v[96:99]
	v_mfma_f32_16x16x32_bf16 v[92:95], v[244:247], v[202:205], v[92:95]
	v_mfma_f32_16x16x32_bf16 v[88:91], v[236:239], v[210:213], v[88:91]
	v_mfma_f32_16x16x32_bf16 v[84:87], v[244:247], v[210:213], v[84:87]
	v_mfma_f32_16x16x32_bf16 v[12:15], v[240:243], v[182:185], v[12:15]
	v_mfma_f32_16x16x32_bf16 v[16:19], v[248:251], v[182:185], v[16:19]
	v_mfma_f32_16x16x32_bf16 v[104:107], v[240:243], v[190:193], v[104:107]
	v_mfma_f32_16x16x32_bf16 v[100:103], v[248:251], v[190:193], v[100:103]
	v_mfma_f32_16x16x32_bf16 v[96:99], v[240:243], v[206:209], v[96:99]
	v_mfma_f32_16x16x32_bf16 v[92:95], v[248:251], v[206:209], v[92:95]
	v_mfma_f32_16x16x32_bf16 v[88:91], v[240:243], v[214:217], v[88:91]
	v_mfma_f32_16x16x32_bf16 v[84:87], v[248:251], v[214:217], v[84:87]
	s_mov_b32 m0, s53
	s_barrier
	ds_read_b128 v[178:181], v172 offset:16384
	ds_read_b128 v[182:185], v172 offset:17408
	ds_read_b128 v[186:189], v172 offset:18432
	ds_read_b128 v[190:193], v172 offset:19456
	ds_read_b128 v[202:205], v172 offset:20480
	ds_read_b128 v[206:209], v172 offset:21504
	ds_read_b128 v[210:213], v172 offset:22528
	ds_read_b128 v[214:217], v172 offset:23552
	global_load_lds_dwordx4 v136, s[48:49]
	s_mov_b32 m0, s54
	s_nop 0
	global_load_lds_dwordx4 v140, s[48:49]
	s_barrier
	s_waitcnt lgkmcnt(0)
	v_mfma_f32_16x16x32_bf16 v[80:83], v[132:135], v[178:181], v[80:83]
	v_mfma_f32_16x16x32_bf16 v[76:79], v[168:171], v[178:181], v[76:79]
	v_mfma_f32_16x16x32_bf16 v[72:75], v[132:135], v[186:189], v[72:75]
	v_mfma_f32_16x16x32_bf16 v[68:71], v[168:171], v[186:189], v[68:71]
	v_mfma_f32_16x16x32_bf16 v[64:67], v[132:135], v[202:205], v[64:67]
	v_mfma_f32_16x16x32_bf16 v[60:63], v[168:171], v[202:205], v[60:63]
	v_mfma_f32_16x16x32_bf16 v[56:59], v[132:135], v[210:213], v[56:59]
	v_mfma_f32_16x16x32_bf16 v[52:55], v[168:171], v[210:213], v[52:55]
	v_mfma_f32_16x16x32_bf16 v[80:83], v[164:167], v[182:185], v[80:83]
	v_mfma_f32_16x16x32_bf16 v[76:79], v[174:177], v[182:185], v[76:79]
	v_mfma_f32_16x16x32_bf16 v[72:75], v[164:167], v[190:193], v[72:75]
	v_mfma_f32_16x16x32_bf16 v[68:71], v[174:177], v[190:193], v[68:71]
	v_mfma_f32_16x16x32_bf16 v[64:67], v[164:167], v[206:209], v[64:67]
	v_mfma_f32_16x16x32_bf16 v[60:63], v[174:177], v[206:209], v[60:63]
	v_mfma_f32_16x16x32_bf16 v[56:59], v[164:167], v[214:217], v[56:59]
	v_mfma_f32_16x16x32_bf16 v[52:55], v[174:177], v[214:217], v[52:55]
	s_barrier
	s_add_u32 s30, s46, 0xc0000
	s_addc_u32 s31, s47, 0
	s_add_i32 s27, s27, s52
	s_mov_b32 m0, s27
	s_nop 0
	global_load_lds_dwordx4 v138, s[30:31]
	s_add_i32 m0, s27, 0x2000
	s_nop 0
	global_load_lds_dwordx4 v142, s[30:31]
	s_waitcnt vmcnt(6)
	s_barrier
	v_mfma_f32_16x16x32_bf16 v[48:51], v[236:239], v[178:181], v[48:51]
	v_mfma_f32_16x16x32_bf16 v[44:47], v[244:247], v[178:181], v[44:47]
	v_mfma_f32_16x16x32_bf16 v[40:43], v[236:239], v[186:189], v[40:43]
	v_mfma_f32_16x16x32_bf16 v[36:39], v[244:247], v[186:189], v[36:39]
	v_mfma_f32_16x16x32_bf16 v[32:35], v[236:239], v[202:205], v[32:35]
	v_mfma_f32_16x16x32_bf16 v[28:31], v[244:247], v[202:205], v[28:31]
	v_mfma_f32_16x16x32_bf16 v[24:27], v[236:239], v[210:213], v[24:27]
	v_mfma_f32_16x16x32_bf16 v[20:23], v[244:247], v[210:213], v[20:23]
	v_mfma_f32_16x16x32_bf16 v[48:51], v[240:243], v[182:185], v[48:51]
	v_mfma_f32_16x16x32_bf16 v[44:47], v[248:251], v[182:185], v[44:47]
	v_mfma_f32_16x16x32_bf16 v[40:43], v[240:243], v[190:193], v[40:43]
	v_mfma_f32_16x16x32_bf16 v[36:39], v[248:251], v[190:193], v[36:39]
	v_mfma_f32_16x16x32_bf16 v[32:35], v[240:243], v[206:209], v[32:35]
	v_mfma_f32_16x16x32_bf16 v[28:31], v[248:251], v[206:209], v[28:31]
	v_mfma_f32_16x16x32_bf16 v[24:27], v[240:243], v[214:217], v[24:27]
	v_mfma_f32_16x16x32_bf16 v[20:23], v[248:251], v[214:217], v[20:23]
	s_add_i32 s27, 0, 0x18000
	v_add_u32_e32 v2, s27, v157
	s_barrier
	ds_read_b128 v[132:135], v2
	ds_read_b128 v[164:167], v2 offset:1024
	ds_read_b128 v[168:171], v2 offset:2048
	ds_read_b128 v[174:177], v2 offset:3072
	s_add_u32 s30, s48, 0x1a0000
	s_addc_u32 s31, s49, 0
	s_mov_b32 m0, s55
	ds_read_b128 v[178:181], v172 offset:32768
	ds_read_b128 v[182:185], v172 offset:33792
	ds_read_b128 v[186:189], v172 offset:34816
	ds_read_b128 v[190:193], v172 offset:35840
	ds_read_b128 v[202:205], v172 offset:36864
	ds_read_b128 v[206:209], v172 offset:37888
	ds_read_b128 v[210:213], v172 offset:38912
	ds_read_b128 v[214:217], v172 offset:39936
	global_load_lds_dwordx4 v136, s[30:31]
	s_mov_b32 m0, s56
	s_nop 0
	global_load_lds_dwordx4 v140, s[30:31]
	s_waitcnt lgkmcnt(8)
	s_barrier
	s_waitcnt lgkmcnt(0)
	v_mfma_f32_16x16x32_bf16 v[4:7], v[132:135], v[178:181], v[4:7]
	v_mfma_f32_16x16x32_bf16 v[8:11], v[168:171], v[178:181], v[8:11]
	v_mfma_f32_16x16x32_bf16 v[128:131], v[132:135], v[186:189], v[128:131]
	v_mfma_f32_16x16x32_bf16 v[124:127], v[168:171], v[186:189], v[124:127]
	v_mfma_f32_16x16x32_bf16 v[120:123], v[132:135], v[202:205], v[120:123]
	v_mfma_f32_16x16x32_bf16 v[116:119], v[168:171], v[202:205], v[116:119]
	v_mfma_f32_16x16x32_bf16 v[112:115], v[132:135], v[210:213], v[112:115]
	v_mfma_f32_16x16x32_bf16 v[108:111], v[168:171], v[210:213], v[108:111]
	v_mfma_f32_16x16x32_bf16 v[4:7], v[164:167], v[182:185], v[4:7]
	v_mfma_f32_16x16x32_bf16 v[8:11], v[174:177], v[182:185], v[8:11]
	v_mfma_f32_16x16x32_bf16 v[128:131], v[164:167], v[190:193], v[128:131]
	v_mfma_f32_16x16x32_bf16 v[124:127], v[174:177], v[190:193], v[124:127]
	v_mfma_f32_16x16x32_bf16 v[120:123], v[164:167], v[206:209], v[120:123]
	v_mfma_f32_16x16x32_bf16 v[116:119], v[174:177], v[206:209], v[116:119]
	v_mfma_f32_16x16x32_bf16 v[112:115], v[164:167], v[214:217], v[112:115]
	v_mfma_f32_16x16x32_bf16 v[108:111], v[174:177], v[214:217], v[108:111]
	s_barrier
	s_add_i32 s36, 0, 0x1c000
	s_add_i32 s27, s27, s52
	v_add_u32_e32 v2, s36, v157
	s_mov_b32 m0, s27
	ds_read_b128 v[236:239], v2
	ds_read_b128 v[240:243], v2 offset:1024
	ds_read_b128 v[244:247], v2 offset:2048
	ds_read_b128 v[248:251], v2 offset:3072
	s_add_u32 s98, s46, 0x80
	s_addc_u32 s99, s47, 0
	global_load_lds_dwordx4 v138, s[98:99]
	s_add_i32 m0, s27, 0x2000
	s_nop 0
	global_load_lds_dwordx4 v142, s[98:99]
	s_barrier
	s_waitcnt lgkmcnt(0)
	v_mfma_f32_16x16x32_bf16 v[12:15], v[236:239], v[178:181], v[12:15]
	v_mfma_f32_16x16x32_bf16 v[16:19], v[244:247], v[178:181], v[16:19]
	v_mfma_f32_16x16x32_bf16 v[104:107], v[236:239], v[186:189], v[104:107]
	v_mfma_f32_16x16x32_bf16 v[100:103], v[244:247], v[186:189], v[100:103]
	v_mfma_f32_16x16x32_bf16 v[96:99], v[236:239], v[202:205], v[96:99]
	v_mfma_f32_16x16x32_bf16 v[92:95], v[244:247], v[202:205], v[92:95]
	v_mfma_f32_16x16x32_bf16 v[88:91], v[236:239], v[210:213], v[88:91]
	v_mfma_f32_16x16x32_bf16 v[84:87], v[244:247], v[210:213], v[84:87]
	v_mfma_f32_16x16x32_bf16 v[12:15], v[240:243], v[182:185], v[12:15]
	v_mfma_f32_16x16x32_bf16 v[16:19], v[248:251], v[182:185], v[16:19]
	v_mfma_f32_16x16x32_bf16 v[104:107], v[240:243], v[190:193], v[104:107]
	v_mfma_f32_16x16x32_bf16 v[100:103], v[248:251], v[190:193], v[100:103]
	v_mfma_f32_16x16x32_bf16 v[96:99], v[240:243], v[206:209], v[96:99]
	v_mfma_f32_16x16x32_bf16 v[92:95], v[248:251], v[206:209], v[92:95]
	v_mfma_f32_16x16x32_bf16 v[88:91], v[240:243], v[214:217], v[88:91]
	v_mfma_f32_16x16x32_bf16 v[84:87], v[248:251], v[214:217], v[84:87]
	s_mov_b32 m0, s59
	s_barrier
	ds_read_b128 v[178:181], v172 offset:49152
	ds_read_b128 v[182:185], v172 offset:50176
	ds_read_b128 v[186:189], v172 offset:51200
	ds_read_b128 v[190:193], v172 offset:52224
	ds_read_b128 v[202:205], v172 offset:53248
	ds_read_b128 v[206:209], v172 offset:54272
	ds_read_b128 v[210:213], v172 offset:55296
	ds_read_b128 v[214:217], v172 offset:56320
	s_add_u32 s98, s48, 0x80
	s_addc_u32 s99, s49, 0
	global_load_lds_dwordx4 v136, s[98:99]
	s_mov_b32 m0, s60
	s_nop 0
	global_load_lds_dwordx4 v140, s[98:99]
	s_barrier
	s_waitcnt lgkmcnt(0)
	v_mfma_f32_16x16x32_bf16 v[80:83], v[132:135], v[178:181], v[80:83]
	v_mfma_f32_16x16x32_bf16 v[76:79], v[168:171], v[178:181], v[76:79]
	v_mfma_f32_16x16x32_bf16 v[72:75], v[132:135], v[186:189], v[72:75]
	v_mfma_f32_16x16x32_bf16 v[68:71], v[168:171], v[186:189], v[68:71]
	v_mfma_f32_16x16x32_bf16 v[64:67], v[132:135], v[202:205], v[64:67]
	v_mfma_f32_16x16x32_bf16 v[60:63], v[168:171], v[202:205], v[60:63]
	v_mfma_f32_16x16x32_bf16 v[56:59], v[132:135], v[210:213], v[56:59]
	v_mfma_f32_16x16x32_bf16 v[52:55], v[168:171], v[210:213], v[52:55]
	v_mfma_f32_16x16x32_bf16 v[80:83], v[164:167], v[182:185], v[80:83]
	v_mfma_f32_16x16x32_bf16 v[76:79], v[174:177], v[182:185], v[76:79]
	v_mfma_f32_16x16x32_bf16 v[72:75], v[164:167], v[190:193], v[72:75]
	v_mfma_f32_16x16x32_bf16 v[68:71], v[174:177], v[190:193], v[68:71]
	v_mfma_f32_16x16x32_bf16 v[64:67], v[164:167], v[206:209], v[64:67]
	v_mfma_f32_16x16x32_bf16 v[60:63], v[174:177], v[206:209], v[60:63]
	v_mfma_f32_16x16x32_bf16 v[56:59], v[164:167], v[214:217], v[56:59]
	v_mfma_f32_16x16x32_bf16 v[52:55], v[174:177], v[214:217], v[52:55]
	s_barrier
	s_add_u32 s30, s46, 0xc0080
	s_addc_u32 s31, s47, 0
	s_add_i32 s27, s36, s52
	s_mov_b32 m0, s27
	s_nop 0
	global_load_lds_dwordx4 v138, s[30:31]
	s_add_i32 m0, s27, 0x2000
	s_nop 0
	global_load_lds_dwordx4 v142, s[30:31]
	s_waitcnt vmcnt(6)
	s_barrier
	v_mfma_f32_16x16x32_bf16 v[48:51], v[236:239], v[178:181], v[48:51]
	v_mfma_f32_16x16x32_bf16 v[44:47], v[244:247], v[178:181], v[44:47]
	v_mfma_f32_16x16x32_bf16 v[40:43], v[236:239], v[186:189], v[40:43]
	v_mfma_f32_16x16x32_bf16 v[36:39], v[244:247], v[186:189], v[36:39]
	v_mfma_f32_16x16x32_bf16 v[32:35], v[236:239], v[202:205], v[32:35]
	v_mfma_f32_16x16x32_bf16 v[28:31], v[244:247], v[202:205], v[28:31]
	v_mfma_f32_16x16x32_bf16 v[24:27], v[236:239], v[210:213], v[24:27]
	v_mfma_f32_16x16x32_bf16 v[20:23], v[244:247], v[210:213], v[20:23]
	v_mfma_f32_16x16x32_bf16 v[48:51], v[240:243], v[182:185], v[48:51]
	v_mfma_f32_16x16x32_bf16 v[44:47], v[248:251], v[182:185], v[44:47]
	v_mfma_f32_16x16x32_bf16 v[40:43], v[240:243], v[190:193], v[40:43]
	v_mfma_f32_16x16x32_bf16 v[36:39], v[248:251], v[190:193], v[36:39]
	v_mfma_f32_16x16x32_bf16 v[32:35], v[240:243], v[206:209], v[32:35]
	v_mfma_f32_16x16x32_bf16 v[28:31], v[248:251], v[206:209], v[28:31]
	v_mfma_f32_16x16x32_bf16 v[24:27], v[240:243], v[214:217], v[24:27]
	v_mfma_f32_16x16x32_bf16 v[20:23], v[248:251], v[214:217], v[20:23]
	s_add_u32 s24, s24, 0x100
	s_addc_u32 s25, s25, 0
	s_cmp_ge_i32 s26, s22
	s_mov_b64 s[40:41], s[44:45]
	s_mov_b32 s27, s26
	s_barrier
	s_cbranch_scc0 .LBB0_175
	s_lshl_b32 s46, s66, 8
	v_lshl_or_b32 v0, s20, 8, v159
	s_mov_b32 s44, 0xbfb8aa3b
	s_mov_b32 s45, 0xbfb8aa3b
	v_lshlrev_b32_e32 v0, 1, v0
	v_add_u32_e32 v0, 0x1000, v0
	s_cmp_lg_u32 s21, 1
	s_cbranch_scc0 .Lg2_kind1
	v_readlane_b32 s22, v252, 34
	v_readlane_b32 s23, v252, 35
	v_add_u32_e32 v2, s46, v144
	v_mad_u32_u24 v2, v2, s29, v0
	global_load_dwordx4 v[132:135], v2, s[96:97] offset:2048
	v_add_u32_e32 v2, s46, v144
	v_mad_u32_u24 v2, v2, s29, v0
	global_load_dwordx4 v[178:181], v2, s[96:97] offset:2304
	v_add_u32_e32 v2, s46, v146
	v_mad_u32_u24 v2, v2, s29, v0
	global_load_dwordx4 v[182:185], v2, s[96:97] offset:2048
	v_add_u32_e32 v2, s46, v146
	v_mad_u32_u24 v2, v2, s29, v0
	global_load_dwordx4 v[186:189], v2, s[96:97] offset:2304
	v_add_u32_e32 v2, s46, v148
	v_mad_u32_u24 v2, v2, s29, v0
	global_load_dwordx4 v[190:193], v2, s[96:97] offset:2048
	v_add_u32_e32 v2, s46, v148
	v_mad_u32_u24 v2, v2, s29, v0
	global_load_dwordx4 v[202:205], v2, s[96:97] offset:2304
	v_add_u32_e32 v2, s46, v150
	v_mad_u32_u24 v2, v2, s29, v0
	global_load_dwordx4 v[206:209], v2, s[96:97] offset:2048
	v_add_u32_e32 v2, s46, v150
	v_mad_u32_u24 v2, v2, s29, v0
	global_load_dwordx4 v[210:213], v2, s[96:97] offset:2304
	v_add_u32_e32 v2, s46, v152
	v_mad_u32_u24 v2, v2, s29, v0
	global_load_dwordx4 v[214:217], v2, s[96:97] offset:2048
	v_add_u32_e32 v2, s46, v152
	v_mad_u32_u24 v2, v2, s29, v0
	global_load_dwordx4 v[236:239], v2, s[96:97] offset:2304
	v_add_u32_e32 v2, s46, v154
	v_mad_u32_u24 v2, v2, s29, v0
	global_load_dwordx4 v[240:243], v2, s[96:97] offset:2048
	v_add_u32_e32 v2, s46, v154
	v_mad_u32_u24 v2, v2, s29, v0
	global_load_dwordx4 v[244:247], v2, s[96:97] offset:2304
	v_add_u32_e32 v2, s46, v156
	v_mad_u32_u24 v2, v2, s29, v0
	global_load_dwordx4 v[248:251], v2, s[96:97] offset:2048
	s_waitcnt vmcnt(12)
	v_lshlrev_b32_e32 v164, 16, v132
	v_and_b32_e32 v165, 0xffff0000, v132
	v_lshlrev_b32_e32 v166, 16, v133
	v_and_b32_e32 v167, 0xffff0000, v133
	v_lshlrev_b32_e32 v168, 16, v134
	v_and_b32_e32 v169, 0xffff0000, v134
	v_lshlrev_b32_e32 v170, 16, v135
	v_and_b32_e32 v171, 0xffff0000, v135
	v_add_u32_e32 v2, s46, v156
	v_mad_u32_u24 v2, v2, s29, v0
	global_load_dwordx4 v[132:135], v2, s[96:97] offset:2304
	v_add_u32_e32 v1, s46, v144
	v_lshl_add_u32 v1, v1, 11, v0
	v_med3_f32 v164, v164, s34, v227
	v_med3_f32 v165, v165, s34, v227
	v_med3_f32 v166, v166, s34, v227
	v_med3_f32 v167, v167, s34, v227
	v_med3_f32 v168, v168, s34, v227
	v_med3_f32 v169, v169, s34, v227
	v_med3_f32 v170, v170, s34, v227
	v_med3_f32 v171, v171, s34, v227
	v_pk_mul_f32 v[164:165], v[164:165], s[44:45]
	v_pk_mul_f32 v[166:167], v[166:167], s[44:45]
	v_pk_mul_f32 v[168:169], v[168:169], s[44:45]
	v_pk_mul_f32 v[170:171], v[170:171], s[44:45]
	v_exp_f32_e32 v164, v164
	v_exp_f32_e32 v165, v165
	v_exp_f32_e32 v166, v166
	v_exp_f32_e32 v167, v167
	v_exp_f32_e32 v168, v168
	v_exp_f32_e32 v169, v169
	v_exp_f32_e32 v170, v170
	v_exp_f32_e32 v171, v171
	v_pk_add_f32 v[164:165], v[164:165], 1.0 op_sel_hi:[1,0]
	v_pk_add_f32 v[166:167], v[166:167], 1.0 op_sel_hi:[1,0]
	v_pk_add_f32 v[168:169], v[168:169], 1.0 op_sel_hi:[1,0]
	v_pk_add_f32 v[170:171], v[170:171], 1.0 op_sel_hi:[1,0]
	v_rcp_f32_e32 v164, v164
	v_rcp_f32_e32 v165, v165
	v_rcp_f32_e32 v166, v166
	v_rcp_f32_e32 v167, v167
	v_rcp_f32_e32 v168, v168
	v_rcp_f32_e32 v169, v169
	v_rcp_f32_e32 v170, v170
	v_rcp_f32_e32 v171, v171
	v_pk_mul_f32 v[164:165], v[4:5], v[164:165]
	v_pk_mul_f32 v[166:167], v[6:7], v[166:167]
	v_pk_mul_f32 v[168:169], v[8:9], v[168:169]
	v_pk_mul_f32 v[170:171], v[10:11], v[170:171]
	v_cvt_pk_bf16_f32 v174, v164, v165
	v_cvt_pk_bf16_f32 v175, v166, v167
	v_cvt_pk_bf16_f32 v176, v168, v169
	v_cvt_pk_bf16_f32 v177, v170, v171
	global_store_dwordx4 v1, v[174:177], s[22:23] offset:-4096
	s_waitcnt vmcnt(13)
	v_lshlrev_b32_e32 v164, 16, v178
	v_and_b32_e32 v165, 0xffff0000, v178
	v_lshlrev_b32_e32 v166, 16, v179
	v_and_b32_e32 v167, 0xffff0000, v179
	v_lshlrev_b32_e32 v168, 16, v180
	v_and_b32_e32 v169, 0xffff0000, v180
	v_lshlrev_b32_e32 v170, 16, v181
	v_and_b32_e32 v171, 0xffff0000, v181
	v_add_u32_e32 v2, s46, v158
	v_mad_u32_u24 v2, v2, s29, v0
	global_load_dwordx4 v[178:181], v2, s[96:97] offset:2048
	v_med3_f32 v164, v164, s34, v227
	v_med3_f32 v165, v165, s34, v227
	v_med3_f32 v166, v166, s34, v227
	v_med3_f32 v167, v167, s34, v227
	v_med3_f32 v168, v168, s34, v227
	v_med3_f32 v169, v169, s34, v227
	v_med3_f32 v170, v170, s34, v227
	v_med3_f32 v171, v171, s34, v227
	v_pk_mul_f32 v[164:165], v[164:165], s[44:45]
	v_pk_mul_f32 v[166:167], v[166:167], s[44:45]
	v_pk_mul_f32 v[168:169], v[168:169], s[44:45]
	v_pk_mul_f32 v[170:171], v[170:171], s[44:45]
	v_exp_f32_e32 v164, v164
	v_exp_f32_e32 v165, v165
	v_exp_f32_e32 v166, v166
	v_exp_f32_e32 v167, v167
	v_exp_f32_e32 v168, v168
	v_exp_f32_e32 v169, v169
	v_exp_f32_e32 v170, v170
	v_exp_f32_e32 v171, v171
	v_pk_add_f32 v[164:165], v[164:165], 1.0 op_sel_hi:[1,0]
	v_pk_add_f32 v[166:167], v[166:167], 1.0 op_sel_hi:[1,0]
	v_pk_add_f32 v[168:169], v[168:169], 1.0 op_sel_hi:[1,0]
	v_pk_add_f32 v[170:171], v[170:171], 1.0 op_sel_hi:[1,0]
	v_rcp_f32_e32 v164, v164
	v_rcp_f32_e32 v165, v165
	v_rcp_f32_e32 v166, v166
	v_rcp_f32_e32 v167, v167
	v_rcp_f32_e32 v168, v168
	v_rcp_f32_e32 v169, v169
	v_rcp_f32_e32 v170, v170
	v_rcp_f32_e32 v171, v171
	v_pk_mul_f32 v[164:165], v[12:13], v[164:165]
	v_pk_mul_f32 v[166:167], v[14:15], v[166:167]
	v_pk_mul_f32 v[168:169], v[16:17], v[168:169]
	v_pk_mul_f32 v[170:171], v[18:19], v[170:171]
	v_cvt_pk_bf16_f32 v174, v164, v165
	v_cvt_pk_bf16_f32 v175, v166, v167
	v_cvt_pk_bf16_f32 v176, v168, v169
	v_cvt_pk_bf16_f32 v177, v170, v171
	global_store_dwordx4 v1, v[174:177], s[22:23] offset:-3840
	s_waitcnt vmcnt(14)
	v_lshlrev_b32_e32 v164, 16, v182
	v_and_b32_e32 v165, 0xffff0000, v182
	v_lshlrev_b32_e32 v166, 16, v183
	v_and_b32_e32 v167, 0xffff0000, v183
	v_lshlrev_b32_e32 v168, 16, v184
	v_and_b32_e32 v169, 0xffff0000, v184
	v_lshlrev_b32_e32 v170, 16, v185
	v_and_b32_e32 v171, 0xffff0000, v185
	v_add_u32_e32 v2, s46, v158
	v_mad_u32_u24 v2, v2, s29, v0
	global_load_dwordx4 v[182:185], v2, s[96:97] offset:2304
	v_add_u32_e32 v1, s46, v146
	v_lshl_add_u32 v1, v1, 11, v0
	v_med3_f32 v164, v164, s34, v227
	v_med3_f32 v165, v165, s34, v227
	v_med3_f32 v166, v166, s34, v227
	v_med3_f32 v167, v167, s34, v227
	v_med3_f32 v168, v168, s34, v227
	v_med3_f32 v169, v169, s34, v227
	v_med3_f32 v170, v170, s34, v227
	v_med3_f32 v171, v171, s34, v227
	v_pk_mul_f32 v[164:165], v[164:165], s[44:45]
	v_pk_mul_f32 v[166:167], v[166:167], s[44:45]
	v_pk_mul_f32 v[168:169], v[168:169], s[44:45]
	v_pk_mul_f32 v[170:171], v[170:171], s[44:45]
	v_exp_f32_e32 v164, v164
	v_exp_f32_e32 v165, v165
	v_exp_f32_e32 v166, v166
	v_exp_f32_e32 v167, v167
	v_exp_f32_e32 v168, v168
	v_exp_f32_e32 v169, v169
	v_exp_f32_e32 v170, v170
	v_exp_f32_e32 v171, v171
	v_pk_add_f32 v[164:165], v[164:165], 1.0 op_sel_hi:[1,0]
	v_pk_add_f32 v[166:167], v[166:167], 1.0 op_sel_hi:[1,0]
	v_pk_add_f32 v[168:169], v[168:169], 1.0 op_sel_hi:[1,0]
	v_pk_add_f32 v[170:171], v[170:171], 1.0 op_sel_hi:[1,0]
	v_rcp_f32_e32 v164, v164
	v_rcp_f32_e32 v165, v165
	v_rcp_f32_e32 v166, v166
	v_rcp_f32_e32 v167, v167
	v_rcp_f32_e32 v168, v168
	v_rcp_f32_e32 v169, v169
	v_rcp_f32_e32 v170, v170
	v_rcp_f32_e32 v171, v171
	v_pk_mul_f32 v[164:165], v[128:129], v[164:165]
	v_pk_mul_f32 v[166:167], v[130:131], v[166:167]
	v_pk_mul_f32 v[168:169], v[124:125], v[168:169]
	v_pk_mul_f32 v[170:171], v[126:127], v[170:171]
	v_cvt_pk_bf16_f32 v174, v164, v165
	v_cvt_pk_bf16_f32 v175, v166, v167
	v_cvt_pk_bf16_f32 v176, v168, v169
	v_cvt_pk_bf16_f32 v177, v170, v171
	global_store_dwordx4 v1, v[174:177], s[22:23] offset:-4096
	s_waitcnt vmcnt(15)
	v_lshlrev_b32_e32 v164, 16, v186
	v_and_b32_e32 v165, 0xffff0000, v186
	v_lshlrev_b32_e32 v166, 16, v187
	v_and_b32_e32 v167, 0xffff0000, v187
	v_lshlrev_b32_e32 v168, 16, v188
	v_and_b32_e32 v169, 0xffff0000, v188
	v_lshlrev_b32_e32 v170, 16, v189
	v_and_b32_e32 v171, 0xffff0000, v189
	v_med3_f32 v164, v164, s34, v227
	v_med3_f32 v165, v165, s34, v227
	v_med3_f32 v166, v166, s34, v227
	v_med3_f32 v167, v167, s34, v227
	v_med3_f32 v168, v168, s34, v227
	v_med3_f32 v169, v169, s34, v227
	v_med3_f32 v170, v170, s34, v227
	v_med3_f32 v171, v171, s34, v227
	v_pk_mul_f32 v[164:165], v[164:165], s[44:45]
	v_pk_mul_f32 v[166:167], v[166:167], s[44:45]
	v_pk_mul_f32 v[168:169], v[168:169], s[44:45]
	v_pk_mul_f32 v[170:171], v[170:171], s[44:45]
	v_exp_f32_e32 v164, v164
	v_exp_f32_e32 v165, v165
	v_exp_f32_e32 v166, v166
	v_exp_f32_e32 v167, v167
	v_exp_f32_e32 v168, v168
	v_exp_f32_e32 v169, v169
	v_exp_f32_e32 v170, v170
	v_exp_f32_e32 v171, v171
	v_pk_add_f32 v[164:165], v[164:165], 1.0 op_sel_hi:[1,0]
	v_pk_add_f32 v[166:167], v[166:167], 1.0 op_sel_hi:[1,0]
	v_pk_add_f32 v[168:169], v[168:169], 1.0 op_sel_hi:[1,0]
	v_pk_add_f32 v[170:171], v[170:171], 1.0 op_sel_hi:[1,0]
	v_rcp_f32_e32 v164, v164
	v_rcp_f32_e32 v165, v165
	v_rcp_f32_e32 v166, v166
	v_rcp_f32_e32 v167, v167
	v_rcp_f32_e32 v168, v168
	v_rcp_f32_e32 v169, v169
	v_rcp_f32_e32 v170, v170
	v_rcp_f32_e32 v171, v171
	v_pk_mul_f32 v[164:165], v[104:105], v[164:165]
	v_pk_mul_f32 v[166:167], v[106:107], v[166:167]
	v_pk_mul_f32 v[168:169], v[100:101], v[168:169]
	v_pk_mul_f32 v[170:171], v[102:103], v[170:171]
	v_cvt_pk_bf16_f32 v174, v164, v165
	v_cvt_pk_bf16_f32 v175, v166, v167
	v_cvt_pk_bf16_f32 v176, v168, v169
	v_cvt_pk_bf16_f32 v177, v170, v171
	global_store_dwordx4 v1, v[174:177], s[22:23] offset:-3840
	s_waitcnt vmcnt(15)
	v_lshlrev_b32_e32 v164, 16, v190
	v_and_b32_e32 v165, 0xffff0000, v190
	v_lshlrev_b32_e32 v166, 16, v191
	v_and_b32_e32 v167, 0xffff0000, v191
	v_lshlrev_b32_e32 v168, 16, v192
	v_and_b32_e32 v169, 0xffff0000, v192
	v_lshlrev_b32_e32 v170, 16, v193
	v_and_b32_e32 v171, 0xffff0000, v193
	v_add_u32_e32 v1, s46, v148
	v_lshl_add_u32 v1, v1, 11, v0
	v_med3_f32 v164, v164, s34, v227
	v_med3_f32 v165, v165, s34, v227
	v_med3_f32 v166, v166, s34, v227
	v_med3_f32 v167, v167, s34, v227
	v_med3_f32 v168, v168, s34, v227
	v_med3_f32 v169, v169, s34, v227
	v_med3_f32 v170, v170, s34, v227
	v_med3_f32 v171, v171, s34, v227
	v_pk_mul_f32 v[164:165], v[164:165], s[44:45]
	v_pk_mul_f32 v[166:167], v[166:167], s[44:45]
	v_pk_mul_f32 v[168:169], v[168:169], s[44:45]
	v_pk_mul_f32 v[170:171], v[170:171], s[44:45]
	v_exp_f32_e32 v164, v164
	v_exp_f32_e32 v165, v165
	v_exp_f32_e32 v166, v166
	v_exp_f32_e32 v167, v167
	v_exp_f32_e32 v168, v168
	v_exp_f32_e32 v169, v169
	v_exp_f32_e32 v170, v170
	v_exp_f32_e32 v171, v171
	v_pk_add_f32 v[164:165], v[164:165], 1.0 op_sel_hi:[1,0]
	v_pk_add_f32 v[166:167], v[166:167], 1.0 op_sel_hi:[1,0]
	v_pk_add_f32 v[168:169], v[168:169], 1.0 op_sel_hi:[1,0]
	v_pk_add_f32 v[170:171], v[170:171], 1.0 op_sel_hi:[1,0]
	v_rcp_f32_e32 v164, v164
	v_rcp_f32_e32 v165, v165
	v_rcp_f32_e32 v166, v166
	v_rcp_f32_e32 v167, v167
	v_rcp_f32_e32 v168, v168
	v_rcp_f32_e32 v169, v169
	v_rcp_f32_e32 v170, v170
	v_rcp_f32_e32 v171, v171
	v_pk_mul_f32 v[164:165], v[120:121], v[164:165]
	v_pk_mul_f32 v[166:167], v[122:123], v[166:167]
	v_pk_mul_f32 v[168:169], v[116:117], v[168:169]
	v_pk_mul_f32 v[170:171], v[118:119], v[170:171]
	v_cvt_pk_bf16_f32 v174, v164, v165
	v_cvt_pk_bf16_f32 v175, v166, v167
	v_cvt_pk_bf16_f32 v176, v168, v169
	v_cvt_pk_bf16_f32 v177, v170, v171
	global_store_dwordx4 v1, v[174:177], s[22:23] offset:-4096
	s_waitcnt vmcnt(15)
	v_lshlrev_b32_e32 v164, 16, v202
	v_and_b32_e32 v165, 0xffff0000, v202
	v_lshlrev_b32_e32 v166, 16, v203
	v_and_b32_e32 v167, 0xffff0000, v203
	v_lshlrev_b32_e32 v168, 16, v204
	v_and_b32_e32 v169, 0xffff0000, v204
	v_lshlrev_b32_e32 v170, 16, v205
	v_and_b32_e32 v171, 0xffff0000, v205
	v_med3_f32 v164, v164, s34, v227
	v_med3_f32 v165, v165, s34, v227
	v_med3_f32 v166, v166, s34, v227
	v_med3_f32 v167, v167, s34, v227
	v_med3_f32 v168, v168, s34, v227
	v_med3_f32 v169, v169, s34, v227
	v_med3_f32 v170, v170, s34, v227
	v_med3_f32 v171, v171, s34, v227
	v_pk_mul_f32 v[164:165], v[164:165], s[44:45]
	v_pk_mul_f32 v[166:167], v[166:167], s[44:45]
	v_pk_mul_f32 v[168:169], v[168:169], s[44:45]
	v_pk_mul_f32 v[170:171], v[170:171], s[44:45]
	v_exp_f32_e32 v164, v164
	v_exp_f32_e32 v165, v165
	v_exp_f32_e32 v166, v166
	v_exp_f32_e32 v167, v167
	v_exp_f32_e32 v168, v168
	v_exp_f32_e32 v169, v169
	v_exp_f32_e32 v170, v170
	v_exp_f32_e32 v171, v171
	v_pk_add_f32 v[164:165], v[164:165], 1.0 op_sel_hi:[1,0]
	v_pk_add_f32 v[166:167], v[166:167], 1.0 op_sel_hi:[1,0]
	v_pk_add_f32 v[168:169], v[168:169], 1.0 op_sel_hi:[1,0]
	v_pk_add_f32 v[170:171], v[170:171], 1.0 op_sel_hi:[1,0]
	v_rcp_f32_e32 v164, v164
	v_rcp_f32_e32 v165, v165
	v_rcp_f32_e32 v166, v166
	v_rcp_f32_e32 v167, v167
	v_rcp_f32_e32 v168, v168
	v_rcp_f32_e32 v169, v169
	v_rcp_f32_e32 v170, v170
	v_rcp_f32_e32 v171, v171
	v_pk_mul_f32 v[164:165], v[96:97], v[164:165]
	v_pk_mul_f32 v[166:167], v[98:99], v[166:167]
	v_pk_mul_f32 v[168:169], v[92:93], v[168:169]
	v_pk_mul_f32 v[170:171], v[94:95], v[170:171]
	v_cvt_pk_bf16_f32 v174, v164, v165
	v_cvt_pk_bf16_f32 v175, v166, v167
	v_cvt_pk_bf16_f32 v176, v168, v169
	v_cvt_pk_bf16_f32 v177, v170, v171
	global_store_dwordx4 v1, v[174:177], s[22:23] offset:-3840
	s_waitcnt vmcnt(15)
	v_lshlrev_b32_e32 v164, 16, v206
	v_and_b32_e32 v165, 0xffff0000, v206
	v_lshlrev_b32_e32 v166, 16, v207
	v_and_b32_e32 v167, 0xffff0000, v207
	v_lshlrev_b32_e32 v168, 16, v208
	v_and_b32_e32 v169, 0xffff0000, v208
	v_lshlrev_b32_e32 v170, 16, v209
	v_and_b32_e32 v171, 0xffff0000, v209
	v_add_u32_e32 v1, s46, v150
	v_lshl_add_u32 v1, v1, 11, v0
	v_med3_f32 v164, v164, s34, v227
	v_med3_f32 v165, v165, s34, v227
	v_med3_f32 v166, v166, s34, v227
	v_med3_f32 v167, v167, s34, v227
	v_med3_f32 v168, v168, s34, v227
	v_med3_f32 v169, v169, s34, v227
	v_med3_f32 v170, v170, s34, v227
	v_med3_f32 v171, v171, s34, v227
	v_pk_mul_f32 v[164:165], v[164:165], s[44:45]
	v_pk_mul_f32 v[166:167], v[166:167], s[44:45]
	v_pk_mul_f32 v[168:169], v[168:169], s[44:45]
	v_pk_mul_f32 v[170:171], v[170:171], s[44:45]
	v_exp_f32_e32 v164, v164
	v_exp_f32_e32 v165, v165
	v_exp_f32_e32 v166, v166
	v_exp_f32_e32 v167, v167
	v_exp_f32_e32 v168, v168
	v_exp_f32_e32 v169, v169
	v_exp_f32_e32 v170, v170
	v_exp_f32_e32 v171, v171
	v_pk_add_f32 v[164:165], v[164:165], 1.0 op_sel_hi:[1,0]
	v_pk_add_f32 v[166:167], v[166:167], 1.0 op_sel_hi:[1,0]
	v_pk_add_f32 v[168:169], v[168:169], 1.0 op_sel_hi:[1,0]
	v_pk_add_f32 v[170:171], v[170:171], 1.0 op_sel_hi:[1,0]
	v_rcp_f32_e32 v164, v164
	v_rcp_f32_e32 v165, v165
	v_rcp_f32_e32 v166, v166
	v_rcp_f32_e32 v167, v167
	v_rcp_f32_e32 v168, v168
	v_rcp_f32_e32 v169, v169
	v_rcp_f32_e32 v170, v170
	v_rcp_f32_e32 v171, v171
	v_pk_mul_f32 v[164:165], v[112:113], v[164:165]
	v_pk_mul_f32 v[166:167], v[114:115], v[166:167]
	v_pk_mul_f32 v[168:169], v[108:109], v[168:169]
	v_pk_mul_f32 v[170:171], v[110:111], v[170:171]
	v_cvt_pk_bf16_f32 v174, v164, v165
	v_cvt_pk_bf16_f32 v175, v166, v167
	v_cvt_pk_bf16_f32 v176, v168, v169
	v_cvt_pk_bf16_f32 v177, v170, v171
	global_store_dwordx4 v1, v[174:177], s[22:23] offset:-4096
	s_waitcnt vmcnt(15)
	v_lshlrev_b32_e32 v164, 16, v210
	v_and_b32_e32 v165, 0xffff0000, v210
	v_lshlrev_b32_e32 v166, 16, v211
	v_and_b32_e32 v167, 0xffff0000, v211
	v_lshlrev_b32_e32 v168, 16, v212
	v_and_b32_e32 v169, 0xffff0000, v212
	v_lshlrev_b32_e32 v170, 16, v213
	v_and_b32_e32 v171, 0xffff0000, v213
	v_med3_f32 v164, v164, s34, v227
	v_med3_f32 v165, v165, s34, v227
	v_med3_f32 v166, v166, s34, v227
	v_med3_f32 v167, v167, s34, v227
	v_med3_f32 v168, v168, s34, v227
	v_med3_f32 v169, v169, s34, v227
	v_med3_f32 v170, v170, s34, v227
	v_med3_f32 v171, v171, s34, v227
	v_pk_mul_f32 v[164:165], v[164:165], s[44:45]
	v_pk_mul_f32 v[166:167], v[166:167], s[44:45]
	v_pk_mul_f32 v[168:169], v[168:169], s[44:45]
	v_pk_mul_f32 v[170:171], v[170:171], s[44:45]
	v_exp_f32_e32 v164, v164
	v_exp_f32_e32 v165, v165
	v_exp_f32_e32 v166, v166
	v_exp_f32_e32 v167, v167
	v_exp_f32_e32 v168, v168
	v_exp_f32_e32 v169, v169
	v_exp_f32_e32 v170, v170
	v_exp_f32_e32 v171, v171
	v_pk_add_f32 v[164:165], v[164:165], 1.0 op_sel_hi:[1,0]
	v_pk_add_f32 v[166:167], v[166:167], 1.0 op_sel_hi:[1,0]
	v_pk_add_f32 v[168:169], v[168:169], 1.0 op_sel_hi:[1,0]
	v_pk_add_f32 v[170:171], v[170:171], 1.0 op_sel_hi:[1,0]
	v_rcp_f32_e32 v164, v164
	v_rcp_f32_e32 v165, v165
	v_rcp_f32_e32 v166, v166
	v_rcp_f32_e32 v167, v167
	v_rcp_f32_e32 v168, v168
	v_rcp_f32_e32 v169, v169
	v_rcp_f32_e32 v170, v170
	v_rcp_f32_e32 v171, v171
	v_pk_mul_f32 v[164:165], v[88:89], v[164:165]
	v_pk_mul_f32 v[166:167], v[90:91], v[166:167]
	v_pk_mul_f32 v[168:169], v[84:85], v[168:169]
	v_pk_mul_f32 v[170:171], v[86:87], v[170:171]
	v_cvt_pk_bf16_f32 v174, v164, v165
	v_cvt_pk_bf16_f32 v175, v166, v167
	v_cvt_pk_bf16_f32 v176, v168, v169
	v_cvt_pk_bf16_f32 v177, v170, v171
	global_store_dwordx4 v1, v[174:177], s[22:23] offset:-3840
	s_waitcnt vmcnt(15)
	v_lshlrev_b32_e32 v164, 16, v214
	v_and_b32_e32 v165, 0xffff0000, v214
	v_lshlrev_b32_e32 v166, 16, v215
	v_and_b32_e32 v167, 0xffff0000, v215
	v_lshlrev_b32_e32 v168, 16, v216
	v_and_b32_e32 v169, 0xffff0000, v216
	v_lshlrev_b32_e32 v170, 16, v217
	v_and_b32_e32 v171, 0xffff0000, v217
	v_add_u32_e32 v1, s46, v152
	v_lshl_add_u32 v1, v1, 11, v0
	v_med3_f32 v164, v164, s34, v227
	v_med3_f32 v165, v165, s34, v227
	v_med3_f32 v166, v166, s34, v227
	v_med3_f32 v167, v167, s34, v227
	v_med3_f32 v168, v168, s34, v227
	v_med3_f32 v169, v169, s34, v227
	v_med3_f32 v170, v170, s34, v227
	v_med3_f32 v171, v171, s34, v227
	v_pk_mul_f32 v[164:165], v[164:165], s[44:45]
	v_pk_mul_f32 v[166:167], v[166:167], s[44:45]
	v_pk_mul_f32 v[168:169], v[168:169], s[44:45]
	v_pk_mul_f32 v[170:171], v[170:171], s[44:45]
	v_exp_f32_e32 v164, v164
	v_exp_f32_e32 v165, v165
	v_exp_f32_e32 v166, v166
	v_exp_f32_e32 v167, v167
	v_exp_f32_e32 v168, v168
	v_exp_f32_e32 v169, v169
	v_exp_f32_e32 v170, v170
	v_exp_f32_e32 v171, v171
	v_pk_add_f32 v[164:165], v[164:165], 1.0 op_sel_hi:[1,0]
	v_pk_add_f32 v[166:167], v[166:167], 1.0 op_sel_hi:[1,0]
	v_pk_add_f32 v[168:169], v[168:169], 1.0 op_sel_hi:[1,0]
	v_pk_add_f32 v[170:171], v[170:171], 1.0 op_sel_hi:[1,0]
	v_rcp_f32_e32 v164, v164
	v_rcp_f32_e32 v165, v165
	v_rcp_f32_e32 v166, v166
	v_rcp_f32_e32 v167, v167
	v_rcp_f32_e32 v168, v168
	v_rcp_f32_e32 v169, v169
	v_rcp_f32_e32 v170, v170
	v_rcp_f32_e32 v171, v171
	v_pk_mul_f32 v[164:165], v[80:81], v[164:165]
	v_pk_mul_f32 v[166:167], v[82:83], v[166:167]
	v_pk_mul_f32 v[168:169], v[76:77], v[168:169]
	v_pk_mul_f32 v[170:171], v[78:79], v[170:171]
	v_cvt_pk_bf16_f32 v174, v164, v165
	v_cvt_pk_bf16_f32 v175, v166, v167
	v_cvt_pk_bf16_f32 v176, v168, v169
	v_cvt_pk_bf16_f32 v177, v170, v171
	global_store_dwordx4 v1, v[174:177], s[22:23] offset:-4096
	s_waitcnt vmcnt(15)
	v_lshlrev_b32_e32 v164, 16, v236
	v_and_b32_e32 v165, 0xffff0000, v236
	v_lshlrev_b32_e32 v166, 16, v237
	v_and_b32_e32 v167, 0xffff0000, v237
	v_lshlrev_b32_e32 v168, 16, v238
	v_and_b32_e32 v169, 0xffff0000, v238
	v_lshlrev_b32_e32 v170, 16, v239
	v_and_b32_e32 v171, 0xffff0000, v239
	v_med3_f32 v164, v164, s34, v227
	v_med3_f32 v165, v165, s34, v227
	v_med3_f32 v166, v166, s34, v227
	v_med3_f32 v167, v167, s34, v227
	v_med3_f32 v168, v168, s34, v227
	v_med3_f32 v169, v169, s34, v227
	v_med3_f32 v170, v170, s34, v227
	v_med3_f32 v171, v171, s34, v227
	v_pk_mul_f32 v[164:165], v[164:165], s[44:45]
	v_pk_mul_f32 v[166:167], v[166:167], s[44:45]
	v_pk_mul_f32 v[168:169], v[168:169], s[44:45]
	v_pk_mul_f32 v[170:171], v[170:171], s[44:45]
	v_exp_f32_e32 v164, v164
	v_exp_f32_e32 v165, v165
	v_exp_f32_e32 v166, v166
	v_exp_f32_e32 v167, v167
	v_exp_f32_e32 v168, v168
	v_exp_f32_e32 v169, v169
	v_exp_f32_e32 v170, v170
	v_exp_f32_e32 v171, v171
	v_pk_add_f32 v[164:165], v[164:165], 1.0 op_sel_hi:[1,0]
	v_pk_add_f32 v[166:167], v[166:167], 1.0 op_sel_hi:[1,0]
	v_pk_add_f32 v[168:169], v[168:169], 1.0 op_sel_hi:[1,0]
	v_pk_add_f32 v[170:171], v[170:171], 1.0 op_sel_hi:[1,0]
	v_rcp_f32_e32 v164, v164
	v_rcp_f32_e32 v165, v165
	v_rcp_f32_e32 v166, v166
	v_rcp_f32_e32 v167, v167
	v_rcp_f32_e32 v168, v168
	v_rcp_f32_e32 v169, v169
	v_rcp_f32_e32 v170, v170
	v_rcp_f32_e32 v171, v171
	v_pk_mul_f32 v[164:165], v[48:49], v[164:165]
	v_pk_mul_f32 v[166:167], v[50:51], v[166:167]
	v_pk_mul_f32 v[168:169], v[44:45], v[168:169]
	v_pk_mul_f32 v[170:171], v[46:47], v[170:171]
	v_cvt_pk_bf16_f32 v174, v164, v165
	v_cvt_pk_bf16_f32 v175, v166, v167
	v_cvt_pk_bf16_f32 v176, v168, v169
	v_cvt_pk_bf16_f32 v177, v170, v171
	global_store_dwordx4 v1, v[174:177], s[22:23] offset:-3840
	s_waitcnt vmcnt(15)
	v_lshlrev_b32_e32 v164, 16, v240
	v_and_b32_e32 v165, 0xffff0000, v240
	v_lshlrev_b32_e32 v166, 16, v241
	v_and_b32_e32 v167, 0xffff0000, v241
	v_lshlrev_b32_e32 v168, 16, v242
	v_and_b32_e32 v169, 0xffff0000, v242
	v_lshlrev_b32_e32 v170, 16, v243
	v_and_b32_e32 v171, 0xffff0000, v243
	v_add_u32_e32 v1, s46, v154
	v_lshl_add_u32 v1, v1, 11, v0
	v_med3_f32 v164, v164, s34, v227
	v_med3_f32 v165, v165, s34, v227
	v_med3_f32 v166, v166, s34, v227
	v_med3_f32 v167, v167, s34, v227
	v_med3_f32 v168, v168, s34, v227
	v_med3_f32 v169, v169, s34, v227
	v_med3_f32 v170, v170, s34, v227
	v_med3_f32 v171, v171, s34, v227
	v_pk_mul_f32 v[164:165], v[164:165], s[44:45]
	v_pk_mul_f32 v[166:167], v[166:167], s[44:45]
	v_pk_mul_f32 v[168:169], v[168:169], s[44:45]
	v_pk_mul_f32 v[170:171], v[170:171], s[44:45]
	v_exp_f32_e32 v164, v164
	v_exp_f32_e32 v165, v165
	v_exp_f32_e32 v166, v166
	v_exp_f32_e32 v167, v167
	v_exp_f32_e32 v168, v168
	v_exp_f32_e32 v169, v169
	v_exp_f32_e32 v170, v170
	v_exp_f32_e32 v171, v171
	v_pk_add_f32 v[164:165], v[164:165], 1.0 op_sel_hi:[1,0]
	v_pk_add_f32 v[166:167], v[166:167], 1.0 op_sel_hi:[1,0]
	v_pk_add_f32 v[168:169], v[168:169], 1.0 op_sel_hi:[1,0]
	v_pk_add_f32 v[170:171], v[170:171], 1.0 op_sel_hi:[1,0]
	v_rcp_f32_e32 v164, v164
	v_rcp_f32_e32 v165, v165
	v_rcp_f32_e32 v166, v166
	v_rcp_f32_e32 v167, v167
	v_rcp_f32_e32 v168, v168
	v_rcp_f32_e32 v169, v169
	v_rcp_f32_e32 v170, v170
	v_rcp_f32_e32 v171, v171
	v_pk_mul_f32 v[164:165], v[72:73], v[164:165]
	v_pk_mul_f32 v[166:167], v[74:75], v[166:167]
	v_pk_mul_f32 v[168:169], v[68:69], v[168:169]
	v_pk_mul_f32 v[170:171], v[70:71], v[170:171]
	v_cvt_pk_bf16_f32 v174, v164, v165
	v_cvt_pk_bf16_f32 v175, v166, v167
	v_cvt_pk_bf16_f32 v176, v168, v169
	v_cvt_pk_bf16_f32 v177, v170, v171
	global_store_dwordx4 v1, v[174:177], s[22:23] offset:-4096
	s_waitcnt vmcnt(15)
	v_lshlrev_b32_e32 v164, 16, v244
	v_and_b32_e32 v165, 0xffff0000, v244
	v_lshlrev_b32_e32 v166, 16, v245
	v_and_b32_e32 v167, 0xffff0000, v245
	v_lshlrev_b32_e32 v168, 16, v246
	v_and_b32_e32 v169, 0xffff0000, v246
	v_lshlrev_b32_e32 v170, 16, v247
	v_and_b32_e32 v171, 0xffff0000, v247
	v_med3_f32 v164, v164, s34, v227
	v_med3_f32 v165, v165, s34, v227
	v_med3_f32 v166, v166, s34, v227
	v_med3_f32 v167, v167, s34, v227
	v_med3_f32 v168, v168, s34, v227
	v_med3_f32 v169, v169, s34, v227
	v_med3_f32 v170, v170, s34, v227
	v_med3_f32 v171, v171, s34, v227
	v_pk_mul_f32 v[164:165], v[164:165], s[44:45]
	v_pk_mul_f32 v[166:167], v[166:167], s[44:45]
	v_pk_mul_f32 v[168:169], v[168:169], s[44:45]
	v_pk_mul_f32 v[170:171], v[170:171], s[44:45]
	v_exp_f32_e32 v164, v164
	v_exp_f32_e32 v165, v165
	v_exp_f32_e32 v166, v166
	v_exp_f32_e32 v167, v167
	v_exp_f32_e32 v168, v168
	v_exp_f32_e32 v169, v169
	v_exp_f32_e32 v170, v170
	v_exp_f32_e32 v171, v171
	v_pk_add_f32 v[164:165], v[164:165], 1.0 op_sel_hi:[1,0]
	v_pk_add_f32 v[166:167], v[166:167], 1.0 op_sel_hi:[1,0]
	v_pk_add_f32 v[168:169], v[168:169], 1.0 op_sel_hi:[1,0]
	v_pk_add_f32 v[170:171], v[170:171], 1.0 op_sel_hi:[1,0]
	v_rcp_f32_e32 v164, v164
	v_rcp_f32_e32 v165, v165
	v_rcp_f32_e32 v166, v166
	v_rcp_f32_e32 v167, v167
	v_rcp_f32_e32 v168, v168
	v_rcp_f32_e32 v169, v169
	v_rcp_f32_e32 v170, v170
	v_rcp_f32_e32 v171, v171
	v_pk_mul_f32 v[164:165], v[40:41], v[164:165]
	v_pk_mul_f32 v[166:167], v[42:43], v[166:167]
	v_pk_mul_f32 v[168:169], v[36:37], v[168:169]
	v_pk_mul_f32 v[170:171], v[38:39], v[170:171]
	v_cvt_pk_bf16_f32 v174, v164, v165
	v_cvt_pk_bf16_f32 v175, v166, v167
	v_cvt_pk_bf16_f32 v176, v168, v169
	v_cvt_pk_bf16_f32 v177, v170, v171
	global_store_dwordx4 v1, v[174:177], s[22:23] offset:-3840
	s_waitcnt vmcnt(15)
	v_lshlrev_b32_e32 v164, 16, v248
	v_and_b32_e32 v165, 0xffff0000, v248
	v_lshlrev_b32_e32 v166, 16, v249
	v_and_b32_e32 v167, 0xffff0000, v249
	v_lshlrev_b32_e32 v168, 16, v250
	v_and_b32_e32 v169, 0xffff0000, v250
	v_lshlrev_b32_e32 v170, 16, v251
	v_and_b32_e32 v171, 0xffff0000, v251
	v_add_u32_e32 v1, s46, v156
	v_lshl_add_u32 v1, v1, 11, v0
	v_med3_f32 v164, v164, s34, v227
	v_med3_f32 v165, v165, s34, v227
	v_med3_f32 v166, v166, s34, v227
	v_med3_f32 v167, v167, s34, v227
	v_med3_f32 v168, v168, s34, v227
	v_med3_f32 v169, v169, s34, v227
	v_med3_f32 v170, v170, s34, v227
	v_med3_f32 v171, v171, s34, v227
	v_pk_mul_f32 v[164:165], v[164:165], s[44:45]
	v_pk_mul_f32 v[166:167], v[166:167], s[44:45]
	v_pk_mul_f32 v[168:169], v[168:169], s[44:45]
	v_pk_mul_f32 v[170:171], v[170:171], s[44:45]
	v_exp_f32_e32 v164, v164
	v_exp_f32_e32 v165, v165
	v_exp_f32_e32 v166, v166
	v_exp_f32_e32 v167, v167
	v_exp_f32_e32 v168, v168
	v_exp_f32_e32 v169, v169
	v_exp_f32_e32 v170, v170
	v_exp_f32_e32 v171, v171
	v_pk_add_f32 v[164:165], v[164:165], 1.0 op_sel_hi:[1,0]
	v_pk_add_f32 v[166:167], v[166:167], 1.0 op_sel_hi:[1,0]
	v_pk_add_f32 v[168:169], v[168:169], 1.0 op_sel_hi:[1,0]
	v_pk_add_f32 v[170:171], v[170:171], 1.0 op_sel_hi:[1,0]
	v_rcp_f32_e32 v164, v164
	v_rcp_f32_e32 v165, v165
	v_rcp_f32_e32 v166, v166
	v_rcp_f32_e32 v167, v167
	v_rcp_f32_e32 v168, v168
	v_rcp_f32_e32 v169, v169
	v_rcp_f32_e32 v170, v170
	v_rcp_f32_e32 v171, v171
	v_pk_mul_f32 v[164:165], v[64:65], v[164:165]
	v_pk_mul_f32 v[166:167], v[66:67], v[166:167]
	v_pk_mul_f32 v[168:169], v[60:61], v[168:169]
	v_pk_mul_f32 v[170:171], v[62:63], v[170:171]
	v_cvt_pk_bf16_f32 v174, v164, v165
	v_cvt_pk_bf16_f32 v175, v166, v167
	v_cvt_pk_bf16_f32 v176, v168, v169
	v_cvt_pk_bf16_f32 v177, v170, v171
	global_store_dwordx4 v1, v[174:177], s[22:23] offset:-4096
	s_waitcnt vmcnt(15)
	v_lshlrev_b32_e32 v164, 16, v132
	v_and_b32_e32 v165, 0xffff0000, v132
	v_lshlrev_b32_e32 v166, 16, v133
	v_and_b32_e32 v167, 0xffff0000, v133
	v_lshlrev_b32_e32 v168, 16, v134
	v_and_b32_e32 v169, 0xffff0000, v134
	v_lshlrev_b32_e32 v170, 16, v135
	v_and_b32_e32 v171, 0xffff0000, v135
	v_med3_f32 v164, v164, s34, v227
	v_med3_f32 v165, v165, s34, v227
	v_med3_f32 v166, v166, s34, v227
	v_med3_f32 v167, v167, s34, v227
	v_med3_f32 v168, v168, s34, v227
	v_med3_f32 v169, v169, s34, v227
	v_med3_f32 v170, v170, s34, v227
	v_med3_f32 v171, v171, s34, v227
	v_pk_mul_f32 v[164:165], v[164:165], s[44:45]
	v_pk_mul_f32 v[166:167], v[166:167], s[44:45]
	v_pk_mul_f32 v[168:169], v[168:169], s[44:45]
	v_pk_mul_f32 v[170:171], v[170:171], s[44:45]
	v_exp_f32_e32 v164, v164
	v_exp_f32_e32 v165, v165
	v_exp_f32_e32 v166, v166
	v_exp_f32_e32 v167, v167
	v_exp_f32_e32 v168, v168
	v_exp_f32_e32 v169, v169
	v_exp_f32_e32 v170, v170
	v_exp_f32_e32 v171, v171
	v_pk_add_f32 v[164:165], v[164:165], 1.0 op_sel_hi:[1,0]
	v_pk_add_f32 v[166:167], v[166:167], 1.0 op_sel_hi:[1,0]
	v_pk_add_f32 v[168:169], v[168:169], 1.0 op_sel_hi:[1,0]
	v_pk_add_f32 v[170:171], v[170:171], 1.0 op_sel_hi:[1,0]
	v_rcp_f32_e32 v164, v164
	v_rcp_f32_e32 v165, v165
	v_rcp_f32_e32 v166, v166
	v_rcp_f32_e32 v167, v167
	v_rcp_f32_e32 v168, v168
	v_rcp_f32_e32 v169, v169
	v_rcp_f32_e32 v170, v170
	v_rcp_f32_e32 v171, v171
	v_pk_mul_f32 v[164:165], v[32:33], v[164:165]
	v_pk_mul_f32 v[166:167], v[34:35], v[166:167]
	v_pk_mul_f32 v[168:169], v[28:29], v[168:169]
	v_pk_mul_f32 v[170:171], v[30:31], v[170:171]
	v_cvt_pk_bf16_f32 v174, v164, v165
	v_cvt_pk_bf16_f32 v175, v166, v167
	v_cvt_pk_bf16_f32 v176, v168, v169
	v_cvt_pk_bf16_f32 v177, v170, v171
	global_store_dwordx4 v1, v[174:177], s[22:23] offset:-3840
	s_waitcnt vmcnt(14)
	v_lshlrev_b32_e32 v164, 16, v178
	v_and_b32_e32 v165, 0xffff0000, v178
	v_lshlrev_b32_e32 v166, 16, v179
	v_and_b32_e32 v167, 0xffff0000, v179
	v_lshlrev_b32_e32 v168, 16, v180
	v_and_b32_e32 v169, 0xffff0000, v180
	v_lshlrev_b32_e32 v170, 16, v181
	v_and_b32_e32 v171, 0xffff0000, v181
	v_add_u32_e32 v1, s46, v158
	v_lshl_add_u32 v1, v1, 11, v0
	v_med3_f32 v164, v164, s34, v227
	v_med3_f32 v165, v165, s34, v227
	v_med3_f32 v166, v166, s34, v227
	v_med3_f32 v167, v167, s34, v227
	v_med3_f32 v168, v168, s34, v227
	v_med3_f32 v169, v169, s34, v227
	v_med3_f32 v170, v170, s34, v227
	v_med3_f32 v171, v171, s34, v227
	v_pk_mul_f32 v[164:165], v[164:165], s[44:45]
	v_pk_mul_f32 v[166:167], v[166:167], s[44:45]
	v_pk_mul_f32 v[168:169], v[168:169], s[44:45]
	v_pk_mul_f32 v[170:171], v[170:171], s[44:45]
	v_exp_f32_e32 v164, v164
	v_exp_f32_e32 v165, v165
	v_exp_f32_e32 v166, v166
	v_exp_f32_e32 v167, v167
	v_exp_f32_e32 v168, v168
	v_exp_f32_e32 v169, v169
	v_exp_f32_e32 v170, v170
	v_exp_f32_e32 v171, v171
	v_pk_add_f32 v[164:165], v[164:165], 1.0 op_sel_hi:[1,0]
	v_pk_add_f32 v[166:167], v[166:167], 1.0 op_sel_hi:[1,0]
	v_pk_add_f32 v[168:169], v[168:169], 1.0 op_sel_hi:[1,0]
	v_pk_add_f32 v[170:171], v[170:171], 1.0 op_sel_hi:[1,0]
	v_rcp_f32_e32 v164, v164
	v_rcp_f32_e32 v165, v165
	v_rcp_f32_e32 v166, v166
	v_rcp_f32_e32 v167, v167
	v_rcp_f32_e32 v168, v168
	v_rcp_f32_e32 v169, v169
	v_rcp_f32_e32 v170, v170
	v_rcp_f32_e32 v171, v171
	v_pk_mul_f32 v[164:165], v[56:57], v[164:165]
	v_pk_mul_f32 v[166:167], v[58:59], v[166:167]
	v_pk_mul_f32 v[168:169], v[52:53], v[168:169]
	v_pk_mul_f32 v[170:171], v[54:55], v[170:171]
	v_cvt_pk_bf16_f32 v174, v164, v165
	v_cvt_pk_bf16_f32 v175, v166, v167
	v_cvt_pk_bf16_f32 v176, v168, v169
	v_cvt_pk_bf16_f32 v177, v170, v171
	global_store_dwordx4 v1, v[174:177], s[22:23] offset:-4096
	s_waitcnt vmcnt(13)
	v_lshlrev_b32_e32 v164, 16, v182
	v_and_b32_e32 v165, 0xffff0000, v182
	v_lshlrev_b32_e32 v166, 16, v183
	v_and_b32_e32 v167, 0xffff0000, v183
	v_lshlrev_b32_e32 v168, 16, v184
	v_and_b32_e32 v169, 0xffff0000, v184
	v_lshlrev_b32_e32 v170, 16, v185
	v_and_b32_e32 v171, 0xffff0000, v185
	v_med3_f32 v164, v164, s34, v227
	v_med3_f32 v165, v165, s34, v227
	v_med3_f32 v166, v166, s34, v227
	v_med3_f32 v167, v167, s34, v227
	v_med3_f32 v168, v168, s34, v227
	v_med3_f32 v169, v169, s34, v227
	v_med3_f32 v170, v170, s34, v227
	v_med3_f32 v171, v171, s34, v227
	v_pk_mul_f32 v[164:165], v[164:165], s[44:45]
	v_pk_mul_f32 v[166:167], v[166:167], s[44:45]
	v_pk_mul_f32 v[168:169], v[168:169], s[44:45]
	v_pk_mul_f32 v[170:171], v[170:171], s[44:45]
	v_exp_f32_e32 v164, v164
	v_exp_f32_e32 v165, v165
	v_exp_f32_e32 v166, v166
	v_exp_f32_e32 v167, v167
	v_exp_f32_e32 v168, v168
	v_exp_f32_e32 v169, v169
	v_exp_f32_e32 v170, v170
	v_exp_f32_e32 v171, v171
	v_pk_add_f32 v[164:165], v[164:165], 1.0 op_sel_hi:[1,0]
	v_pk_add_f32 v[166:167], v[166:167], 1.0 op_sel_hi:[1,0]
	v_pk_add_f32 v[168:169], v[168:169], 1.0 op_sel_hi:[1,0]
	v_pk_add_f32 v[170:171], v[170:171], 1.0 op_sel_hi:[1,0]
	v_rcp_f32_e32 v164, v164
	v_rcp_f32_e32 v165, v165
	v_rcp_f32_e32 v166, v166
	v_rcp_f32_e32 v167, v167
	v_rcp_f32_e32 v168, v168
	v_rcp_f32_e32 v169, v169
	v_rcp_f32_e32 v170, v170
	v_rcp_f32_e32 v171, v171
	v_pk_mul_f32 v[164:165], v[24:25], v[164:165]
	v_pk_mul_f32 v[166:167], v[26:27], v[166:167]
	v_pk_mul_f32 v[168:169], v[20:21], v[168:169]
	v_pk_mul_f32 v[170:171], v[22:23], v[170:171]
	v_cvt_pk_bf16_f32 v174, v164, v165
	v_cvt_pk_bf16_f32 v175, v166, v167
	v_cvt_pk_bf16_f32 v176, v168, v169
	v_cvt_pk_bf16_f32 v177, v170, v171
	global_store_dwordx4 v1, v[174:177], s[22:23] offset:-3840
	s_mov_b64 s[40:41], 0
	s_branch .LBB0_206

.LBB0_242:
	s_add_u32 s23, s0, 0xfffc0080
	s_addc_u32 s24, s1, -1
	s_add_i32 s25, 0, 0x10000
	v_add_u32_e32 v2, s25, v187
	ds_read_b128 v[132:135], v2
	ds_read_b128 v[136:139], v2 offset:1024
	ds_read_b128 v[140:143], v2 offset:2048
	ds_read_b128 v[144:147], v2 offset:3072
	s_cmp_eq_u32 s22, 12
	s_cselect_b32 s47, s57, s24
	s_cselect_b32 s46, s56, s23
	s_cselect_b32 s45, s59, s21
	s_cselect_b32 s44, s58, s20
	s_add_i32 m0, s67, 0xc000
	ds_read_b128 v[148:151], v240
	ds_read_b128 v[152:155], v240 offset:1024
	ds_read_b128 v[156:159], v240 offset:2048
	ds_read_b128 v[160:163], v240 offset:3072
	ds_read_b128 v[164:167], v240 offset:4096
	ds_read_b128 v[168:171], v240 offset:5120
	ds_read_b128 v[172:175], v240 offset:6144
	ds_read_b128 v[204:207], v240 offset:7168
	global_load_lds_dwordx4 v194, s[0:1]
	s_add_i32 m0, s67, 0xe000
	s_nop 0
	global_load_lds_dwordx4 v202, s[0:1]
	s_waitcnt lgkmcnt(8)
	s_barrier
	s_waitcnt lgkmcnt(0)
	v_mfma_f32_16x16x32_bf16 v[128:131], v[132:135], v[148:151], v[128:131]
	v_mfma_f32_16x16x32_bf16 v[124:127], v[140:143], v[148:151], v[124:127]
	v_mfma_f32_16x16x32_bf16 v[120:123], v[132:135], v[156:159], v[120:123]
	v_mfma_f32_16x16x32_bf16 v[116:119], v[140:143], v[156:159], v[116:119]
	v_mfma_f32_16x16x32_bf16 v[112:115], v[132:135], v[164:167], v[112:115]
	v_mfma_f32_16x16x32_bf16 v[108:111], v[140:143], v[164:167], v[108:111]
	v_mfma_f32_16x16x32_bf16 v[104:107], v[132:135], v[172:175], v[104:107]
	v_mfma_f32_16x16x32_bf16 v[100:103], v[140:143], v[172:175], v[100:103]
	v_mfma_f32_16x16x32_bf16 v[128:131], v[136:139], v[152:155], v[128:131]
	v_mfma_f32_16x16x32_bf16 v[124:127], v[144:147], v[152:155], v[124:127]
	v_mfma_f32_16x16x32_bf16 v[120:123], v[136:139], v[160:163], v[120:123]
	v_mfma_f32_16x16x32_bf16 v[116:119], v[144:147], v[160:163], v[116:119]
	v_mfma_f32_16x16x32_bf16 v[112:115], v[136:139], v[168:171], v[112:115]
	v_mfma_f32_16x16x32_bf16 v[108:111], v[144:147], v[168:171], v[108:111]
	v_mfma_f32_16x16x32_bf16 v[104:107], v[136:139], v[204:207], v[104:107]
	v_mfma_f32_16x16x32_bf16 v[100:103], v[144:147], v[204:207], v[100:103]
	s_barrier
	s_add_i32 s23, 0, 0x14000
	s_add_i32 s24, s25, s61
	v_add_u32_e32 v2, s23, v187
	s_mov_b32 m0, s24
	ds_read_b128 v[208:211], v2
	ds_read_b128 v[212:215], v2 offset:1024
	ds_read_b128 v[242:245], v2 offset:2048
	ds_read_b128 v[246:249], v2 offset:3072
	global_load_lds_dwordx4 v176, s[44:45]
	s_add_i32 m0, s24, 0x2000
	s_nop 0
	global_load_lds_dwordx4 v180, s[44:45]
	s_barrier
	s_waitcnt lgkmcnt(0)
	v_mfma_f32_16x16x32_bf16 v[64:67], v[208:211], v[148:151], v[64:67]
	v_mfma_f32_16x16x32_bf16 v[60:63], v[242:245], v[148:151], v[60:63]
	v_mfma_f32_16x16x32_bf16 v[56:59], v[208:211], v[156:159], v[56:59]
	v_mfma_f32_16x16x32_bf16 v[52:55], v[242:245], v[156:159], v[52:55]
	v_mfma_f32_16x16x32_bf16 v[48:51], v[208:211], v[164:167], v[48:51]
	v_mfma_f32_16x16x32_bf16 v[44:47], v[242:245], v[164:167], v[44:47]
	v_mfma_f32_16x16x32_bf16 v[40:43], v[208:211], v[172:175], v[40:43]
	v_mfma_f32_16x16x32_bf16 v[36:39], v[242:245], v[172:175], v[36:39]
	v_mfma_f32_16x16x32_bf16 v[64:67], v[212:215], v[152:155], v[64:67]
	v_mfma_f32_16x16x32_bf16 v[60:63], v[246:249], v[152:155], v[60:63]
	v_mfma_f32_16x16x32_bf16 v[56:59], v[212:215], v[160:163], v[56:59]
	v_mfma_f32_16x16x32_bf16 v[52:55], v[246:249], v[160:163], v[52:55]
	v_mfma_f32_16x16x32_bf16 v[48:51], v[212:215], v[168:171], v[48:51]
	v_mfma_f32_16x16x32_bf16 v[44:47], v[246:249], v[168:171], v[44:47]
	v_mfma_f32_16x16x32_bf16 v[40:43], v[212:215], v[204:207], v[40:43]
	v_mfma_f32_16x16x32_bf16 v[36:39], v[246:249], v[204:207], v[36:39]
	s_mov_b32 m0, s67
	s_barrier
	ds_read_b128 v[148:151], v240 offset:16384
	ds_read_b128 v[152:155], v240 offset:17408
	ds_read_b128 v[156:159], v240 offset:18432
	ds_read_b128 v[160:163], v240 offset:19456
	ds_read_b128 v[164:167], v240 offset:20480
	ds_read_b128 v[168:171], v240 offset:21504
	ds_read_b128 v[172:175], v240 offset:22528
	ds_read_b128 v[204:207], v240 offset:23552
	global_load_lds_dwordx4 v0, s[46:47]
	s_mov_b32 m0, s74
	s_nop 0
	global_load_lds_dwordx4 v178, s[46:47]
	s_barrier
	s_waitcnt lgkmcnt(0)
	v_mfma_f32_16x16x32_bf16 v[96:99], v[132:135], v[148:151], v[96:99]
	v_mfma_f32_16x16x32_bf16 v[92:95], v[140:143], v[148:151], v[92:95]
	v_mfma_f32_16x16x32_bf16 v[88:91], v[132:135], v[156:159], v[88:91]
	v_mfma_f32_16x16x32_bf16 v[84:87], v[140:143], v[156:159], v[84:87]
	v_mfma_f32_16x16x32_bf16 v[80:83], v[132:135], v[164:167], v[80:83]
	v_mfma_f32_16x16x32_bf16 v[76:79], v[140:143], v[164:167], v[76:79]
	v_mfma_f32_16x16x32_bf16 v[72:75], v[132:135], v[172:175], v[72:75]
	v_mfma_f32_16x16x32_bf16 v[68:71], v[140:143], v[172:175], v[68:71]
	v_mfma_f32_16x16x32_bf16 v[96:99], v[136:139], v[152:155], v[96:99]
	v_mfma_f32_16x16x32_bf16 v[92:95], v[144:147], v[152:155], v[92:95]
	v_mfma_f32_16x16x32_bf16 v[88:91], v[136:139], v[160:163], v[88:91]
	v_mfma_f32_16x16x32_bf16 v[84:87], v[144:147], v[160:163], v[84:87]
	v_mfma_f32_16x16x32_bf16 v[80:83], v[136:139], v[168:171], v[80:83]
	v_mfma_f32_16x16x32_bf16 v[76:79], v[144:147], v[168:171], v[76:79]
	v_mfma_f32_16x16x32_bf16 v[72:75], v[136:139], v[204:207], v[72:75]
	v_mfma_f32_16x16x32_bf16 v[68:71], v[144:147], v[204:207], v[68:71]
	s_barrier
	s_add_u32 s24, s44, 0x40000
	s_addc_u32 s25, s45, 0
	s_add_i32 s23, s23, s61
	s_mov_b32 m0, s23
	s_nop 0
	global_load_lds_dwordx4 v176, s[24:25]
	s_add_i32 m0, s23, 0x2000
	s_nop 0
	global_load_lds_dwordx4 v180, s[24:25]
	s_waitcnt vmcnt(6)
	s_barrier
	v_mfma_f32_16x16x32_bf16 v[32:35], v[208:211], v[148:151], v[32:35]
	v_mfma_f32_16x16x32_bf16 v[28:31], v[242:245], v[148:151], v[28:31]
	v_mfma_f32_16x16x32_bf16 v[24:27], v[208:211], v[156:159], v[24:27]
	v_mfma_f32_16x16x32_bf16 v[20:23], v[242:245], v[156:159], v[20:23]
	v_mfma_f32_16x16x32_bf16 v[16:19], v[208:211], v[164:167], v[16:19]
	v_mfma_f32_16x16x32_bf16 v[12:15], v[242:245], v[164:167], v[12:15]
	v_mfma_f32_16x16x32_bf16 v[8:11], v[208:211], v[172:175], v[8:11]
	v_mfma_f32_16x16x32_bf16 v[4:7], v[242:245], v[172:175], v[4:7]
	v_mfma_f32_16x16x32_bf16 v[32:35], v[212:215], v[152:155], v[32:35]
	v_mfma_f32_16x16x32_bf16 v[28:31], v[246:249], v[152:155], v[28:31]
	v_mfma_f32_16x16x32_bf16 v[24:27], v[212:215], v[160:163], v[24:27]
	v_mfma_f32_16x16x32_bf16 v[20:23], v[246:249], v[160:163], v[20:23]
	v_mfma_f32_16x16x32_bf16 v[16:19], v[212:215], v[168:171], v[16:19]
	v_mfma_f32_16x16x32_bf16 v[12:15], v[246:249], v[168:171], v[12:15]
	v_mfma_f32_16x16x32_bf16 v[8:11], v[212:215], v[204:207], v[8:11]
	v_mfma_f32_16x16x32_bf16 v[4:7], v[246:249], v[204:207], v[4:7]
	s_add_i32 s23, 0, 0x18000
	v_add_u32_e32 v2, s23, v187
	s_barrier
	ds_read_b128 v[132:135], v2
	ds_read_b128 v[136:139], v2 offset:1024
	ds_read_b128 v[140:143], v2 offset:2048
	ds_read_b128 v[144:147], v2 offset:3072
	s_add_u32 s24, s46, 0x40000
	s_addc_u32 s25, s47, 0
	s_mov_b32 m0, s75
	ds_read_b128 v[148:151], v240 offset:32768
	ds_read_b128 v[152:155], v240 offset:33792
	ds_read_b128 v[156:159], v240 offset:34816
	ds_read_b128 v[160:163], v240 offset:35840
	ds_read_b128 v[164:167], v240 offset:36864
	ds_read_b128 v[168:171], v240 offset:37888
	ds_read_b128 v[172:175], v240 offset:38912
	ds_read_b128 v[204:207], v240 offset:39936
	global_load_lds_dwordx4 v0, s[24:25]
	s_mov_b32 m0, s82
	s_nop 0
	global_load_lds_dwordx4 v178, s[24:25]
	s_waitcnt lgkmcnt(8)
	s_barrier
	s_waitcnt lgkmcnt(0)
	v_mfma_f32_16x16x32_bf16 v[128:131], v[132:135], v[148:151], v[128:131]
	v_mfma_f32_16x16x32_bf16 v[124:127], v[140:143], v[148:151], v[124:127]
	v_mfma_f32_16x16x32_bf16 v[120:123], v[132:135], v[156:159], v[120:123]
	v_mfma_f32_16x16x32_bf16 v[116:119], v[140:143], v[156:159], v[116:119]
	v_mfma_f32_16x16x32_bf16 v[112:115], v[132:135], v[164:167], v[112:115]
	v_mfma_f32_16x16x32_bf16 v[108:111], v[140:143], v[164:167], v[108:111]
	v_mfma_f32_16x16x32_bf16 v[104:107], v[132:135], v[172:175], v[104:107]
	v_mfma_f32_16x16x32_bf16 v[100:103], v[140:143], v[172:175], v[100:103]
	v_mfma_f32_16x16x32_bf16 v[128:131], v[136:139], v[152:155], v[128:131]
	v_mfma_f32_16x16x32_bf16 v[124:127], v[144:147], v[152:155], v[124:127]
	v_mfma_f32_16x16x32_bf16 v[120:123], v[136:139], v[160:163], v[120:123]
	v_mfma_f32_16x16x32_bf16 v[116:119], v[144:147], v[160:163], v[116:119]
	v_mfma_f32_16x16x32_bf16 v[112:115], v[136:139], v[168:171], v[112:115]
	v_mfma_f32_16x16x32_bf16 v[108:111], v[144:147], v[168:171], v[108:111]
	v_mfma_f32_16x16x32_bf16 v[104:107], v[136:139], v[204:207], v[104:107]
	v_mfma_f32_16x16x32_bf16 v[100:103], v[144:147], v[204:207], v[100:103]
	s_barrier
	s_add_i32 s26, 0, 0x1c000
	s_add_i32 s23, s23, s61
	v_add_u32_e32 v2, s26, v187
	s_mov_b32 m0, s23
	ds_read_b128 v[208:211], v2
	ds_read_b128 v[212:215], v2 offset:1024
	ds_read_b128 v[242:245], v2 offset:2048
	ds_read_b128 v[246:249], v2 offset:3072
	s_add_u32 s98, s44, 0x80
	s_addc_u32 s99, s45, 0
	global_load_lds_dwordx4 v176, s[98:99]
	s_add_i32 m0, s23, 0x2000
	s_nop 0
	global_load_lds_dwordx4 v180, s[98:99]
	s_barrier
	s_waitcnt lgkmcnt(0)
	v_mfma_f32_16x16x32_bf16 v[64:67], v[208:211], v[148:151], v[64:67]
	v_mfma_f32_16x16x32_bf16 v[60:63], v[242:245], v[148:151], v[60:63]
	v_mfma_f32_16x16x32_bf16 v[56:59], v[208:211], v[156:159], v[56:59]
	v_mfma_f32_16x16x32_bf16 v[52:55], v[242:245], v[156:159], v[52:55]
	v_mfma_f32_16x16x32_bf16 v[48:51], v[208:211], v[164:167], v[48:51]
	v_mfma_f32_16x16x32_bf16 v[44:47], v[242:245], v[164:167], v[44:47]
	v_mfma_f32_16x16x32_bf16 v[40:43], v[208:211], v[172:175], v[40:43]
	v_mfma_f32_16x16x32_bf16 v[36:39], v[242:245], v[172:175], v[36:39]
	v_mfma_f32_16x16x32_bf16 v[64:67], v[212:215], v[152:155], v[64:67]
	v_mfma_f32_16x16x32_bf16 v[60:63], v[246:249], v[152:155], v[60:63]
	v_mfma_f32_16x16x32_bf16 v[56:59], v[212:215], v[160:163], v[56:59]
	v_mfma_f32_16x16x32_bf16 v[52:55], v[246:249], v[160:163], v[52:55]
	v_mfma_f32_16x16x32_bf16 v[48:51], v[212:215], v[168:171], v[48:51]
	v_mfma_f32_16x16x32_bf16 v[44:47], v[246:249], v[168:171], v[44:47]
	v_mfma_f32_16x16x32_bf16 v[40:43], v[212:215], v[204:207], v[40:43]
	v_mfma_f32_16x16x32_bf16 v[36:39], v[246:249], v[204:207], v[36:39]
	s_mov_b32 m0, s48
	s_barrier
	ds_read_b128 v[148:151], v240 offset:49152
	ds_read_b128 v[152:155], v240 offset:50176
	ds_read_b128 v[156:159], v240 offset:51200
	ds_read_b128 v[160:163], v240 offset:52224
	ds_read_b128 v[164:167], v240 offset:53248
	ds_read_b128 v[168:171], v240 offset:54272
	ds_read_b128 v[172:175], v240 offset:55296
	ds_read_b128 v[204:207], v240 offset:56320
	s_add_u32 s98, s46, 0x80
	s_addc_u32 s99, s47, 0
	global_load_lds_dwordx4 v0, s[98:99]
	s_mov_b32 m0, s50
	s_nop 0
	global_load_lds_dwordx4 v178, s[98:99]
	s_barrier
	s_waitcnt lgkmcnt(0)
	v_mfma_f32_16x16x32_bf16 v[96:99], v[132:135], v[148:151], v[96:99]
	v_mfma_f32_16x16x32_bf16 v[92:95], v[140:143], v[148:151], v[92:95]
	v_mfma_f32_16x16x32_bf16 v[88:91], v[132:135], v[156:159], v[88:91]
	v_mfma_f32_16x16x32_bf16 v[84:87], v[140:143], v[156:159], v[84:87]
	v_mfma_f32_16x16x32_bf16 v[80:83], v[132:135], v[164:167], v[80:83]
	v_mfma_f32_16x16x32_bf16 v[76:79], v[140:143], v[164:167], v[76:79]
	v_mfma_f32_16x16x32_bf16 v[72:75], v[132:135], v[172:175], v[72:75]
	v_mfma_f32_16x16x32_bf16 v[68:71], v[140:143], v[172:175], v[68:71]
	v_mfma_f32_16x16x32_bf16 v[96:99], v[136:139], v[152:155], v[96:99]
	v_mfma_f32_16x16x32_bf16 v[92:95], v[144:147], v[152:155], v[92:95]
	v_mfma_f32_16x16x32_bf16 v[88:91], v[136:139], v[160:163], v[88:91]
	v_mfma_f32_16x16x32_bf16 v[84:87], v[144:147], v[160:163], v[84:87]
	v_mfma_f32_16x16x32_bf16 v[80:83], v[136:139], v[168:171], v[80:83]
	v_mfma_f32_16x16x32_bf16 v[76:79], v[144:147], v[168:171], v[76:79]
	v_mfma_f32_16x16x32_bf16 v[72:75], v[136:139], v[204:207], v[72:75]
	v_mfma_f32_16x16x32_bf16 v[68:71], v[144:147], v[204:207], v[68:71]
	s_barrier
	s_add_u32 s24, s44, 0x40080
	s_addc_u32 s25, s45, 0
	s_add_i32 s23, s26, s61
	s_mov_b32 m0, s23
	s_nop 0
	global_load_lds_dwordx4 v176, s[24:25]
	s_add_i32 m0, s23, 0x2000
	s_nop 0
	global_load_lds_dwordx4 v180, s[24:25]
	s_waitcnt vmcnt(6)
	s_barrier
	v_mfma_f32_16x16x32_bf16 v[32:35], v[208:211], v[148:151], v[32:35]
	v_mfma_f32_16x16x32_bf16 v[28:31], v[242:245], v[148:151], v[28:31]
	v_mfma_f32_16x16x32_bf16 v[24:27], v[208:211], v[156:159], v[24:27]
	v_mfma_f32_16x16x32_bf16 v[20:23], v[242:245], v[156:159], v[20:23]
	v_mfma_f32_16x16x32_bf16 v[16:19], v[208:211], v[164:167], v[16:19]
	v_mfma_f32_16x16x32_bf16 v[12:15], v[242:245], v[164:167], v[12:15]
	v_mfma_f32_16x16x32_bf16 v[8:11], v[208:211], v[172:175], v[8:11]
	v_mfma_f32_16x16x32_bf16 v[4:7], v[242:245], v[172:175], v[4:7]
	v_mfma_f32_16x16x32_bf16 v[32:35], v[212:215], v[152:155], v[32:35]
	v_mfma_f32_16x16x32_bf16 v[28:31], v[246:249], v[152:155], v[28:31]
	v_mfma_f32_16x16x32_bf16 v[24:27], v[212:215], v[160:163], v[24:27]
	v_mfma_f32_16x16x32_bf16 v[20:23], v[246:249], v[160:163], v[20:23]
	v_mfma_f32_16x16x32_bf16 v[16:19], v[212:215], v[168:171], v[16:19]
	v_mfma_f32_16x16x32_bf16 v[12:15], v[246:249], v[168:171], v[12:15]
	v_mfma_f32_16x16x32_bf16 v[8:11], v[212:215], v[204:207], v[8:11]
	v_mfma_f32_16x16x32_bf16 v[4:7], v[246:249], v[204:207], v[4:7]
	s_add_i32 s22, s22, 2
	s_add_u32 s0, s0, 0x100
	s_addc_u32 s1, s1, 0
	s_add_u32 s20, s20, 0x100
	s_addc_u32 s21, s21, 0
	s_cmp_gt_u32 s22, 13
	s_barrier
	s_cbranch_scc0 .LBB0_242
	s_add_i32 s0, s66, -8
	s_cmp_lt_u32 s0, 12
	s_mov_b64 s[0:1], -1
	s_cbranch_scc1 .LBB0_266
	s_cmp_gt_i32 s66, 33
	s_cselect_b64 s[64:65], -1, 0
	s_lshl_b32 s0, s66, 8
	s_lshl_b32 s53, s60, 8
	s_add_i32 s1, s0, 0xffffee00
	s_cmp_lt_i32 s66, 26
	v_cndmask_b32_e64 v2, 0, 1, s[80:81]
	s_cselect_b32 s62, s0, s1
	s_mov_b64 s[0:1], -1
	s_and_b64 vcc, exec, s[64:65]
	v_cmp_ne_u32_e64 s[44:45], 1, v2
	s_cbranch_vccz .LBB0_248
	s_and_b64 vcc, exec, s[44:45]
	s_cbranch_vccnz .LBB0_247
	v_add_u32_e32 v132, s53, v185
	v_ashrrev_i32_e32 v133, 31, v132
	v_lshlrev_b64 v[140:141], 7, v[132:133]
	global_load_dwordx4 v[132:135], v[188:189], off offset:16
	global_load_dwordx4 v[136:139], v[188:189], off
	s_mov_b32 s3, 0xbfb8aa3b
	s_mov_b32 s2, 0x800000
	s_mov_b32 s5, 0x3f317217
	s_mov_b32 s6, 0x7f800000
	s_waitcnt vmcnt(0)
	v_add_f32_e32 v147, v126, v134
	v_add_f32_e32 v2, v128, v136
	v_max_f32_e32 v142, 0, v2
	v_mul_f32_e64 v2, |v2|, s3
	v_exp_f32_e32 v2, v2
	v_add_f32_e32 v136, v124, v132
	v_add_f32_e32 v149, v127, v135
	v_add_f32_e32 v2, 1.0, v2
	v_cmp_gt_f32_e32 vcc, s2, v2
	s_nop 1
	v_cndmask_b32_e64 v132, 0, 32, vcc
	v_ldexp_f32 v2, v2, v132
	v_log_f32_e32 v2, v2
	s_nop 0
	v_mul_f32_e32 v132, 0x3f317217, v2
	v_fma_f32 v132, v2, s5, -v132
	v_fmac_f32_e32 v132, 0x3377d1cf, v2
	v_fmac_f32_e32 v132, 0x3f317217, v2
	v_cmp_lt_f32_e64 s[0:1], |v2|, s6
	s_nop 1
	v_cndmask_b32_e64 v2, v2, v132, s[0:1]
	v_cndmask_b32_e32 v132, 0, v228, vcc
	v_sub_f32_e32 v144, v2, v132
	v_mul_f32_e64 v2, |v136|, s3
	v_exp_f32_e32 v2, v2
	v_max_f32_e32 v132, 0, v136
	v_add_f32_e32 v2, 1.0, v2
	v_cmp_gt_f32_e32 vcc, s2, v2
	s_nop 1
	v_cndmask_b32_e64 v136, 0, 32, vcc
	v_ldexp_f32 v2, v2, v136
	v_log_f32_e32 v2, v2
	s_nop 0
	v_mul_f32_e32 v136, 0x3f317217, v2
	v_fma_f32 v136, v2, s5, -v136
	v_fmac_f32_e32 v136, 0x3377d1cf, v2
	v_fmac_f32_e32 v136, 0x3f317217, v2
	v_cmp_lt_f32_e64 s[0:1], |v2|, s6
	s_nop 1
	v_cndmask_b32_e64 v2, v2, v136, s[0:1]
	v_cndmask_b32_e32 v136, 0, v228, vcc
	v_sub_f32_e32 v136, v2, v136
	v_add_f32_e32 v2, v129, v137
	v_max_f32_e32 v143, 0, v2
	v_mul_f32_e64 v2, |v2|, s3
	v_exp_f32_e32 v2, v2
	v_add_f32_e32 v137, v125, v133
	v_add_f32_e32 v2, 1.0, v2
	v_cmp_gt_f32_e32 vcc, s2, v2
	s_nop 1
	v_cndmask_b32_e64 v133, 0, 32, vcc
	v_ldexp_f32 v2, v2, v133
	v_log_f32_e32 v2, v2
	s_nop 0
	v_mul_f32_e32 v133, 0x3f317217, v2
	v_fma_f32 v133, v2, s5, -v133
	v_fmac_f32_e32 v133, 0x3377d1cf, v2
	v_fmac_f32_e32 v133, 0x3f317217, v2
	v_cmp_lt_f32_e64 s[0:1], |v2|, s6
	s_nop 1
	v_cndmask_b32_e64 v2, v2, v133, s[0:1]
	v_cndmask_b32_e32 v133, 0, v228, vcc
	v_sub_f32_e32 v145, v2, v133
	v_mul_f32_e64 v2, |v137|, s3
	v_exp_f32_e32 v2, v2
	v_max_f32_e32 v133, 0, v137
	v_pk_add_f32 v[142:143], v[142:143], v[144:145]
	v_add_f32_e32 v2, 1.0, v2
	v_cmp_gt_f32_e32 vcc, s2, v2
	s_nop 1
	v_cndmask_b32_e64 v137, 0, 32, vcc
	v_ldexp_f32 v2, v2, v137
	v_log_f32_e32 v2, v2
	s_nop 0
	v_mul_f32_e32 v137, 0x3f317217, v2
	v_fma_f32 v137, v2, s5, -v137
	v_fmac_f32_e32 v137, 0x3377d1cf, v2
	v_fmac_f32_e32 v137, 0x3f317217, v2
	v_cmp_lt_f32_e64 s[0:1], |v2|, s6
	s_nop 1
	v_cndmask_b32_e64 v2, v2, v137, s[0:1]
	v_cndmask_b32_e32 v137, 0, v228, vcc
	v_sub_f32_e32 v137, v2, v137
	v_add_f32_e32 v2, v130, v138
	v_max_f32_e32 v138, 0, v2
	v_mul_f32_e64 v2, |v2|, s3
	v_exp_f32_e32 v2, v2
	v_pk_add_f32 v[132:133], v[132:133], v[136:137]
	v_lshl_add_u64 v[136:137], v[190:191], 0, v[140:141]
	v_add_f32_e32 v2, 1.0, v2
	v_cmp_gt_f32_e32 vcc, s2, v2
	s_nop 1
	v_cndmask_b32_e64 v134, 0, 32, vcc
	v_ldexp_f32 v2, v2, v134
	v_log_f32_e32 v2, v2
	s_nop 0
	v_mul_f32_e32 v134, 0x3f317217, v2
	v_fma_f32 v134, v2, s5, -v134
	v_fmac_f32_e32 v134, 0x3377d1cf, v2
	v_fmac_f32_e32 v134, 0x3f317217, v2
	v_cmp_lt_f32_e64 s[0:1], |v2|, s6
	s_nop 1
	v_cndmask_b32_e64 v2, v2, v134, s[0:1]
	v_cndmask_b32_e32 v134, 0, v228, vcc
	v_sub_f32_e32 v146, v2, v134
	v_mul_f32_e64 v2, |v147|, s3
	v_exp_f32_e32 v2, v2
	v_max_f32_e32 v134, 0, v147
	v_add_f32_e32 v2, 1.0, v2
	v_cmp_gt_f32_e32 vcc, s2, v2
	s_nop 1
	v_cndmask_b32_e64 v147, 0, 32, vcc
	v_ldexp_f32 v2, v2, v147
	v_log_f32_e32 v2, v2
	s_nop 0
	v_mul_f32_e32 v147, 0x3f317217, v2
	v_fma_f32 v147, v2, s5, -v147
	v_fmac_f32_e32 v147, 0x3377d1cf, v2
	v_fmac_f32_e32 v147, 0x3f317217, v2
	v_cmp_lt_f32_e64 s[0:1], |v2|, s6
	s_nop 1
	v_cndmask_b32_e64 v2, v2, v147, s[0:1]
	v_cndmask_b32_e32 v147, 0, v228, vcc
	v_sub_f32_e32 v148, v2, v147
	v_add_f32_e32 v2, v131, v139
	v_max_f32_e32 v139, 0, v2
	v_mul_f32_e64 v2, |v2|, s3
	v_exp_f32_e32 v2, v2
	s_nop 0
	v_add_f32_e32 v2, 1.0, v2
	v_cmp_gt_f32_e32 vcc, s2, v2
	s_nop 1
	v_cndmask_b32_e64 v135, 0, 32, vcc
	v_ldexp_f32 v2, v2, v135
	v_log_f32_e32 v2, v2
	s_nop 0
	v_mul_f32_e32 v135, 0x3f317217, v2
	v_fma_f32 v135, v2, s5, -v135
	v_fmac_f32_e32 v135, 0x3377d1cf, v2
	v_fmac_f32_e32 v135, 0x3f317217, v2
	v_cmp_lt_f32_e64 s[0:1], |v2|, s6
	s_nop 1
	v_cndmask_b32_e64 v2, v2, v135, s[0:1]
	v_cndmask_b32_e32 v135, 0, v228, vcc
	v_sub_f32_e32 v147, v2, v135
	v_mul_f32_e64 v2, |v149|, s3
	v_exp_f32_e32 v2, v2
	v_pk_add_f32 v[144:145], v[138:139], v[146:147]
	v_max_f32_e32 v135, 0, v149
	v_add_f32_e32 v2, 1.0, v2
	v_cmp_gt_f32_e32 vcc, s2, v2
	s_nop 1
	v_cndmask_b32_e64 v138, 0, 32, vcc
	v_ldexp_f32 v2, v2, v138
	v_log_f32_e32 v2, v2
	s_nop 0
	v_mul_f32_e32 v138, 0x3f317217, v2
	v_fma_f32 v138, v2, s5, -v138
	v_fmac_f32_e32 v138, 0x3377d1cf, v2
	v_fmac_f32_e32 v138, 0x3f317217, v2
	v_cmp_lt_f32_e64 s[0:1], |v2|, s6
	s_nop 1
	v_cndmask_b32_e64 v2, v2, v138, s[0:1]
	v_cndmask_b32_e32 v138, 0, v228, vcc
	v_sub_f32_e32 v149, v2, v138
	v_pk_add_f32 v[134:135], v[134:135], v[148:149]
	global_store_dwordx4 v[136:137], v[142:145], off
	global_store_dwordx4 v[136:137], v[132:135], off offset:16

.LBB0_427:
	s_add_u32 s23, s0, 0xfffc0080
	s_addc_u32 s24, s1, -1
	s_add_i32 s25, 0, 0x10000
	v_add_u32_e32 v2, s25, v187
	ds_read_b128 v[132:135], v2
	ds_read_b128 v[136:139], v2 offset:1024
	ds_read_b128 v[140:143], v2 offset:2048
	ds_read_b128 v[144:147], v2 offset:3072
	s_cmp_eq_u32 s22, 12
	s_cselect_b32 s47, s57, s24
	s_cselect_b32 s46, s56, s23
	s_cselect_b32 s45, s59, s21
	s_cselect_b32 s44, s58, s20
	s_add_i32 m0, s74, 0xc000
	ds_read_b128 v[148:151], v240
	ds_read_b128 v[152:155], v240 offset:1024
	ds_read_b128 v[156:159], v240 offset:2048
	ds_read_b128 v[160:163], v240 offset:3072
	ds_read_b128 v[164:167], v240 offset:4096
	ds_read_b128 v[168:171], v240 offset:5120
	ds_read_b128 v[172:175], v240 offset:6144
	ds_read_b128 v[204:207], v240 offset:7168
	global_load_lds_dwordx4 v194, s[0:1]
	s_add_i32 m0, s74, 0xe000
	s_nop 0
	global_load_lds_dwordx4 v202, s[0:1]
	s_waitcnt lgkmcnt(8)
	s_barrier
	s_waitcnt lgkmcnt(0)
	v_mfma_f32_16x16x32_bf16 v[128:131], v[132:135], v[148:151], v[128:131]
	v_mfma_f32_16x16x32_bf16 v[124:127], v[140:143], v[148:151], v[124:127]
	v_mfma_f32_16x16x32_bf16 v[120:123], v[132:135], v[156:159], v[120:123]
	v_mfma_f32_16x16x32_bf16 v[116:119], v[140:143], v[156:159], v[116:119]
	v_mfma_f32_16x16x32_bf16 v[112:115], v[132:135], v[164:167], v[112:115]
	v_mfma_f32_16x16x32_bf16 v[108:111], v[140:143], v[164:167], v[108:111]
	v_mfma_f32_16x16x32_bf16 v[104:107], v[132:135], v[172:175], v[104:107]
	v_mfma_f32_16x16x32_bf16 v[100:103], v[140:143], v[172:175], v[100:103]
	v_mfma_f32_16x16x32_bf16 v[128:131], v[136:139], v[152:155], v[128:131]
	v_mfma_f32_16x16x32_bf16 v[124:127], v[144:147], v[152:155], v[124:127]
	v_mfma_f32_16x16x32_bf16 v[120:123], v[136:139], v[160:163], v[120:123]
	v_mfma_f32_16x16x32_bf16 v[116:119], v[144:147], v[160:163], v[116:119]
	v_mfma_f32_16x16x32_bf16 v[112:115], v[136:139], v[168:171], v[112:115]
	v_mfma_f32_16x16x32_bf16 v[108:111], v[144:147], v[168:171], v[108:111]
	v_mfma_f32_16x16x32_bf16 v[104:107], v[136:139], v[204:207], v[104:107]
	v_mfma_f32_16x16x32_bf16 v[100:103], v[144:147], v[204:207], v[100:103]
	s_barrier
	s_add_i32 s23, 0, 0x14000
	s_add_i32 s24, s25, s67
	v_add_u32_e32 v2, s23, v187
	s_mov_b32 m0, s24
	ds_read_b128 v[208:211], v2
	ds_read_b128 v[212:215], v2 offset:1024
	ds_read_b128 v[242:245], v2 offset:2048
	ds_read_b128 v[246:249], v2 offset:3072
	global_load_lds_dwordx4 v176, s[44:45]
	s_add_i32 m0, s24, 0x2000
	s_nop 0
	global_load_lds_dwordx4 v180, s[44:45]
	s_barrier
	s_waitcnt lgkmcnt(0)
	v_mfma_f32_16x16x32_bf16 v[64:67], v[208:211], v[148:151], v[64:67]
	v_mfma_f32_16x16x32_bf16 v[60:63], v[242:245], v[148:151], v[60:63]
	v_mfma_f32_16x16x32_bf16 v[56:59], v[208:211], v[156:159], v[56:59]
	v_mfma_f32_16x16x32_bf16 v[52:55], v[242:245], v[156:159], v[52:55]
	v_mfma_f32_16x16x32_bf16 v[48:51], v[208:211], v[164:167], v[48:51]
	v_mfma_f32_16x16x32_bf16 v[44:47], v[242:245], v[164:167], v[44:47]
	v_mfma_f32_16x16x32_bf16 v[40:43], v[208:211], v[172:175], v[40:43]
	v_mfma_f32_16x16x32_bf16 v[36:39], v[242:245], v[172:175], v[36:39]
	v_mfma_f32_16x16x32_bf16 v[64:67], v[212:215], v[152:155], v[64:67]
	v_mfma_f32_16x16x32_bf16 v[60:63], v[246:249], v[152:155], v[60:63]
	v_mfma_f32_16x16x32_bf16 v[56:59], v[212:215], v[160:163], v[56:59]
	v_mfma_f32_16x16x32_bf16 v[52:55], v[246:249], v[160:163], v[52:55]
	v_mfma_f32_16x16x32_bf16 v[48:51], v[212:215], v[168:171], v[48:51]
	v_mfma_f32_16x16x32_bf16 v[44:47], v[246:249], v[168:171], v[44:47]
	v_mfma_f32_16x16x32_bf16 v[40:43], v[212:215], v[204:207], v[40:43]
	v_mfma_f32_16x16x32_bf16 v[36:39], v[246:249], v[204:207], v[36:39]
	s_mov_b32 m0, s74
	s_barrier
	ds_read_b128 v[148:151], v240 offset:16384
	ds_read_b128 v[152:155], v240 offset:17408
	ds_read_b128 v[156:159], v240 offset:18432
	ds_read_b128 v[160:163], v240 offset:19456
	ds_read_b128 v[164:167], v240 offset:20480
	ds_read_b128 v[168:171], v240 offset:21504
	ds_read_b128 v[172:175], v240 offset:22528
	ds_read_b128 v[204:207], v240 offset:23552
	global_load_lds_dwordx4 v0, s[46:47]
	s_mov_b32 m0, s75
	s_nop 0
	global_load_lds_dwordx4 v178, s[46:47]
	s_barrier
	s_waitcnt lgkmcnt(0)
	v_mfma_f32_16x16x32_bf16 v[96:99], v[132:135], v[148:151], v[96:99]
	v_mfma_f32_16x16x32_bf16 v[92:95], v[140:143], v[148:151], v[92:95]
	v_mfma_f32_16x16x32_bf16 v[88:91], v[132:135], v[156:159], v[88:91]
	v_mfma_f32_16x16x32_bf16 v[84:87], v[140:143], v[156:159], v[84:87]
	v_mfma_f32_16x16x32_bf16 v[80:83], v[132:135], v[164:167], v[80:83]
	v_mfma_f32_16x16x32_bf16 v[76:79], v[140:143], v[164:167], v[76:79]
	v_mfma_f32_16x16x32_bf16 v[72:75], v[132:135], v[172:175], v[72:75]
	v_mfma_f32_16x16x32_bf16 v[68:71], v[140:143], v[172:175], v[68:71]
	v_mfma_f32_16x16x32_bf16 v[96:99], v[136:139], v[152:155], v[96:99]
	v_mfma_f32_16x16x32_bf16 v[92:95], v[144:147], v[152:155], v[92:95]
	v_mfma_f32_16x16x32_bf16 v[88:91], v[136:139], v[160:163], v[88:91]
	v_mfma_f32_16x16x32_bf16 v[84:87], v[144:147], v[160:163], v[84:87]
	v_mfma_f32_16x16x32_bf16 v[80:83], v[136:139], v[168:171], v[80:83]
	v_mfma_f32_16x16x32_bf16 v[76:79], v[144:147], v[168:171], v[76:79]
	v_mfma_f32_16x16x32_bf16 v[72:75], v[136:139], v[204:207], v[72:75]
	v_mfma_f32_16x16x32_bf16 v[68:71], v[144:147], v[204:207], v[68:71]
	s_barrier
	s_add_u32 s24, s44, 0x40000
	s_addc_u32 s25, s45, 0
	s_add_i32 s23, s23, s67
	s_mov_b32 m0, s23
	s_nop 0
	global_load_lds_dwordx4 v176, s[24:25]
	s_add_i32 m0, s23, 0x2000
	s_nop 0
	global_load_lds_dwordx4 v180, s[24:25]
	s_waitcnt vmcnt(6)
	s_barrier
	v_mfma_f32_16x16x32_bf16 v[32:35], v[208:211], v[148:151], v[32:35]
	v_mfma_f32_16x16x32_bf16 v[28:31], v[242:245], v[148:151], v[28:31]
	v_mfma_f32_16x16x32_bf16 v[24:27], v[208:211], v[156:159], v[24:27]
	v_mfma_f32_16x16x32_bf16 v[20:23], v[242:245], v[156:159], v[20:23]
	v_mfma_f32_16x16x32_bf16 v[16:19], v[208:211], v[164:167], v[16:19]
	v_mfma_f32_16x16x32_bf16 v[12:15], v[242:245], v[164:167], v[12:15]
	v_mfma_f32_16x16x32_bf16 v[8:11], v[208:211], v[172:175], v[8:11]
	v_mfma_f32_16x16x32_bf16 v[4:7], v[242:245], v[172:175], v[4:7]
	v_mfma_f32_16x16x32_bf16 v[32:35], v[212:215], v[152:155], v[32:35]
	v_mfma_f32_16x16x32_bf16 v[28:31], v[246:249], v[152:155], v[28:31]
	v_mfma_f32_16x16x32_bf16 v[24:27], v[212:215], v[160:163], v[24:27]
	v_mfma_f32_16x16x32_bf16 v[20:23], v[246:249], v[160:163], v[20:23]
	v_mfma_f32_16x16x32_bf16 v[16:19], v[212:215], v[168:171], v[16:19]
	v_mfma_f32_16x16x32_bf16 v[12:15], v[246:249], v[168:171], v[12:15]
	v_mfma_f32_16x16x32_bf16 v[8:11], v[212:215], v[204:207], v[8:11]
	v_mfma_f32_16x16x32_bf16 v[4:7], v[246:249], v[204:207], v[4:7]
	s_add_i32 s23, 0, 0x18000
	v_add_u32_e32 v2, s23, v187
	s_barrier
	ds_read_b128 v[132:135], v2
	ds_read_b128 v[136:139], v2 offset:1024
	ds_read_b128 v[140:143], v2 offset:2048
	ds_read_b128 v[144:147], v2 offset:3072
	s_add_u32 s24, s46, 0x40000
	s_addc_u32 s25, s47, 0
	s_mov_b32 m0, s82
	ds_read_b128 v[148:151], v240 offset:32768
	ds_read_b128 v[152:155], v240 offset:33792
	ds_read_b128 v[156:159], v240 offset:34816
	ds_read_b128 v[160:163], v240 offset:35840
	ds_read_b128 v[164:167], v240 offset:36864
	ds_read_b128 v[168:171], v240 offset:37888
	ds_read_b128 v[172:175], v240 offset:38912
	ds_read_b128 v[204:207], v240 offset:39936
	global_load_lds_dwordx4 v0, s[24:25]
	s_mov_b32 m0, s83
	s_nop 0
	global_load_lds_dwordx4 v178, s[24:25]
	s_waitcnt lgkmcnt(8)
	s_barrier
	s_waitcnt lgkmcnt(0)
	v_mfma_f32_16x16x32_bf16 v[128:131], v[132:135], v[148:151], v[128:131]
	v_mfma_f32_16x16x32_bf16 v[124:127], v[140:143], v[148:151], v[124:127]
	v_mfma_f32_16x16x32_bf16 v[120:123], v[132:135], v[156:159], v[120:123]
	v_mfma_f32_16x16x32_bf16 v[116:119], v[140:143], v[156:159], v[116:119]
	v_mfma_f32_16x16x32_bf16 v[112:115], v[132:135], v[164:167], v[112:115]
	v_mfma_f32_16x16x32_bf16 v[108:111], v[140:143], v[164:167], v[108:111]
	v_mfma_f32_16x16x32_bf16 v[104:107], v[132:135], v[172:175], v[104:107]
	v_mfma_f32_16x16x32_bf16 v[100:103], v[140:143], v[172:175], v[100:103]
	v_mfma_f32_16x16x32_bf16 v[128:131], v[136:139], v[152:155], v[128:131]
	v_mfma_f32_16x16x32_bf16 v[124:127], v[144:147], v[152:155], v[124:127]
	v_mfma_f32_16x16x32_bf16 v[120:123], v[136:139], v[160:163], v[120:123]
	v_mfma_f32_16x16x32_bf16 v[116:119], v[144:147], v[160:163], v[116:119]
	v_mfma_f32_16x16x32_bf16 v[112:115], v[136:139], v[168:171], v[112:115]
	v_mfma_f32_16x16x32_bf16 v[108:111], v[144:147], v[168:171], v[108:111]
	v_mfma_f32_16x16x32_bf16 v[104:107], v[136:139], v[204:207], v[104:107]
	v_mfma_f32_16x16x32_bf16 v[100:103], v[144:147], v[204:207], v[100:103]
	s_barrier
	s_add_i32 s26, 0, 0x1c000
	s_add_i32 s23, s23, s67
	v_add_u32_e32 v2, s26, v187
	s_mov_b32 m0, s23
	ds_read_b128 v[208:211], v2
	ds_read_b128 v[212:215], v2 offset:1024
	ds_read_b128 v[242:245], v2 offset:2048
	ds_read_b128 v[246:249], v2 offset:3072
	s_add_u32 s98, s44, 0x80
	s_addc_u32 s99, s45, 0
	global_load_lds_dwordx4 v176, s[98:99]
	s_add_i32 m0, s23, 0x2000
	s_nop 0
	global_load_lds_dwordx4 v180, s[98:99]
	s_barrier
	s_waitcnt lgkmcnt(0)
	v_mfma_f32_16x16x32_bf16 v[64:67], v[208:211], v[148:151], v[64:67]
	v_mfma_f32_16x16x32_bf16 v[60:63], v[242:245], v[148:151], v[60:63]
	v_mfma_f32_16x16x32_bf16 v[56:59], v[208:211], v[156:159], v[56:59]
	v_mfma_f32_16x16x32_bf16 v[52:55], v[242:245], v[156:159], v[52:55]
	v_mfma_f32_16x16x32_bf16 v[48:51], v[208:211], v[164:167], v[48:51]
	v_mfma_f32_16x16x32_bf16 v[44:47], v[242:245], v[164:167], v[44:47]
	v_mfma_f32_16x16x32_bf16 v[40:43], v[208:211], v[172:175], v[40:43]
	v_mfma_f32_16x16x32_bf16 v[36:39], v[242:245], v[172:175], v[36:39]
	v_mfma_f32_16x16x32_bf16 v[64:67], v[212:215], v[152:155], v[64:67]
	v_mfma_f32_16x16x32_bf16 v[60:63], v[246:249], v[152:155], v[60:63]
	v_mfma_f32_16x16x32_bf16 v[56:59], v[212:215], v[160:163], v[56:59]
	v_mfma_f32_16x16x32_bf16 v[52:55], v[246:249], v[160:163], v[52:55]
	v_mfma_f32_16x16x32_bf16 v[48:51], v[212:215], v[168:171], v[48:51]
	v_mfma_f32_16x16x32_bf16 v[44:47], v[246:249], v[168:171], v[44:47]
	v_mfma_f32_16x16x32_bf16 v[40:43], v[212:215], v[204:207], v[40:43]
	v_mfma_f32_16x16x32_bf16 v[36:39], v[246:249], v[204:207], v[36:39]
	s_mov_b32 m0, s48
	s_barrier
	ds_read_b128 v[148:151], v240 offset:49152
	ds_read_b128 v[152:155], v240 offset:50176
	ds_read_b128 v[156:159], v240 offset:51200
	ds_read_b128 v[160:163], v240 offset:52224
	ds_read_b128 v[164:167], v240 offset:53248
	ds_read_b128 v[168:171], v240 offset:54272
	ds_read_b128 v[172:175], v240 offset:55296
	ds_read_b128 v[204:207], v240 offset:56320
	s_add_u32 s98, s46, 0x80
	s_addc_u32 s99, s47, 0
	global_load_lds_dwordx4 v0, s[98:99]
	s_mov_b32 m0, s50
	s_nop 0
	global_load_lds_dwordx4 v178, s[98:99]
	s_barrier
	s_waitcnt lgkmcnt(0)
	v_mfma_f32_16x16x32_bf16 v[96:99], v[132:135], v[148:151], v[96:99]
	v_mfma_f32_16x16x32_bf16 v[92:95], v[140:143], v[148:151], v[92:95]
	v_mfma_f32_16x16x32_bf16 v[88:91], v[132:135], v[156:159], v[88:91]
	v_mfma_f32_16x16x32_bf16 v[84:87], v[140:143], v[156:159], v[84:87]
	v_mfma_f32_16x16x32_bf16 v[80:83], v[132:135], v[164:167], v[80:83]
	v_mfma_f32_16x16x32_bf16 v[76:79], v[140:143], v[164:167], v[76:79]
	v_mfma_f32_16x16x32_bf16 v[72:75], v[132:135], v[172:175], v[72:75]
	v_mfma_f32_16x16x32_bf16 v[68:71], v[140:143], v[172:175], v[68:71]
	v_mfma_f32_16x16x32_bf16 v[96:99], v[136:139], v[152:155], v[96:99]
	v_mfma_f32_16x16x32_bf16 v[92:95], v[144:147], v[152:155], v[92:95]
	v_mfma_f32_16x16x32_bf16 v[88:91], v[136:139], v[160:163], v[88:91]
	v_mfma_f32_16x16x32_bf16 v[84:87], v[144:147], v[160:163], v[84:87]
	v_mfma_f32_16x16x32_bf16 v[80:83], v[136:139], v[168:171], v[80:83]
	v_mfma_f32_16x16x32_bf16 v[76:79], v[144:147], v[168:171], v[76:79]
	v_mfma_f32_16x16x32_bf16 v[72:75], v[136:139], v[204:207], v[72:75]
	v_mfma_f32_16x16x32_bf16 v[68:71], v[144:147], v[204:207], v[68:71]
	s_barrier
	s_add_u32 s24, s44, 0x40080
	s_addc_u32 s25, s45, 0
	s_add_i32 s23, s26, s67
	s_mov_b32 m0, s23
	s_nop 0
	global_load_lds_dwordx4 v176, s[24:25]
	s_add_i32 m0, s23, 0x2000
	s_nop 0
	global_load_lds_dwordx4 v180, s[24:25]
	s_waitcnt vmcnt(6)
	s_barrier
	v_mfma_f32_16x16x32_bf16 v[32:35], v[208:211], v[148:151], v[32:35]
	v_mfma_f32_16x16x32_bf16 v[28:31], v[242:245], v[148:151], v[28:31]
	v_mfma_f32_16x16x32_bf16 v[24:27], v[208:211], v[156:159], v[24:27]
	v_mfma_f32_16x16x32_bf16 v[20:23], v[242:245], v[156:159], v[20:23]
	v_mfma_f32_16x16x32_bf16 v[16:19], v[208:211], v[164:167], v[16:19]
	v_mfma_f32_16x16x32_bf16 v[12:15], v[242:245], v[164:167], v[12:15]
	v_mfma_f32_16x16x32_bf16 v[8:11], v[208:211], v[172:175], v[8:11]
	v_mfma_f32_16x16x32_bf16 v[4:7], v[242:245], v[172:175], v[4:7]
	v_mfma_f32_16x16x32_bf16 v[32:35], v[212:215], v[152:155], v[32:35]
	v_mfma_f32_16x16x32_bf16 v[28:31], v[246:249], v[152:155], v[28:31]
	v_mfma_f32_16x16x32_bf16 v[24:27], v[212:215], v[160:163], v[24:27]
	v_mfma_f32_16x16x32_bf16 v[20:23], v[246:249], v[160:163], v[20:23]
	v_mfma_f32_16x16x32_bf16 v[16:19], v[212:215], v[168:171], v[16:19]
	v_mfma_f32_16x16x32_bf16 v[12:15], v[246:249], v[168:171], v[12:15]
	v_mfma_f32_16x16x32_bf16 v[8:11], v[212:215], v[204:207], v[8:11]
	v_mfma_f32_16x16x32_bf16 v[4:7], v[246:249], v[204:207], v[4:7]
	s_add_i32 s22, s22, 2
	s_add_u32 s0, s0, 0x100
	s_addc_u32 s1, s1, 0
	s_add_u32 s20, s20, 0x100
	s_addc_u32 s21, s21, 0
	s_cmp_gt_u32 s22, 13
	s_barrier
	s_cbranch_scc0 .LBB0_427
	s_add_i32 s0, s61, -8
	s_cmp_lt_u32 s0, 12
	s_mov_b64 s[0:1], -1
	s_cbranch_scc1 .LBB0_451
	s_cmp_gt_i32 s61, 33
	s_cselect_b64 s[64:65], -1, 0
	s_lshl_b32 s0, s61, 8
	s_lshl_b32 s53, s60, 8
	s_add_i32 s1, s0, 0xffffee00
	s_cmp_lt_i32 s61, 26
	v_cndmask_b32_e64 v2, 0, 1, s[36:37]
	s_cselect_b32 s62, s0, s1
	s_mov_b64 s[0:1], -1
	s_and_b64 vcc, exec, s[64:65]
	v_cmp_ne_u32_e64 s[44:45], 1, v2
	s_cbranch_vccz .LBB0_433
	s_and_b64 vcc, exec, s[44:45]
	s_cbranch_vccnz .LBB0_432
	v_add_u32_e32 v132, s53, v185
	v_ashrrev_i32_e32 v133, 31, v132
	v_lshlrev_b64 v[140:141], 7, v[132:133]
	global_load_dwordx4 v[204:207], v[188:189], off offset:16
	global_load_dwordx4 v[208:211], v[188:189], off
	s_mov_b32 s3, 0xbfb8aa3b
	s_mov_b32 s2, 0x800000
	s_mov_b32 s4, 0x3f317217
	s_mov_b32 s5, 0x7f800000
	s_waitcnt vmcnt(0)
	v_mov_b32_e32 v132, v204
	v_mov_b32_e32 v133, v205
	v_mov_b32_e32 v134, v206
	v_mov_b32_e32 v135, v207
	v_mov_b32_e32 v136, v208
	v_mov_b32_e32 v137, v209
	v_mov_b32_e32 v138, v210
	v_mov_b32_e32 v139, v211
	v_add_f32_e32 v147, v126, v134
	v_add_f32_e32 v2, v128, v136
	v_max_f32_e32 v142, 0, v2
	v_mul_f32_e64 v2, |v2|, s3
	v_exp_f32_e32 v2, v2
	v_add_f32_e32 v136, v124, v132
	v_add_f32_e32 v149, v127, v135
	v_add_f32_e32 v2, 1.0, v2
	v_cmp_gt_f32_e32 vcc, s2, v2
	s_nop 1
	v_cndmask_b32_e64 v132, 0, 32, vcc
	v_ldexp_f32 v2, v2, v132
	v_log_f32_e32 v2, v2
	s_nop 0
	v_mul_f32_e32 v132, 0x3f317217, v2
	v_fma_f32 v132, v2, s4, -v132
	v_fmac_f32_e32 v132, 0x3377d1cf, v2
	v_fmac_f32_e32 v132, 0x3f317217, v2
	v_cmp_lt_f32_e64 s[0:1], |v2|, s5
	s_nop 1
	v_cndmask_b32_e64 v2, v2, v132, s[0:1]
	v_cndmask_b32_e32 v132, 0, v228, vcc
	v_sub_f32_e32 v144, v2, v132
	v_mul_f32_e64 v2, |v136|, s3
	v_exp_f32_e32 v2, v2
	v_max_f32_e32 v132, 0, v136
	v_add_f32_e32 v2, 1.0, v2
	v_cmp_gt_f32_e32 vcc, s2, v2
	s_nop 1
	v_cndmask_b32_e64 v136, 0, 32, vcc
	v_ldexp_f32 v2, v2, v136
	v_log_f32_e32 v2, v2
	s_nop 0
	v_mul_f32_e32 v136, 0x3f317217, v2
	v_fma_f32 v136, v2, s4, -v136
	v_fmac_f32_e32 v136, 0x3377d1cf, v2
	v_fmac_f32_e32 v136, 0x3f317217, v2
	v_cmp_lt_f32_e64 s[0:1], |v2|, s5
	s_nop 1
	v_cndmask_b32_e64 v2, v2, v136, s[0:1]
	v_cndmask_b32_e32 v136, 0, v228, vcc
	v_sub_f32_e32 v136, v2, v136
	v_add_f32_e32 v2, v129, v137
	v_max_f32_e32 v143, 0, v2
	v_mul_f32_e64 v2, |v2|, s3
	v_exp_f32_e32 v2, v2
	v_add_f32_e32 v137, v125, v133
	v_add_f32_e32 v2, 1.0, v2
	v_cmp_gt_f32_e32 vcc, s2, v2
	s_nop 1
	v_cndmask_b32_e64 v133, 0, 32, vcc
	v_ldexp_f32 v2, v2, v133
	v_log_f32_e32 v2, v2
	s_nop 0
	v_mul_f32_e32 v133, 0x3f317217, v2
	v_fma_f32 v133, v2, s4, -v133
	v_fmac_f32_e32 v133, 0x3377d1cf, v2
	v_fmac_f32_e32 v133, 0x3f317217, v2
	v_cmp_lt_f32_e64 s[0:1], |v2|, s5
	s_nop 1
	v_cndmask_b32_e64 v2, v2, v133, s[0:1]
	v_cndmask_b32_e32 v133, 0, v228, vcc
	v_sub_f32_e32 v145, v2, v133
	v_mul_f32_e64 v2, |v137|, s3
	v_exp_f32_e32 v2, v2
	v_max_f32_e32 v133, 0, v137
	v_pk_add_f32 v[142:143], v[142:143], v[144:145]
	v_add_f32_e32 v2, 1.0, v2
	v_cmp_gt_f32_e32 vcc, s2, v2
	s_nop 1
	v_cndmask_b32_e64 v137, 0, 32, vcc
	v_ldexp_f32 v2, v2, v137
	v_log_f32_e32 v2, v2
	s_nop 0
	v_mul_f32_e32 v137, 0x3f317217, v2
	v_fma_f32 v137, v2, s4, -v137
	v_fmac_f32_e32 v137, 0x3377d1cf, v2
	v_fmac_f32_e32 v137, 0x3f317217, v2
	v_cmp_lt_f32_e64 s[0:1], |v2|, s5
	s_nop 1
	v_cndmask_b32_e64 v2, v2, v137, s[0:1]
	v_cndmask_b32_e32 v137, 0, v228, vcc
	v_sub_f32_e32 v137, v2, v137
	v_add_f32_e32 v2, v130, v138
	v_max_f32_e32 v138, 0, v2
	v_mul_f32_e64 v2, |v2|, s3
	v_exp_f32_e32 v2, v2
	v_pk_add_f32 v[132:133], v[132:133], v[136:137]
	v_lshl_add_u64 v[136:137], v[190:191], 0, v[140:141]
	v_add_f32_e32 v2, 1.0, v2
	v_cmp_gt_f32_e32 vcc, s2, v2
	s_nop 1
	v_cndmask_b32_e64 v134, 0, 32, vcc
	v_ldexp_f32 v2, v2, v134
	v_log_f32_e32 v2, v2
	s_nop 0
	v_mul_f32_e32 v134, 0x3f317217, v2
	v_fma_f32 v134, v2, s4, -v134
	v_fmac_f32_e32 v134, 0x3377d1cf, v2
	v_fmac_f32_e32 v134, 0x3f317217, v2
	v_cmp_lt_f32_e64 s[0:1], |v2|, s5
	s_nop 1
	v_cndmask_b32_e64 v2, v2, v134, s[0:1]
	v_cndmask_b32_e32 v134, 0, v228, vcc
	v_sub_f32_e32 v146, v2, v134
	v_mul_f32_e64 v2, |v147|, s3
	v_exp_f32_e32 v2, v2
	v_max_f32_e32 v134, 0, v147
	v_add_f32_e32 v2, 1.0, v2
	v_cmp_gt_f32_e32 vcc, s2, v2
	s_nop 1
	v_cndmask_b32_e64 v147, 0, 32, vcc
	v_ldexp_f32 v2, v2, v147
	v_log_f32_e32 v2, v2
	s_nop 0
	v_mul_f32_e32 v147, 0x3f317217, v2
	v_fma_f32 v147, v2, s4, -v147
	v_fmac_f32_e32 v147, 0x3377d1cf, v2
	v_fmac_f32_e32 v147, 0x3f317217, v2
	v_cmp_lt_f32_e64 s[0:1], |v2|, s5
	s_nop 1
	v_cndmask_b32_e64 v2, v2, v147, s[0:1]
	v_cndmask_b32_e32 v147, 0, v228, vcc
	v_sub_f32_e32 v148, v2, v147
	v_add_f32_e32 v2, v131, v139
	v_max_f32_e32 v139, 0, v2
	v_mul_f32_e64 v2, |v2|, s3
	v_exp_f32_e32 v2, v2
	s_nop 0
	v_add_f32_e32 v2, 1.0, v2
	v_cmp_gt_f32_e32 vcc, s2, v2
	s_nop 1
	v_cndmask_b32_e64 v135, 0, 32, vcc
	v_ldexp_f32 v2, v2, v135
	v_log_f32_e32 v2, v2
	s_nop 0
	v_mul_f32_e32 v135, 0x3f317217, v2
	v_fma_f32 v135, v2, s4, -v135
	v_fmac_f32_e32 v135, 0x3377d1cf, v2
	v_fmac_f32_e32 v135, 0x3f317217, v2
	v_cmp_lt_f32_e64 s[0:1], |v2|, s5
	s_nop 1
	v_cndmask_b32_e64 v2, v2, v135, s[0:1]
	v_cndmask_b32_e32 v135, 0, v228, vcc
	v_sub_f32_e32 v147, v2, v135
	v_mul_f32_e64 v2, |v149|, s3
	v_exp_f32_e32 v2, v2
	v_pk_add_f32 v[144:145], v[138:139], v[146:147]
	v_max_f32_e32 v135, 0, v149
	v_add_f32_e32 v2, 1.0, v2
	v_cmp_gt_f32_e32 vcc, s2, v2
	s_nop 1
	v_cndmask_b32_e64 v138, 0, 32, vcc
	v_ldexp_f32 v2, v2, v138
	v_log_f32_e32 v2, v2
	s_nop 0
	v_mul_f32_e32 v138, 0x3f317217, v2
	v_fma_f32 v138, v2, s4, -v138
	v_fmac_f32_e32 v138, 0x3377d1cf, v2
	v_fmac_f32_e32 v138, 0x3f317217, v2
	v_cmp_lt_f32_e64 s[0:1], |v2|, s5
	s_nop 1
	v_cndmask_b32_e64 v2, v2, v138, s[0:1]
	v_cndmask_b32_e32 v138, 0, v228, vcc
	v_sub_f32_e32 v149, v2, v138
	v_pk_add_f32 v[134:135], v[134:135], v[148:149]
	global_store_dwordx4 v[136:137], v[142:145], off
	global_store_dwordx4 v[136:137], v[132:135], off offset:16
